# indexer: barrier-free per-wave LDS-DMA pipeline (each wave only reads its own tile), 3 stages in flight, counted vmcnt, MFMA/VALU interleave
# speedup vs baseline: 1.0066x; 1.0066x over previous
.LBB0_532:
	v_mov_b32_e32 v129, v194
	v_readfirstlane_b32 s83, v194
	v_and_b32_e32 v180, 31, v194
	v_bfe_u32 v131, v194, 5, 1
	v_and_b32_e32 v243, 63, v194
	s_ashr_i32 s84, s83, 6
	s_lshl_b32 s0, s84, 5
	v_or_b32_e32 v130, s0, v180
	v_lshlrev_b32_e32 v243, 2, v243
	s_lshl_b32 s0, s2, 17
	s_lshl_b32 s1, s84, 8
	s_add_u32 s0, s0, s1
	s_add_u32 s8, s28, s0
	s_addc_u32 s9, s29, 0
	s_lshl_b32 s21, s84, 12
	s_cmp_lg_u32 s82, 0
	s_cbranch_scc1 .Lix_reload
	v_bfe_u32 v0, v194, 2, 1
	v_lshrrev_b32_e32 v1, 1, v194
	v_and_b32_e32 v1, 12, v1
	v_and_b32_e32 v228, 3, v194
	v_or_b32_e32 v1, v1, v228
	v_add_u32_e32 v0, s34, v0
	v_lshlrev_b32_e32 v0, 11, v0
	v_lshl_add_u32 v0, v1, 7, v0
	v_lshl_add_u32 v0, v131, 4, v0
	v_add_u32_e32 v1, 0x1000, v0
	global_load_dwordx4 v[70:73], v0, s[36:37]
	global_load_dwordx4 v[74:77], v0, s[36:37] offset:32
	global_load_dwordx4 v[78:81], v0, s[36:37] offset:64
	global_load_dwordx4 v[82:85], v0, s[36:37] offset:96
	global_load_dwordx4 v[86:89], v1, s[36:37]
	global_load_dwordx4 v[90:93], v1, s[36:37] offset:32
	global_load_dwordx4 v[94:97], v1, s[36:37] offset:64
	global_load_dwordx4 v[98:101], v1, s[36:37] offset:96
	v_add_u32_e32 v228, s34, v131
	v_lshlrev_b32_e32 v228, 6, v228
	global_load_dwordx4 v[22:25], v228, s[38:39]
	global_load_dwordx4 v[26:29], v228, s[38:39] offset:16
	global_load_dwordx4 v[30:33], v228, s[38:39] offset:32
	global_load_dwordx4 v[34:37], v228, s[38:39] offset:48
	global_load_dwordx2 v[244:245], v228, s[38:39] offset:128
	global_load_dwordx2 v[246:247], v228, s[38:39] offset:136
	global_load_dwordx2 v[248:249], v228, s[38:39] offset:144
	global_load_dwordx2 v[250:251], v228, s[38:39] offset:152
	global_load_dwordx2 v[252:253], v228, s[38:39] offset:160
	global_load_dwordx2 v[254:255], v228, s[38:39] offset:168
	global_load_dwordx2 v[200:201], v228, s[38:39] offset:176
	global_load_dwordx2 v[202:203], v228, s[38:39] offset:184
	v_lshrrev_b32_e32 v0, 2, v243
	v_lshrrev_b32_e32 v1, 3, v0
	v_lshrrev_b32_e32 v228, 4, v0
	v_and_b32_e32 v229, 7, v0
	v_xor_b32_e32 v228, v229, v228
	v_xor_b32_e32 v229, 4, v228
	s_lshl_b32 s0, s84, 12
	v_lshl_add_u32 v1, v1, 7, s0
	v_lshl_add_u32 v102, v228, 4, v1
	v_lshl_add_u32 v110, v229, 4, v1
	v_add_u32_e32 v110, 0x400, v110
	v_add_u32_e32 v112, 0x800, v102
	v_add_u32_e32 v193, 0x800, v110
	v_lshlrev_b32_e32 v0, 7, v130
	v_bfe_u32 v1, v180, 1, 3
	v_or_b32_e32 v228, 0, v131
	v_xor_b32_e32 v228, v228, v1
	v_lshl_add_u32 v5, v228, 4, v0
	v_or_b32_e32 v228, 2, v131
	v_xor_b32_e32 v228, v228, v1
	v_lshl_add_u32 v52, v228, 4, v0
	v_or_b32_e32 v228, 4, v131
	v_xor_b32_e32 v228, v228, v1
	v_lshl_add_u32 v55, v228, 4, v0
	v_or_b32_e32 v228, 6, v131
	v_xor_b32_e32 v228, v228, v1
	v_lshl_add_u32 v56, v228, 4, v0
	s_mov_b32 s6, s14
	s_mov_b32 s7, s15
	s_add_i32 s10, s0, 10496
	s_sub_i32 s11, s35, s84
	s_add_i32 m0, s10, 0
	s_nop 0
	global_load_lds_dwordx4 v102, s[6:7]
	s_add_i32 m0, s10, 1024
	s_nop 0
	global_load_lds_dwordx4 v110, s[6:7]
	s_add_i32 m0, s10, 2048
	s_nop 0
	global_load_lds_dwordx4 v112, s[6:7]
	s_add_i32 m0, s10, 3072
	s_nop 0
	global_load_lds_dwordx4 v193, s[6:7]
	s_add_u32 s6, s6, 0x8000
	s_addc_u32 s7, s7, 0
	s_add_i32 m0, s10, 32768
	s_nop 0
	global_load_lds_dwordx4 v102, s[6:7]
	s_add_i32 m0, s10, 33792
	s_nop 0
	global_load_lds_dwordx4 v110, s[6:7]
	s_add_i32 m0, s10, 34816
	s_nop 0
	global_load_lds_dwordx4 v112, s[6:7]
	s_add_i32 m0, s10, 35840
	s_nop 0
	global_load_lds_dwordx4 v193, s[6:7]
	s_add_u32 s6, s6, 0x8000
	s_addc_u32 s7, s7, 0
	s_add_i32 m0, s10, 65536
	s_nop 0
	global_load_lds_dwordx4 v102, s[6:7]
	s_add_i32 m0, s10, 66560
	s_nop 0
	global_load_lds_dwordx4 v110, s[6:7]
	s_add_i32 m0, s10, 67584
	s_nop 0
	global_load_lds_dwordx4 v112, s[6:7]
	s_add_i32 m0, s10, 68608
	s_nop 0
	global_load_lds_dwordx4 v193, s[6:7]
	s_add_u32 s6, s6, 0x8000
	s_addc_u32 s7, s7, 0
	s_add_i32 m0, s10, 98304
	s_nop 0
	global_load_lds_dwordx4 v102, s[6:7]
	s_add_i32 m0, s10, 99328
	s_nop 0
	global_load_lds_dwordx4 v110, s[6:7]
	s_add_i32 m0, s10, 100352
	s_nop 0
	global_load_lds_dwordx4 v112, s[6:7]
	s_add_i32 m0, s10, 101376
	s_nop 0
	global_load_lds_dwordx4 v193, s[6:7]
	s_add_u32 s6, s6, 0x8000
	s_addc_u32 s7, s7, 0
	s_waitcnt vmcnt(12)
	ds_read_b128 v[38:41], v5 offset:10496
	ds_read_b128 v[42:45], v52 offset:10496
	ds_read_b128 v[46:49], v55 offset:10496
	ds_read_b128 v[196:199], v56 offset:10496
	s_waitcnt lgkmcnt(3)
	v_mfma_f32_32x32x16_bf16 v[212:227], v[70:73], v[38:41], 0
	s_waitcnt lgkmcnt(2)
	v_mfma_f32_32x32x16_bf16 v[212:227], v[74:77], v[42:45], v[212:227]
	s_waitcnt lgkmcnt(1)
	v_mfma_f32_32x32x16_bf16 v[212:227], v[78:81], v[46:49], v[212:227]
	s_waitcnt lgkmcnt(0)
	v_mfma_f32_32x32x16_bf16 v[212:227], v[82:85], v[196:199], v[212:227]
	v_mfma_f32_32x32x16_bf16 v[6:21], v[86:89], v[38:41], 0
	v_mfma_f32_32x32x16_bf16 v[6:21], v[90:93], v[42:45], v[6:21]
	v_mfma_f32_32x32x16_bf16 v[6:21], v[94:97], v[46:49], v[6:21]
	v_mfma_f32_32x32x16_bf16 v[6:21], v[98:101], v[196:199], v[6:21]
	s_nop 7
	s_cmpk_gt_i32 s11, 0
	s_cselect_b64 vcc, -1, 0
	v_max_f32_e32 v108, 0, v212
	v_max_f32_e32 v109, 0, v213
	v_pk_mul_f32 v[0:1], v[22:23], v[108:109]
	v_max_f32_e32 v210, 0, v214
	v_max_f32_e32 v211, 0, v215
	v_pk_fma_f32 v[0:1], v[24:25], v[210:211], v[0:1]
	v_max_f32_e32 v108, 0, v216
	v_max_f32_e32 v109, 0, v217
	v_pk_fma_f32 v[0:1], v[26:27], v[108:109], v[0:1]
	v_max_f32_e32 v210, 0, v218
	v_max_f32_e32 v211, 0, v219
	v_pk_fma_f32 v[0:1], v[28:29], v[210:211], v[0:1]
	v_max_f32_e32 v108, 0, v220
	v_max_f32_e32 v109, 0, v221
	v_pk_fma_f32 v[0:1], v[30:31], v[108:109], v[0:1]
	v_max_f32_e32 v210, 0, v222
	v_max_f32_e32 v211, 0, v223
	v_pk_fma_f32 v[0:1], v[32:33], v[210:211], v[0:1]
	v_max_f32_e32 v108, 0, v224
	v_max_f32_e32 v109, 0, v225
	v_pk_fma_f32 v[0:1], v[34:35], v[108:109], v[0:1]
	v_max_f32_e32 v210, 0, v226
	v_max_f32_e32 v211, 0, v227
	v_pk_fma_f32 v[0:1], v[36:37], v[210:211], v[0:1]
	v_add_f32_e32 v0, v0, v1
	v_ashrrev_i32_e32 v1, 31, v0
	v_or_b32_e32 v1, 0x80000000, v1
	v_xor_b32_e32 v0, v1, v0
	v_cndmask_b32_e32 v133, v123, v0, vcc
	s_add_i32 m0, s10, 0
	s_nop 0
	global_load_lds_dwordx4 v102, s[6:7]
	s_add_i32 m0, s10, 1024
	s_nop 0
	global_load_lds_dwordx4 v110, s[6:7]
	s_add_i32 m0, s10, 2048
	s_nop 0
	global_load_lds_dwordx4 v112, s[6:7]
	s_add_i32 m0, s10, 3072
	s_nop 0
	global_load_lds_dwordx4 v193, s[6:7]
	s_add_u32 s6, s6, 0x8000
	s_addc_u32 s7, s7, 0
	s_waitcnt vmcnt(12)
	ds_read_b128 v[38:41], v5 offset:43264
	ds_read_b128 v[42:45], v52 offset:43264
	ds_read_b128 v[46:49], v55 offset:43264
	ds_read_b128 v[196:199], v56 offset:43264
	s_waitcnt lgkmcnt(3)
	v_mfma_f32_32x32x16_bf16 v[212:227], v[70:73], v[38:41], 0
	s_waitcnt lgkmcnt(2)
	v_mfma_f32_32x32x16_bf16 v[212:227], v[74:77], v[42:45], v[212:227]
	s_waitcnt lgkmcnt(1)
	v_mfma_f32_32x32x16_bf16 v[212:227], v[78:81], v[46:49], v[212:227]
	s_waitcnt lgkmcnt(0)
	v_mfma_f32_32x32x16_bf16 v[212:227], v[82:85], v[196:199], v[212:227]
	s_cmpk_gt_i32 s11, 0
	s_cselect_b64 vcc, -1, 0
	v_max_f32_e32 v108, 0, v6
	v_max_f32_e32 v109, 0, v7
	v_pk_mul_f32 v[50:51], v[244:245], v[108:109]
	v_max_f32_e32 v210, 0, v8
	v_max_f32_e32 v211, 0, v9
	v_pk_fma_f32 v[50:51], v[246:247], v[210:211], v[50:51]
	v_max_f32_e32 v108, 0, v10
	v_max_f32_e32 v109, 0, v11
	v_pk_fma_f32 v[50:51], v[248:249], v[108:109], v[50:51]
	v_max_f32_e32 v210, 0, v12
	v_max_f32_e32 v211, 0, v13
	v_pk_fma_f32 v[50:51], v[250:251], v[210:211], v[50:51]
	v_max_f32_e32 v108, 0, v14
	v_max_f32_e32 v109, 0, v15
	v_pk_fma_f32 v[50:51], v[252:253], v[108:109], v[50:51]
	v_max_f32_e32 v210, 0, v16
	v_max_f32_e32 v211, 0, v17
	v_pk_fma_f32 v[50:51], v[254:255], v[210:211], v[50:51]
	v_max_f32_e32 v108, 0, v18
	v_max_f32_e32 v109, 0, v19
	v_pk_fma_f32 v[50:51], v[200:201], v[108:109], v[50:51]
	v_max_f32_e32 v210, 0, v20
	v_max_f32_e32 v211, 0, v21
	v_pk_fma_f32 v[50:51], v[202:203], v[210:211], v[50:51]
	v_add_f32_e32 v50, v50, v51
	v_ashrrev_i32_e32 v51, 31, v50
	v_or_b32_e32 v51, 0x80000000, v51
	v_xor_b32_e32 v50, v51, v50
	v_cndmask_b32_e32 v50, v123, v50, vcc
	global_store_dword v243, v50, s[8:9]
	v_mfma_f32_32x32x16_bf16 v[6:21], v[86:89], v[38:41], 0
	v_mfma_f32_32x32x16_bf16 v[6:21], v[90:93], v[42:45], v[6:21]
	v_mfma_f32_32x32x16_bf16 v[6:21], v[94:97], v[46:49], v[6:21]
	v_mfma_f32_32x32x16_bf16 v[6:21], v[98:101], v[196:199], v[6:21]
	s_cmpk_gt_i32 s11, 8
	s_cselect_b64 vcc, -1, 0
	v_max_f32_e32 v108, 0, v212
	v_max_f32_e32 v109, 0, v213
	v_pk_mul_f32 v[0:1], v[22:23], v[108:109]
	v_max_f32_e32 v210, 0, v214
	v_max_f32_e32 v211, 0, v215
	v_pk_fma_f32 v[0:1], v[24:25], v[210:211], v[0:1]
	v_max_f32_e32 v108, 0, v216
	v_max_f32_e32 v109, 0, v217
	v_pk_fma_f32 v[0:1], v[26:27], v[108:109], v[0:1]
	v_max_f32_e32 v210, 0, v218
	v_max_f32_e32 v211, 0, v219
	v_pk_fma_f32 v[0:1], v[28:29], v[210:211], v[0:1]
	v_max_f32_e32 v108, 0, v220
	v_max_f32_e32 v109, 0, v221
	v_pk_fma_f32 v[0:1], v[30:31], v[108:109], v[0:1]
	v_max_f32_e32 v210, 0, v222
	v_max_f32_e32 v211, 0, v223
	v_pk_fma_f32 v[0:1], v[32:33], v[210:211], v[0:1]
	v_max_f32_e32 v108, 0, v224
	v_max_f32_e32 v109, 0, v225
	v_pk_fma_f32 v[0:1], v[34:35], v[108:109], v[0:1]
	v_max_f32_e32 v210, 0, v226
	v_max_f32_e32 v211, 0, v227
	v_pk_fma_f32 v[0:1], v[36:37], v[210:211], v[0:1]
	v_add_f32_e32 v0, v0, v1
	v_ashrrev_i32_e32 v1, 31, v0
	v_or_b32_e32 v1, 0x80000000, v1
	v_xor_b32_e32 v0, v1, v0
	v_cndmask_b32_e32 v132, v123, v0, vcc
	s_add_i32 m0, s10, 32768
	s_nop 0
	global_load_lds_dwordx4 v102, s[6:7]
	s_add_i32 m0, s10, 33792
	s_nop 0
	global_load_lds_dwordx4 v110, s[6:7]
	s_add_i32 m0, s10, 34816
	s_nop 0
	global_load_lds_dwordx4 v112, s[6:7]
	s_add_i32 m0, s10, 35840
	s_nop 0
	global_load_lds_dwordx4 v193, s[6:7]
	s_add_u32 s6, s6, 0x8000
	s_addc_u32 s7, s7, 0
	s_waitcnt vmcnt(13)
	v_add_u32_e32 v228, 0x10000, v5
	ds_read_b128 v[38:41], v228 offset:10496
	v_add_u32_e32 v228, 0x10000, v52
	ds_read_b128 v[42:45], v228 offset:10496
	v_add_u32_e32 v228, 0x10000, v55
	ds_read_b128 v[46:49], v228 offset:10496
	v_add_u32_e32 v228, 0x10000, v56
	ds_read_b128 v[196:199], v228 offset:10496
	s_waitcnt lgkmcnt(3)
	v_mfma_f32_32x32x16_bf16 v[212:227], v[70:73], v[38:41], 0
	s_waitcnt lgkmcnt(2)
	v_mfma_f32_32x32x16_bf16 v[212:227], v[74:77], v[42:45], v[212:227]
	s_waitcnt lgkmcnt(1)
	v_mfma_f32_32x32x16_bf16 v[212:227], v[78:81], v[46:49], v[212:227]
	s_waitcnt lgkmcnt(0)
	v_mfma_f32_32x32x16_bf16 v[212:227], v[82:85], v[196:199], v[212:227]
	s_cmpk_gt_i32 s11, 8
	s_cselect_b64 vcc, -1, 0
	v_max_f32_e32 v108, 0, v6
	v_max_f32_e32 v109, 0, v7
	v_pk_mul_f32 v[50:51], v[244:245], v[108:109]
	v_max_f32_e32 v210, 0, v8
	v_max_f32_e32 v211, 0, v9
	v_pk_fma_f32 v[50:51], v[246:247], v[210:211], v[50:51]
	v_max_f32_e32 v108, 0, v10
	v_max_f32_e32 v109, 0, v11
	v_pk_fma_f32 v[50:51], v[248:249], v[108:109], v[50:51]
	v_max_f32_e32 v210, 0, v12
	v_max_f32_e32 v211, 0, v13
	v_pk_fma_f32 v[50:51], v[250:251], v[210:211], v[50:51]
	v_max_f32_e32 v108, 0, v14
	v_max_f32_e32 v109, 0, v15
	v_pk_fma_f32 v[50:51], v[252:253], v[108:109], v[50:51]
	v_max_f32_e32 v210, 0, v16
	v_max_f32_e32 v211, 0, v17
	v_pk_fma_f32 v[50:51], v[254:255], v[210:211], v[50:51]
	v_max_f32_e32 v108, 0, v18
	v_max_f32_e32 v109, 0, v19
	v_pk_fma_f32 v[50:51], v[200:201], v[108:109], v[50:51]
	v_max_f32_e32 v210, 0, v20
	v_max_f32_e32 v211, 0, v21
	v_pk_fma_f32 v[50:51], v[202:203], v[210:211], v[50:51]
	v_add_f32_e32 v50, v50, v51
	v_ashrrev_i32_e32 v51, 31, v50
	v_or_b32_e32 v51, 0x80000000, v51
	v_xor_b32_e32 v50, v51, v50
	v_cndmask_b32_e32 v50, v123, v50, vcc
	global_store_dword v243, v50, s[8:9] offset:2048
	s_add_u32 s8, s8, 0x1000
	s_addc_u32 s9, s9, 0
	v_mfma_f32_32x32x16_bf16 v[6:21], v[86:89], v[38:41], 0
	v_mfma_f32_32x32x16_bf16 v[6:21], v[90:93], v[42:45], v[6:21]
	v_mfma_f32_32x32x16_bf16 v[6:21], v[94:97], v[46:49], v[6:21]
	v_mfma_f32_32x32x16_bf16 v[6:21], v[98:101], v[196:199], v[6:21]
	s_cmpk_gt_i32 s11, 16
	s_cselect_b64 vcc, -1, 0
	v_max_f32_e32 v108, 0, v212
	v_max_f32_e32 v109, 0, v213
	v_pk_mul_f32 v[0:1], v[22:23], v[108:109]
	v_max_f32_e32 v210, 0, v214
	v_max_f32_e32 v211, 0, v215
	v_pk_fma_f32 v[0:1], v[24:25], v[210:211], v[0:1]
	v_max_f32_e32 v108, 0, v216
	v_max_f32_e32 v109, 0, v217
	v_pk_fma_f32 v[0:1], v[26:27], v[108:109], v[0:1]
	v_max_f32_e32 v210, 0, v218
	v_max_f32_e32 v211, 0, v219
	v_pk_fma_f32 v[0:1], v[28:29], v[210:211], v[0:1]
	v_max_f32_e32 v108, 0, v220
	v_max_f32_e32 v109, 0, v221
	v_pk_fma_f32 v[0:1], v[30:31], v[108:109], v[0:1]
	v_max_f32_e32 v210, 0, v222
	v_max_f32_e32 v211, 0, v223
	v_pk_fma_f32 v[0:1], v[32:33], v[210:211], v[0:1]
	v_max_f32_e32 v108, 0, v224
	v_max_f32_e32 v109, 0, v225
	v_pk_fma_f32 v[0:1], v[34:35], v[108:109], v[0:1]
	v_max_f32_e32 v210, 0, v226
	v_max_f32_e32 v211, 0, v227
	v_pk_fma_f32 v[0:1], v[36:37], v[210:211], v[0:1]
	v_add_f32_e32 v0, v0, v1
	v_ashrrev_i32_e32 v1, 31, v0
	v_or_b32_e32 v1, 0x80000000, v1
	v_xor_b32_e32 v0, v1, v0
	v_cndmask_b32_e32 v135, v123, v0, vcc
	s_add_i32 m0, s10, 65536
	s_nop 0
	global_load_lds_dwordx4 v102, s[6:7]
	s_add_i32 m0, s10, 66560
	s_nop 0
	global_load_lds_dwordx4 v110, s[6:7]
	s_add_i32 m0, s10, 67584
	s_nop 0
	global_load_lds_dwordx4 v112, s[6:7]
	s_add_i32 m0, s10, 68608
	s_nop 0
	global_load_lds_dwordx4 v193, s[6:7]
	s_add_u32 s6, s6, 0x8000
	s_addc_u32 s7, s7, 0
	s_waitcnt vmcnt(14)
	v_add_u32_e32 v228, 0x10000, v5
	ds_read_b128 v[38:41], v228 offset:43264
	v_add_u32_e32 v228, 0x10000, v52
	ds_read_b128 v[42:45], v228 offset:43264
	v_add_u32_e32 v228, 0x10000, v55
	ds_read_b128 v[46:49], v228 offset:43264
	v_add_u32_e32 v228, 0x10000, v56
	ds_read_b128 v[196:199], v228 offset:43264
	s_waitcnt lgkmcnt(3)
	v_mfma_f32_32x32x16_bf16 v[212:227], v[70:73], v[38:41], 0
	s_waitcnt lgkmcnt(2)
	v_mfma_f32_32x32x16_bf16 v[212:227], v[74:77], v[42:45], v[212:227]
	s_waitcnt lgkmcnt(1)
	v_mfma_f32_32x32x16_bf16 v[212:227], v[78:81], v[46:49], v[212:227]
	s_waitcnt lgkmcnt(0)
	v_mfma_f32_32x32x16_bf16 v[212:227], v[82:85], v[196:199], v[212:227]
	s_cmpk_gt_i32 s11, 16
	s_cselect_b64 vcc, -1, 0
	v_max_f32_e32 v108, 0, v6
	v_max_f32_e32 v109, 0, v7
	v_pk_mul_f32 v[50:51], v[244:245], v[108:109]
	v_max_f32_e32 v210, 0, v8
	v_max_f32_e32 v211, 0, v9
	v_pk_fma_f32 v[50:51], v[246:247], v[210:211], v[50:51]
	v_max_f32_e32 v108, 0, v10
	v_max_f32_e32 v109, 0, v11
	v_pk_fma_f32 v[50:51], v[248:249], v[108:109], v[50:51]
	v_max_f32_e32 v210, 0, v12
	v_max_f32_e32 v211, 0, v13
	v_pk_fma_f32 v[50:51], v[250:251], v[210:211], v[50:51]
	v_max_f32_e32 v108, 0, v14
	v_max_f32_e32 v109, 0, v15
	v_pk_fma_f32 v[50:51], v[252:253], v[108:109], v[50:51]
	v_max_f32_e32 v210, 0, v16
	v_max_f32_e32 v211, 0, v17
	v_pk_fma_f32 v[50:51], v[254:255], v[210:211], v[50:51]
	v_max_f32_e32 v108, 0, v18
	v_max_f32_e32 v109, 0, v19
	v_pk_fma_f32 v[50:51], v[200:201], v[108:109], v[50:51]
	v_max_f32_e32 v210, 0, v20
	v_max_f32_e32 v211, 0, v21
	v_pk_fma_f32 v[50:51], v[202:203], v[210:211], v[50:51]
	v_add_f32_e32 v50, v50, v51
	v_ashrrev_i32_e32 v51, 31, v50
	v_or_b32_e32 v51, 0x80000000, v51
	v_xor_b32_e32 v50, v51, v50
	v_cndmask_b32_e32 v50, v123, v50, vcc
	global_store_dword v243, v50, s[8:9]
	v_mfma_f32_32x32x16_bf16 v[6:21], v[86:89], v[38:41], 0
	v_mfma_f32_32x32x16_bf16 v[6:21], v[90:93], v[42:45], v[6:21]
	v_mfma_f32_32x32x16_bf16 v[6:21], v[94:97], v[46:49], v[6:21]
	v_mfma_f32_32x32x16_bf16 v[6:21], v[98:101], v[196:199], v[6:21]
	s_cmpk_gt_i32 s11, 24
	s_cselect_b64 vcc, -1, 0
	v_max_f32_e32 v108, 0, v212
	v_max_f32_e32 v109, 0, v213
	v_pk_mul_f32 v[0:1], v[22:23], v[108:109]
	v_max_f32_e32 v210, 0, v214
	v_max_f32_e32 v211, 0, v215
	v_pk_fma_f32 v[0:1], v[24:25], v[210:211], v[0:1]
	v_max_f32_e32 v108, 0, v216
	v_max_f32_e32 v109, 0, v217
	v_pk_fma_f32 v[0:1], v[26:27], v[108:109], v[0:1]
	v_max_f32_e32 v210, 0, v218
	v_max_f32_e32 v211, 0, v219
	v_pk_fma_f32 v[0:1], v[28:29], v[210:211], v[0:1]
	v_max_f32_e32 v108, 0, v220
	v_max_f32_e32 v109, 0, v221
	v_pk_fma_f32 v[0:1], v[30:31], v[108:109], v[0:1]
	v_max_f32_e32 v210, 0, v222
	v_max_f32_e32 v211, 0, v223
	v_pk_fma_f32 v[0:1], v[32:33], v[210:211], v[0:1]
	v_max_f32_e32 v108, 0, v224
	v_max_f32_e32 v109, 0, v225
	v_pk_fma_f32 v[0:1], v[34:35], v[108:109], v[0:1]
	v_max_f32_e32 v210, 0, v226
	v_max_f32_e32 v211, 0, v227
	v_pk_fma_f32 v[0:1], v[36:37], v[210:211], v[0:1]
	v_add_f32_e32 v0, v0, v1
	v_ashrrev_i32_e32 v1, 31, v0
	v_or_b32_e32 v1, 0x80000000, v1
	v_xor_b32_e32 v0, v1, v0
	v_cndmask_b32_e32 v134, v123, v0, vcc
	s_add_i32 m0, s10, 98304
	s_nop 0
	global_load_lds_dwordx4 v102, s[6:7]
	s_add_i32 m0, s10, 99328
	s_nop 0
	global_load_lds_dwordx4 v110, s[6:7]
	s_add_i32 m0, s10, 100352
	s_nop 0
	global_load_lds_dwordx4 v112, s[6:7]
	s_add_i32 m0, s10, 101376
	s_nop 0
	global_load_lds_dwordx4 v193, s[6:7]
	s_add_u32 s6, s6, 0x8000
	s_addc_u32 s7, s7, 0
	s_waitcnt vmcnt(15)
	ds_read_b128 v[38:41], v5 offset:10496
	ds_read_b128 v[42:45], v52 offset:10496
	ds_read_b128 v[46:49], v55 offset:10496
	ds_read_b128 v[196:199], v56 offset:10496
	s_waitcnt lgkmcnt(3)
	v_mfma_f32_32x32x16_bf16 v[212:227], v[70:73], v[38:41], 0
	s_waitcnt lgkmcnt(2)
	v_mfma_f32_32x32x16_bf16 v[212:227], v[74:77], v[42:45], v[212:227]
	s_waitcnt lgkmcnt(1)
	v_mfma_f32_32x32x16_bf16 v[212:227], v[78:81], v[46:49], v[212:227]
	s_waitcnt lgkmcnt(0)
	v_mfma_f32_32x32x16_bf16 v[212:227], v[82:85], v[196:199], v[212:227]
	s_cmpk_gt_i32 s11, 24
	s_cselect_b64 vcc, -1, 0
	v_max_f32_e32 v108, 0, v6
	v_max_f32_e32 v109, 0, v7
	v_pk_mul_f32 v[50:51], v[244:245], v[108:109]
	v_max_f32_e32 v210, 0, v8
	v_max_f32_e32 v211, 0, v9
	v_pk_fma_f32 v[50:51], v[246:247], v[210:211], v[50:51]
	v_max_f32_e32 v108, 0, v10
	v_max_f32_e32 v109, 0, v11
	v_pk_fma_f32 v[50:51], v[248:249], v[108:109], v[50:51]
	v_max_f32_e32 v210, 0, v12
	v_max_f32_e32 v211, 0, v13
	v_pk_fma_f32 v[50:51], v[250:251], v[210:211], v[50:51]
	v_max_f32_e32 v108, 0, v14
	v_max_f32_e32 v109, 0, v15
	v_pk_fma_f32 v[50:51], v[252:253], v[108:109], v[50:51]
	v_max_f32_e32 v210, 0, v16
	v_max_f32_e32 v211, 0, v17
	v_pk_fma_f32 v[50:51], v[254:255], v[210:211], v[50:51]
	v_max_f32_e32 v108, 0, v18
	v_max_f32_e32 v109, 0, v19
	v_pk_fma_f32 v[50:51], v[200:201], v[108:109], v[50:51]
	v_max_f32_e32 v210, 0, v20
	v_max_f32_e32 v211, 0, v21
	v_pk_fma_f32 v[50:51], v[202:203], v[210:211], v[50:51]
	v_add_f32_e32 v50, v50, v51
	v_ashrrev_i32_e32 v51, 31, v50
	v_or_b32_e32 v51, 0x80000000, v51
	v_xor_b32_e32 v50, v51, v50
	v_cndmask_b32_e32 v50, v123, v50, vcc
	global_store_dword v243, v50, s[8:9] offset:2048
	s_add_u32 s8, s8, 0x1000
	s_addc_u32 s9, s9, 0
	v_mfma_f32_32x32x16_bf16 v[6:21], v[86:89], v[38:41], 0
	v_mfma_f32_32x32x16_bf16 v[6:21], v[90:93], v[42:45], v[6:21]
	v_mfma_f32_32x32x16_bf16 v[6:21], v[94:97], v[46:49], v[6:21]
	v_mfma_f32_32x32x16_bf16 v[6:21], v[98:101], v[196:199], v[6:21]
	s_cmpk_gt_i32 s11, 32
	s_cselect_b64 vcc, -1, 0
	v_max_f32_e32 v108, 0, v212
	v_max_f32_e32 v109, 0, v213
	v_pk_mul_f32 v[0:1], v[22:23], v[108:109]
	v_max_f32_e32 v210, 0, v214
	v_max_f32_e32 v211, 0, v215
	v_pk_fma_f32 v[0:1], v[24:25], v[210:211], v[0:1]
	v_max_f32_e32 v108, 0, v216
	v_max_f32_e32 v109, 0, v217
	v_pk_fma_f32 v[0:1], v[26:27], v[108:109], v[0:1]
	v_max_f32_e32 v210, 0, v218
	v_max_f32_e32 v211, 0, v219
	v_pk_fma_f32 v[0:1], v[28:29], v[210:211], v[0:1]
	v_max_f32_e32 v108, 0, v220
	v_max_f32_e32 v109, 0, v221
	v_pk_fma_f32 v[0:1], v[30:31], v[108:109], v[0:1]
	v_max_f32_e32 v210, 0, v222
	v_max_f32_e32 v211, 0, v223
	v_pk_fma_f32 v[0:1], v[32:33], v[210:211], v[0:1]
	v_max_f32_e32 v108, 0, v224
	v_max_f32_e32 v109, 0, v225
	v_pk_fma_f32 v[0:1], v[34:35], v[108:109], v[0:1]
	v_max_f32_e32 v210, 0, v226
	v_max_f32_e32 v211, 0, v227
	v_pk_fma_f32 v[0:1], v[36:37], v[210:211], v[0:1]
	v_add_f32_e32 v0, v0, v1
	v_ashrrev_i32_e32 v1, 31, v0
	v_or_b32_e32 v1, 0x80000000, v1
	v_xor_b32_e32 v0, v1, v0
	v_cndmask_b32_e32 v138, v123, v0, vcc
	s_add_i32 m0, s10, 0
	s_nop 0
	global_load_lds_dwordx4 v102, s[6:7]
	s_add_i32 m0, s10, 1024
	s_nop 0
	global_load_lds_dwordx4 v110, s[6:7]
	s_add_i32 m0, s10, 2048
	s_nop 0
	global_load_lds_dwordx4 v112, s[6:7]
	s_add_i32 m0, s10, 3072
	s_nop 0
	global_load_lds_dwordx4 v193, s[6:7]
	s_add_u32 s6, s6, 0x8000
	s_addc_u32 s7, s7, 0
	s_waitcnt vmcnt(15)
	ds_read_b128 v[38:41], v5 offset:43264
	ds_read_b128 v[42:45], v52 offset:43264
	ds_read_b128 v[46:49], v55 offset:43264
	ds_read_b128 v[196:199], v56 offset:43264
	s_waitcnt lgkmcnt(3)
	v_mfma_f32_32x32x16_bf16 v[212:227], v[70:73], v[38:41], 0
	s_waitcnt lgkmcnt(2)
	v_mfma_f32_32x32x16_bf16 v[212:227], v[74:77], v[42:45], v[212:227]
	s_waitcnt lgkmcnt(1)
	v_mfma_f32_32x32x16_bf16 v[212:227], v[78:81], v[46:49], v[212:227]
	s_waitcnt lgkmcnt(0)
	v_mfma_f32_32x32x16_bf16 v[212:227], v[82:85], v[196:199], v[212:227]
	s_cmpk_gt_i32 s11, 32
	s_cselect_b64 vcc, -1, 0
	v_max_f32_e32 v108, 0, v6
	v_max_f32_e32 v109, 0, v7
	v_pk_mul_f32 v[50:51], v[244:245], v[108:109]
	v_max_f32_e32 v210, 0, v8
	v_max_f32_e32 v211, 0, v9
	v_pk_fma_f32 v[50:51], v[246:247], v[210:211], v[50:51]
	v_max_f32_e32 v108, 0, v10
	v_max_f32_e32 v109, 0, v11
	v_pk_fma_f32 v[50:51], v[248:249], v[108:109], v[50:51]
	v_max_f32_e32 v210, 0, v12
	v_max_f32_e32 v211, 0, v13
	v_pk_fma_f32 v[50:51], v[250:251], v[210:211], v[50:51]
	v_max_f32_e32 v108, 0, v14
	v_max_f32_e32 v109, 0, v15
	v_pk_fma_f32 v[50:51], v[252:253], v[108:109], v[50:51]
	v_max_f32_e32 v210, 0, v16
	v_max_f32_e32 v211, 0, v17
	v_pk_fma_f32 v[50:51], v[254:255], v[210:211], v[50:51]
	v_max_f32_e32 v108, 0, v18
	v_max_f32_e32 v109, 0, v19
	v_pk_fma_f32 v[50:51], v[200:201], v[108:109], v[50:51]
	v_max_f32_e32 v210, 0, v20
	v_max_f32_e32 v211, 0, v21
	v_pk_fma_f32 v[50:51], v[202:203], v[210:211], v[50:51]
	v_add_f32_e32 v50, v50, v51
	v_ashrrev_i32_e32 v51, 31, v50
	v_or_b32_e32 v51, 0x80000000, v51
	v_xor_b32_e32 v50, v51, v50
	v_cndmask_b32_e32 v50, v123, v50, vcc
	global_store_dword v243, v50, s[8:9]
	v_mfma_f32_32x32x16_bf16 v[6:21], v[86:89], v[38:41], 0
	v_mfma_f32_32x32x16_bf16 v[6:21], v[90:93], v[42:45], v[6:21]
	v_mfma_f32_32x32x16_bf16 v[6:21], v[94:97], v[46:49], v[6:21]
	v_mfma_f32_32x32x16_bf16 v[6:21], v[98:101], v[196:199], v[6:21]
	s_cmpk_gt_i32 s11, 40
	s_cselect_b64 vcc, -1, 0
	v_max_f32_e32 v108, 0, v212
	v_max_f32_e32 v109, 0, v213
	v_pk_mul_f32 v[0:1], v[22:23], v[108:109]
	v_max_f32_e32 v210, 0, v214
	v_max_f32_e32 v211, 0, v215
	v_pk_fma_f32 v[0:1], v[24:25], v[210:211], v[0:1]
	v_max_f32_e32 v108, 0, v216
	v_max_f32_e32 v109, 0, v217
	v_pk_fma_f32 v[0:1], v[26:27], v[108:109], v[0:1]
	v_max_f32_e32 v210, 0, v218
	v_max_f32_e32 v211, 0, v219
	v_pk_fma_f32 v[0:1], v[28:29], v[210:211], v[0:1]
	v_max_f32_e32 v108, 0, v220
	v_max_f32_e32 v109, 0, v221
	v_pk_fma_f32 v[0:1], v[30:31], v[108:109], v[0:1]
	v_max_f32_e32 v210, 0, v222
	v_max_f32_e32 v211, 0, v223
	v_pk_fma_f32 v[0:1], v[32:33], v[210:211], v[0:1]
	v_max_f32_e32 v108, 0, v224
	v_max_f32_e32 v109, 0, v225
	v_pk_fma_f32 v[0:1], v[34:35], v[108:109], v[0:1]
	v_max_f32_e32 v210, 0, v226
	v_max_f32_e32 v211, 0, v227
	v_pk_fma_f32 v[0:1], v[36:37], v[210:211], v[0:1]
	v_add_f32_e32 v0, v0, v1
	v_ashrrev_i32_e32 v1, 31, v0
	v_or_b32_e32 v1, 0x80000000, v1
	v_xor_b32_e32 v0, v1, v0
	v_cndmask_b32_e32 v137, v123, v0, vcc
	s_add_i32 m0, s10, 32768
	s_nop 0
	global_load_lds_dwordx4 v102, s[6:7]
	s_add_i32 m0, s10, 33792
	s_nop 0
	global_load_lds_dwordx4 v110, s[6:7]
	s_add_i32 m0, s10, 34816
	s_nop 0
	global_load_lds_dwordx4 v112, s[6:7]
	s_add_i32 m0, s10, 35840
	s_nop 0
	global_load_lds_dwordx4 v193, s[6:7]
	s_add_u32 s6, s6, 0x8000
	s_addc_u32 s7, s7, 0
	s_waitcnt vmcnt(15)
	v_add_u32_e32 v228, 0x10000, v5
	ds_read_b128 v[38:41], v228 offset:10496
	v_add_u32_e32 v228, 0x10000, v52
	ds_read_b128 v[42:45], v228 offset:10496
	v_add_u32_e32 v228, 0x10000, v55
	ds_read_b128 v[46:49], v228 offset:10496
	v_add_u32_e32 v228, 0x10000, v56
	ds_read_b128 v[196:199], v228 offset:10496
	s_waitcnt lgkmcnt(3)
	v_mfma_f32_32x32x16_bf16 v[212:227], v[70:73], v[38:41], 0
	s_waitcnt lgkmcnt(2)
	v_mfma_f32_32x32x16_bf16 v[212:227], v[74:77], v[42:45], v[212:227]
	s_waitcnt lgkmcnt(1)
	v_mfma_f32_32x32x16_bf16 v[212:227], v[78:81], v[46:49], v[212:227]
	s_waitcnt lgkmcnt(0)
	v_mfma_f32_32x32x16_bf16 v[212:227], v[82:85], v[196:199], v[212:227]
	s_cmpk_gt_i32 s11, 40
	s_cselect_b64 vcc, -1, 0
	v_max_f32_e32 v108, 0, v6
	v_max_f32_e32 v109, 0, v7
	v_pk_mul_f32 v[50:51], v[244:245], v[108:109]
	v_max_f32_e32 v210, 0, v8
	v_max_f32_e32 v211, 0, v9
	v_pk_fma_f32 v[50:51], v[246:247], v[210:211], v[50:51]
	v_max_f32_e32 v108, 0, v10
	v_max_f32_e32 v109, 0, v11
	v_pk_fma_f32 v[50:51], v[248:249], v[108:109], v[50:51]
	v_max_f32_e32 v210, 0, v12
	v_max_f32_e32 v211, 0, v13
	v_pk_fma_f32 v[50:51], v[250:251], v[210:211], v[50:51]
	v_max_f32_e32 v108, 0, v14
	v_max_f32_e32 v109, 0, v15
	v_pk_fma_f32 v[50:51], v[252:253], v[108:109], v[50:51]
	v_max_f32_e32 v210, 0, v16
	v_max_f32_e32 v211, 0, v17
	v_pk_fma_f32 v[50:51], v[254:255], v[210:211], v[50:51]
	v_max_f32_e32 v108, 0, v18
	v_max_f32_e32 v109, 0, v19
	v_pk_fma_f32 v[50:51], v[200:201], v[108:109], v[50:51]
	v_max_f32_e32 v210, 0, v20
	v_max_f32_e32 v211, 0, v21
	v_pk_fma_f32 v[50:51], v[202:203], v[210:211], v[50:51]
	v_add_f32_e32 v50, v50, v51
	v_ashrrev_i32_e32 v51, 31, v50
	v_or_b32_e32 v51, 0x80000000, v51
	v_xor_b32_e32 v50, v51, v50
	v_cndmask_b32_e32 v50, v123, v50, vcc
	global_store_dword v243, v50, s[8:9] offset:2048
	s_add_u32 s8, s8, 0x1000
	s_addc_u32 s9, s9, 0
	v_mfma_f32_32x32x16_bf16 v[6:21], v[86:89], v[38:41], 0
	v_mfma_f32_32x32x16_bf16 v[6:21], v[90:93], v[42:45], v[6:21]
	v_mfma_f32_32x32x16_bf16 v[6:21], v[94:97], v[46:49], v[6:21]
	v_mfma_f32_32x32x16_bf16 v[6:21], v[98:101], v[196:199], v[6:21]
	s_cmpk_gt_i32 s11, 48
	s_cselect_b64 vcc, -1, 0
	v_max_f32_e32 v108, 0, v212
	v_max_f32_e32 v109, 0, v213
	v_pk_mul_f32 v[0:1], v[22:23], v[108:109]
	v_max_f32_e32 v210, 0, v214
	v_max_f32_e32 v211, 0, v215
	v_pk_fma_f32 v[0:1], v[24:25], v[210:211], v[0:1]
	v_max_f32_e32 v108, 0, v216
	v_max_f32_e32 v109, 0, v217
	v_pk_fma_f32 v[0:1], v[26:27], v[108:109], v[0:1]
	v_max_f32_e32 v210, 0, v218
	v_max_f32_e32 v211, 0, v219
	v_pk_fma_f32 v[0:1], v[28:29], v[210:211], v[0:1]
	v_max_f32_e32 v108, 0, v220
	v_max_f32_e32 v109, 0, v221
	v_pk_fma_f32 v[0:1], v[30:31], v[108:109], v[0:1]
	v_max_f32_e32 v210, 0, v222
	v_max_f32_e32 v211, 0, v223
	v_pk_fma_f32 v[0:1], v[32:33], v[210:211], v[0:1]
	v_max_f32_e32 v108, 0, v224
	v_max_f32_e32 v109, 0, v225
	v_pk_fma_f32 v[0:1], v[34:35], v[108:109], v[0:1]
	v_max_f32_e32 v210, 0, v226
	v_max_f32_e32 v211, 0, v227
	v_pk_fma_f32 v[0:1], v[36:37], v[210:211], v[0:1]
	v_add_f32_e32 v0, v0, v1
	v_ashrrev_i32_e32 v1, 31, v0
	v_or_b32_e32 v1, 0x80000000, v1
	v_xor_b32_e32 v0, v1, v0
	v_cndmask_b32_e32 v140, v123, v0, vcc
	s_add_i32 m0, s10, 65536
	s_nop 0
	global_load_lds_dwordx4 v102, s[6:7]
	s_add_i32 m0, s10, 66560
	s_nop 0
	global_load_lds_dwordx4 v110, s[6:7]
	s_add_i32 m0, s10, 67584
	s_nop 0
	global_load_lds_dwordx4 v112, s[6:7]
	s_add_i32 m0, s10, 68608
	s_nop 0
	global_load_lds_dwordx4 v193, s[6:7]
	s_add_u32 s6, s6, 0x8000
	s_addc_u32 s7, s7, 0
	s_waitcnt vmcnt(15)
	v_add_u32_e32 v228, 0x10000, v5
	ds_read_b128 v[38:41], v228 offset:43264
	v_add_u32_e32 v228, 0x10000, v52
	ds_read_b128 v[42:45], v228 offset:43264
	v_add_u32_e32 v228, 0x10000, v55
	ds_read_b128 v[46:49], v228 offset:43264
	v_add_u32_e32 v228, 0x10000, v56
	ds_read_b128 v[196:199], v228 offset:43264
	s_waitcnt lgkmcnt(3)
	v_mfma_f32_32x32x16_bf16 v[212:227], v[70:73], v[38:41], 0
	s_waitcnt lgkmcnt(2)
	v_mfma_f32_32x32x16_bf16 v[212:227], v[74:77], v[42:45], v[212:227]
	s_waitcnt lgkmcnt(1)
	v_mfma_f32_32x32x16_bf16 v[212:227], v[78:81], v[46:49], v[212:227]
	s_waitcnt lgkmcnt(0)
	v_mfma_f32_32x32x16_bf16 v[212:227], v[82:85], v[196:199], v[212:227]
	s_cmpk_gt_i32 s11, 48
	s_cselect_b64 vcc, -1, 0
	v_max_f32_e32 v108, 0, v6
	v_max_f32_e32 v109, 0, v7
	v_pk_mul_f32 v[50:51], v[244:245], v[108:109]
	v_max_f32_e32 v210, 0, v8
	v_max_f32_e32 v211, 0, v9
	v_pk_fma_f32 v[50:51], v[246:247], v[210:211], v[50:51]
	v_max_f32_e32 v108, 0, v10
	v_max_f32_e32 v109, 0, v11
	v_pk_fma_f32 v[50:51], v[248:249], v[108:109], v[50:51]
	v_max_f32_e32 v210, 0, v12
	v_max_f32_e32 v211, 0, v13
	v_pk_fma_f32 v[50:51], v[250:251], v[210:211], v[50:51]
	v_max_f32_e32 v108, 0, v14
	v_max_f32_e32 v109, 0, v15
	v_pk_fma_f32 v[50:51], v[252:253], v[108:109], v[50:51]
	v_max_f32_e32 v210, 0, v16
	v_max_f32_e32 v211, 0, v17
	v_pk_fma_f32 v[50:51], v[254:255], v[210:211], v[50:51]
	v_max_f32_e32 v108, 0, v18
	v_max_f32_e32 v109, 0, v19
	v_pk_fma_f32 v[50:51], v[200:201], v[108:109], v[50:51]
	v_max_f32_e32 v210, 0, v20
	v_max_f32_e32 v211, 0, v21
	v_pk_fma_f32 v[50:51], v[202:203], v[210:211], v[50:51]
	v_add_f32_e32 v50, v50, v51
	v_ashrrev_i32_e32 v51, 31, v50
	v_or_b32_e32 v51, 0x80000000, v51
	v_xor_b32_e32 v50, v51, v50
	v_cndmask_b32_e32 v50, v123, v50, vcc
	global_store_dword v243, v50, s[8:9]
	v_mfma_f32_32x32x16_bf16 v[6:21], v[86:89], v[38:41], 0
	v_mfma_f32_32x32x16_bf16 v[6:21], v[90:93], v[42:45], v[6:21]
	v_mfma_f32_32x32x16_bf16 v[6:21], v[94:97], v[46:49], v[6:21]
	v_mfma_f32_32x32x16_bf16 v[6:21], v[98:101], v[196:199], v[6:21]
	s_cmpk_gt_i32 s11, 56
	s_cselect_b64 vcc, -1, 0
	v_max_f32_e32 v108, 0, v212
	v_max_f32_e32 v109, 0, v213
	v_pk_mul_f32 v[0:1], v[22:23], v[108:109]
	v_max_f32_e32 v210, 0, v214
	v_max_f32_e32 v211, 0, v215
	v_pk_fma_f32 v[0:1], v[24:25], v[210:211], v[0:1]
	v_max_f32_e32 v108, 0, v216
	v_max_f32_e32 v109, 0, v217
	v_pk_fma_f32 v[0:1], v[26:27], v[108:109], v[0:1]
	v_max_f32_e32 v210, 0, v218
	v_max_f32_e32 v211, 0, v219
	v_pk_fma_f32 v[0:1], v[28:29], v[210:211], v[0:1]
	v_max_f32_e32 v108, 0, v220
	v_max_f32_e32 v109, 0, v221
	v_pk_fma_f32 v[0:1], v[30:31], v[108:109], v[0:1]
	v_max_f32_e32 v210, 0, v222
	v_max_f32_e32 v211, 0, v223
	v_pk_fma_f32 v[0:1], v[32:33], v[210:211], v[0:1]
	v_max_f32_e32 v108, 0, v224
	v_max_f32_e32 v109, 0, v225
	v_pk_fma_f32 v[0:1], v[34:35], v[108:109], v[0:1]
	v_max_f32_e32 v210, 0, v226
	v_max_f32_e32 v211, 0, v227
	v_pk_fma_f32 v[0:1], v[36:37], v[210:211], v[0:1]
	v_add_f32_e32 v0, v0, v1
	v_ashrrev_i32_e32 v1, 31, v0
	v_or_b32_e32 v1, 0x80000000, v1
	v_xor_b32_e32 v0, v1, v0
	v_cndmask_b32_e32 v139, v123, v0, vcc
	v_max_f32_e32 v108, 0, v6
	v_max_f32_e32 v109, 0, v7
	v_pk_mul_f32 v[50:51], v[244:245], v[108:109]
	v_max_f32_e32 v210, 0, v8
	v_max_f32_e32 v211, 0, v9
	v_pk_fma_f32 v[50:51], v[246:247], v[210:211], v[50:51]
	v_max_f32_e32 v108, 0, v10
	v_max_f32_e32 v109, 0, v11
	v_pk_fma_f32 v[50:51], v[248:249], v[108:109], v[50:51]
	v_max_f32_e32 v210, 0, v12
	v_max_f32_e32 v211, 0, v13
	v_pk_fma_f32 v[50:51], v[250:251], v[210:211], v[50:51]
	v_max_f32_e32 v108, 0, v14
	v_max_f32_e32 v109, 0, v15
	v_pk_fma_f32 v[50:51], v[252:253], v[108:109], v[50:51]
	v_max_f32_e32 v210, 0, v16
	v_max_f32_e32 v211, 0, v17
	v_pk_fma_f32 v[50:51], v[254:255], v[210:211], v[50:51]
	v_max_f32_e32 v108, 0, v18
	v_max_f32_e32 v109, 0, v19
	v_pk_fma_f32 v[50:51], v[200:201], v[108:109], v[50:51]
	v_max_f32_e32 v210, 0, v20
	v_max_f32_e32 v211, 0, v21
	v_pk_fma_f32 v[50:51], v[202:203], v[210:211], v[50:51]
	v_add_f32_e32 v50, v50, v51
	v_ashrrev_i32_e32 v51, 31, v50
	v_or_b32_e32 v51, 0x80000000, v51
	v_xor_b32_e32 v50, v51, v50
	v_cndmask_b32_e32 v50, v123, v50, vcc
	global_store_dword v243, v50, s[8:9] offset:2048
	s_add_u32 s8, s8, 0x1000
	s_addc_u32 s9, s9, 0
	s_cmpk_gt_i32 s81, 8
	s_cbranch_scc0 .Lix_fill_1
	s_add_i32 m0, s10, 98304
	s_nop 0
	global_load_lds_dwordx4 v102, s[6:7]
	s_add_i32 m0, s10, 99328
	s_nop 0
	global_load_lds_dwordx4 v110, s[6:7]
	s_add_i32 m0, s10, 100352
	s_nop 0
	global_load_lds_dwordx4 v112, s[6:7]
	s_add_i32 m0, s10, 101376
	s_nop 0
	global_load_lds_dwordx4 v193, s[6:7]
	s_add_u32 s6, s6, 0x8000
	s_addc_u32 s7, s7, 0
	s_waitcnt vmcnt(16)
	ds_read_b128 v[38:41], v5 offset:10496
	ds_read_b128 v[42:45], v52 offset:10496
	ds_read_b128 v[46:49], v55 offset:10496
	ds_read_b128 v[196:199], v56 offset:10496
	s_waitcnt lgkmcnt(3)
	v_mfma_f32_32x32x16_bf16 v[212:227], v[70:73], v[38:41], 0
	s_waitcnt lgkmcnt(2)
	v_mfma_f32_32x32x16_bf16 v[212:227], v[74:77], v[42:45], v[212:227]
	s_waitcnt lgkmcnt(1)
	v_mfma_f32_32x32x16_bf16 v[212:227], v[78:81], v[46:49], v[212:227]
	s_waitcnt lgkmcnt(0)
	v_mfma_f32_32x32x16_bf16 v[212:227], v[82:85], v[196:199], v[212:227]
	v_mfma_f32_32x32x16_bf16 v[6:21], v[86:89], v[38:41], 0
	v_mfma_f32_32x32x16_bf16 v[6:21], v[90:93], v[42:45], v[6:21]
	v_mfma_f32_32x32x16_bf16 v[6:21], v[94:97], v[46:49], v[6:21]
	v_mfma_f32_32x32x16_bf16 v[6:21], v[98:101], v[196:199], v[6:21]
	s_nop 7
	s_cmpk_gt_i32 s11, 64
	s_cselect_b64 vcc, -1, 0
	v_max_f32_e32 v108, 0, v212
	v_max_f32_e32 v109, 0, v213
	v_pk_mul_f32 v[0:1], v[22:23], v[108:109]
	v_max_f32_e32 v210, 0, v214
	v_max_f32_e32 v211, 0, v215
	v_pk_fma_f32 v[0:1], v[24:25], v[210:211], v[0:1]
	v_max_f32_e32 v108, 0, v216
	v_max_f32_e32 v109, 0, v217
	v_pk_fma_f32 v[0:1], v[26:27], v[108:109], v[0:1]
	v_max_f32_e32 v210, 0, v218
	v_max_f32_e32 v211, 0, v219
	v_pk_fma_f32 v[0:1], v[28:29], v[210:211], v[0:1]
	v_max_f32_e32 v108, 0, v220
	v_max_f32_e32 v109, 0, v221
	v_pk_fma_f32 v[0:1], v[30:31], v[108:109], v[0:1]
	v_max_f32_e32 v210, 0, v222
	v_max_f32_e32 v211, 0, v223
	v_pk_fma_f32 v[0:1], v[32:33], v[210:211], v[0:1]
	v_max_f32_e32 v108, 0, v224
	v_max_f32_e32 v109, 0, v225
	v_pk_fma_f32 v[0:1], v[34:35], v[108:109], v[0:1]
	v_max_f32_e32 v210, 0, v226
	v_max_f32_e32 v211, 0, v227
	v_pk_fma_f32 v[0:1], v[36:37], v[210:211], v[0:1]
	v_add_f32_e32 v0, v0, v1
	v_ashrrev_i32_e32 v1, 31, v0
	v_or_b32_e32 v1, 0x80000000, v1
	v_xor_b32_e32 v0, v1, v0
	v_cndmask_b32_e32 v142, v123, v0, vcc
	s_add_i32 m0, s10, 0
	s_nop 0
	global_load_lds_dwordx4 v102, s[6:7]
	s_add_i32 m0, s10, 1024
	s_nop 0
	global_load_lds_dwordx4 v110, s[6:7]
	s_add_i32 m0, s10, 2048
	s_nop 0
	global_load_lds_dwordx4 v112, s[6:7]
	s_add_i32 m0, s10, 3072
	s_nop 0
	global_load_lds_dwordx4 v193, s[6:7]
	s_add_u32 s6, s6, 0x8000
	s_addc_u32 s7, s7, 0
	s_waitcnt vmcnt(15)
	ds_read_b128 v[38:41], v5 offset:43264
	ds_read_b128 v[42:45], v52 offset:43264
	ds_read_b128 v[46:49], v55 offset:43264
	ds_read_b128 v[196:199], v56 offset:43264
	s_waitcnt lgkmcnt(3)
	v_mfma_f32_32x32x16_bf16 v[212:227], v[70:73], v[38:41], 0
	s_waitcnt lgkmcnt(2)
	v_mfma_f32_32x32x16_bf16 v[212:227], v[74:77], v[42:45], v[212:227]
	s_waitcnt lgkmcnt(1)
	v_mfma_f32_32x32x16_bf16 v[212:227], v[78:81], v[46:49], v[212:227]
	s_waitcnt lgkmcnt(0)
	v_mfma_f32_32x32x16_bf16 v[212:227], v[82:85], v[196:199], v[212:227]
	s_cmpk_gt_i32 s11, 64
	s_cselect_b64 vcc, -1, 0
	v_max_f32_e32 v108, 0, v6
	v_max_f32_e32 v109, 0, v7
	v_pk_mul_f32 v[50:51], v[244:245], v[108:109]
	v_max_f32_e32 v210, 0, v8
	v_max_f32_e32 v211, 0, v9
	v_pk_fma_f32 v[50:51], v[246:247], v[210:211], v[50:51]
	v_max_f32_e32 v108, 0, v10
	v_max_f32_e32 v109, 0, v11
	v_pk_fma_f32 v[50:51], v[248:249], v[108:109], v[50:51]
	v_max_f32_e32 v210, 0, v12
	v_max_f32_e32 v211, 0, v13
	v_pk_fma_f32 v[50:51], v[250:251], v[210:211], v[50:51]
	v_max_f32_e32 v108, 0, v14
	v_max_f32_e32 v109, 0, v15
	v_pk_fma_f32 v[50:51], v[252:253], v[108:109], v[50:51]
	v_max_f32_e32 v210, 0, v16
	v_max_f32_e32 v211, 0, v17
	v_pk_fma_f32 v[50:51], v[254:255], v[210:211], v[50:51]
	v_max_f32_e32 v108, 0, v18
	v_max_f32_e32 v109, 0, v19
	v_pk_fma_f32 v[50:51], v[200:201], v[108:109], v[50:51]
	v_max_f32_e32 v210, 0, v20
	v_max_f32_e32 v211, 0, v21
	v_pk_fma_f32 v[50:51], v[202:203], v[210:211], v[50:51]
	v_add_f32_e32 v50, v50, v51
	v_ashrrev_i32_e32 v51, 31, v50
	v_or_b32_e32 v51, 0x80000000, v51
	v_xor_b32_e32 v50, v51, v50
	v_cndmask_b32_e32 v50, v123, v50, vcc
	global_store_dword v243, v50, s[8:9]
	v_mfma_f32_32x32x16_bf16 v[6:21], v[86:89], v[38:41], 0
	v_mfma_f32_32x32x16_bf16 v[6:21], v[90:93], v[42:45], v[6:21]
	v_mfma_f32_32x32x16_bf16 v[6:21], v[94:97], v[46:49], v[6:21]
	v_mfma_f32_32x32x16_bf16 v[6:21], v[98:101], v[196:199], v[6:21]
	s_cmpk_gt_i32 s11, 72
	s_cselect_b64 vcc, -1, 0
	v_max_f32_e32 v108, 0, v212
	v_max_f32_e32 v109, 0, v213
	v_pk_mul_f32 v[0:1], v[22:23], v[108:109]
	v_max_f32_e32 v210, 0, v214
	v_max_f32_e32 v211, 0, v215
	v_pk_fma_f32 v[0:1], v[24:25], v[210:211], v[0:1]
	v_max_f32_e32 v108, 0, v216
	v_max_f32_e32 v109, 0, v217
	v_pk_fma_f32 v[0:1], v[26:27], v[108:109], v[0:1]
	v_max_f32_e32 v210, 0, v218
	v_max_f32_e32 v211, 0, v219
	v_pk_fma_f32 v[0:1], v[28:29], v[210:211], v[0:1]
	v_max_f32_e32 v108, 0, v220
	v_max_f32_e32 v109, 0, v221
	v_pk_fma_f32 v[0:1], v[30:31], v[108:109], v[0:1]
	v_max_f32_e32 v210, 0, v222
	v_max_f32_e32 v211, 0, v223
	v_pk_fma_f32 v[0:1], v[32:33], v[210:211], v[0:1]
	v_max_f32_e32 v108, 0, v224
	v_max_f32_e32 v109, 0, v225
	v_pk_fma_f32 v[0:1], v[34:35], v[108:109], v[0:1]
	v_max_f32_e32 v210, 0, v226
	v_max_f32_e32 v211, 0, v227
	v_pk_fma_f32 v[0:1], v[36:37], v[210:211], v[0:1]
	v_add_f32_e32 v0, v0, v1
	v_ashrrev_i32_e32 v1, 31, v0
	v_or_b32_e32 v1, 0x80000000, v1
	v_xor_b32_e32 v0, v1, v0
	v_cndmask_b32_e32 v141, v123, v0, vcc
	s_add_i32 m0, s10, 32768
	s_nop 0
	global_load_lds_dwordx4 v102, s[6:7]
	s_add_i32 m0, s10, 33792
	s_nop 0
	global_load_lds_dwordx4 v110, s[6:7]
	s_add_i32 m0, s10, 34816
	s_nop 0
	global_load_lds_dwordx4 v112, s[6:7]
	s_add_i32 m0, s10, 35840
	s_nop 0
	global_load_lds_dwordx4 v193, s[6:7]
	s_add_u32 s6, s6, 0x8000
	s_addc_u32 s7, s7, 0
	s_waitcnt vmcnt(15)
	v_add_u32_e32 v228, 0x10000, v5
	ds_read_b128 v[38:41], v228 offset:10496
	v_add_u32_e32 v228, 0x10000, v52
	ds_read_b128 v[42:45], v228 offset:10496
	v_add_u32_e32 v228, 0x10000, v55
	ds_read_b128 v[46:49], v228 offset:10496
	v_add_u32_e32 v228, 0x10000, v56
	ds_read_b128 v[196:199], v228 offset:10496
	s_waitcnt lgkmcnt(3)
	v_mfma_f32_32x32x16_bf16 v[212:227], v[70:73], v[38:41], 0
	s_waitcnt lgkmcnt(2)
	v_mfma_f32_32x32x16_bf16 v[212:227], v[74:77], v[42:45], v[212:227]
	s_waitcnt lgkmcnt(1)
	v_mfma_f32_32x32x16_bf16 v[212:227], v[78:81], v[46:49], v[212:227]
	s_waitcnt lgkmcnt(0)
	v_mfma_f32_32x32x16_bf16 v[212:227], v[82:85], v[196:199], v[212:227]
	s_cmpk_gt_i32 s11, 72
	s_cselect_b64 vcc, -1, 0
	v_max_f32_e32 v108, 0, v6
	v_max_f32_e32 v109, 0, v7
	v_pk_mul_f32 v[50:51], v[244:245], v[108:109]
	v_max_f32_e32 v210, 0, v8
	v_max_f32_e32 v211, 0, v9
	v_pk_fma_f32 v[50:51], v[246:247], v[210:211], v[50:51]
	v_max_f32_e32 v108, 0, v10
	v_max_f32_e32 v109, 0, v11
	v_pk_fma_f32 v[50:51], v[248:249], v[108:109], v[50:51]
	v_max_f32_e32 v210, 0, v12
	v_max_f32_e32 v211, 0, v13
	v_pk_fma_f32 v[50:51], v[250:251], v[210:211], v[50:51]
	v_max_f32_e32 v108, 0, v14
	v_max_f32_e32 v109, 0, v15
	v_pk_fma_f32 v[50:51], v[252:253], v[108:109], v[50:51]
	v_max_f32_e32 v210, 0, v16
	v_max_f32_e32 v211, 0, v17
	v_pk_fma_f32 v[50:51], v[254:255], v[210:211], v[50:51]
	v_max_f32_e32 v108, 0, v18
	v_max_f32_e32 v109, 0, v19
	v_pk_fma_f32 v[50:51], v[200:201], v[108:109], v[50:51]
	v_max_f32_e32 v210, 0, v20
	v_max_f32_e32 v211, 0, v21
	v_pk_fma_f32 v[50:51], v[202:203], v[210:211], v[50:51]
	v_add_f32_e32 v50, v50, v51
	v_ashrrev_i32_e32 v51, 31, v50
	v_or_b32_e32 v51, 0x80000000, v51
	v_xor_b32_e32 v50, v51, v50
	v_cndmask_b32_e32 v50, v123, v50, vcc
	global_store_dword v243, v50, s[8:9] offset:2048
	s_add_u32 s8, s8, 0x1000
	s_addc_u32 s9, s9, 0
	v_mfma_f32_32x32x16_bf16 v[6:21], v[86:89], v[38:41], 0
	v_mfma_f32_32x32x16_bf16 v[6:21], v[90:93], v[42:45], v[6:21]
	v_mfma_f32_32x32x16_bf16 v[6:21], v[94:97], v[46:49], v[6:21]
	v_mfma_f32_32x32x16_bf16 v[6:21], v[98:101], v[196:199], v[6:21]
	s_cmpk_gt_i32 s11, 80
	s_cselect_b64 vcc, -1, 0
	v_max_f32_e32 v108, 0, v212
	v_max_f32_e32 v109, 0, v213
	v_pk_mul_f32 v[0:1], v[22:23], v[108:109]
	v_max_f32_e32 v210, 0, v214
	v_max_f32_e32 v211, 0, v215
	v_pk_fma_f32 v[0:1], v[24:25], v[210:211], v[0:1]
	v_max_f32_e32 v108, 0, v216
	v_max_f32_e32 v109, 0, v217
	v_pk_fma_f32 v[0:1], v[26:27], v[108:109], v[0:1]
	v_max_f32_e32 v210, 0, v218
	v_max_f32_e32 v211, 0, v219
	v_pk_fma_f32 v[0:1], v[28:29], v[210:211], v[0:1]
	v_max_f32_e32 v108, 0, v220
	v_max_f32_e32 v109, 0, v221
	v_pk_fma_f32 v[0:1], v[30:31], v[108:109], v[0:1]
	v_max_f32_e32 v210, 0, v222
	v_max_f32_e32 v211, 0, v223
	v_pk_fma_f32 v[0:1], v[32:33], v[210:211], v[0:1]
	v_max_f32_e32 v108, 0, v224
	v_max_f32_e32 v109, 0, v225
	v_pk_fma_f32 v[0:1], v[34:35], v[108:109], v[0:1]
	v_max_f32_e32 v210, 0, v226
	v_max_f32_e32 v211, 0, v227
	v_pk_fma_f32 v[0:1], v[36:37], v[210:211], v[0:1]
	v_add_f32_e32 v0, v0, v1
	v_ashrrev_i32_e32 v1, 31, v0
	v_or_b32_e32 v1, 0x80000000, v1
	v_xor_b32_e32 v0, v1, v0
	v_cndmask_b32_e32 v144, v123, v0, vcc
	s_add_i32 m0, s10, 65536
	s_nop 0
	global_load_lds_dwordx4 v102, s[6:7]
	s_add_i32 m0, s10, 66560
	s_nop 0
	global_load_lds_dwordx4 v110, s[6:7]
	s_add_i32 m0, s10, 67584
	s_nop 0
	global_load_lds_dwordx4 v112, s[6:7]
	s_add_i32 m0, s10, 68608
	s_nop 0
	global_load_lds_dwordx4 v193, s[6:7]
	s_add_u32 s6, s6, 0x8000
	s_addc_u32 s7, s7, 0
	s_waitcnt vmcnt(14)
	v_add_u32_e32 v228, 0x10000, v5
	ds_read_b128 v[38:41], v228 offset:43264
	v_add_u32_e32 v228, 0x10000, v52
	ds_read_b128 v[42:45], v228 offset:43264
	v_add_u32_e32 v228, 0x10000, v55
	ds_read_b128 v[46:49], v228 offset:43264
	v_add_u32_e32 v228, 0x10000, v56
	ds_read_b128 v[196:199], v228 offset:43264
	s_waitcnt lgkmcnt(3)
	v_mfma_f32_32x32x16_bf16 v[212:227], v[70:73], v[38:41], 0
	s_waitcnt lgkmcnt(2)
	v_mfma_f32_32x32x16_bf16 v[212:227], v[74:77], v[42:45], v[212:227]
	s_waitcnt lgkmcnt(1)
	v_mfma_f32_32x32x16_bf16 v[212:227], v[78:81], v[46:49], v[212:227]
	s_waitcnt lgkmcnt(0)
	v_mfma_f32_32x32x16_bf16 v[212:227], v[82:85], v[196:199], v[212:227]
	s_cmpk_gt_i32 s11, 80
	s_cselect_b64 vcc, -1, 0
	v_max_f32_e32 v108, 0, v6
	v_max_f32_e32 v109, 0, v7
	v_pk_mul_f32 v[50:51], v[244:245], v[108:109]
	v_max_f32_e32 v210, 0, v8
	v_max_f32_e32 v211, 0, v9
	v_pk_fma_f32 v[50:51], v[246:247], v[210:211], v[50:51]
	v_max_f32_e32 v108, 0, v10
	v_max_f32_e32 v109, 0, v11
	v_pk_fma_f32 v[50:51], v[248:249], v[108:109], v[50:51]
	v_max_f32_e32 v210, 0, v12
	v_max_f32_e32 v211, 0, v13
	v_pk_fma_f32 v[50:51], v[250:251], v[210:211], v[50:51]
	v_max_f32_e32 v108, 0, v14
	v_max_f32_e32 v109, 0, v15
	v_pk_fma_f32 v[50:51], v[252:253], v[108:109], v[50:51]
	v_max_f32_e32 v210, 0, v16
	v_max_f32_e32 v211, 0, v17
	v_pk_fma_f32 v[50:51], v[254:255], v[210:211], v[50:51]
	v_max_f32_e32 v108, 0, v18
	v_max_f32_e32 v109, 0, v19
	v_pk_fma_f32 v[50:51], v[200:201], v[108:109], v[50:51]
	v_max_f32_e32 v210, 0, v20
	v_max_f32_e32 v211, 0, v21
	v_pk_fma_f32 v[50:51], v[202:203], v[210:211], v[50:51]
	v_add_f32_e32 v50, v50, v51
	v_ashrrev_i32_e32 v51, 31, v50
	v_or_b32_e32 v51, 0x80000000, v51
	v_xor_b32_e32 v50, v51, v50
	v_cndmask_b32_e32 v50, v123, v50, vcc
	global_store_dword v243, v50, s[8:9]
	v_mfma_f32_32x32x16_bf16 v[6:21], v[86:89], v[38:41], 0
	v_mfma_f32_32x32x16_bf16 v[6:21], v[90:93], v[42:45], v[6:21]
	v_mfma_f32_32x32x16_bf16 v[6:21], v[94:97], v[46:49], v[6:21]
	v_mfma_f32_32x32x16_bf16 v[6:21], v[98:101], v[196:199], v[6:21]
	s_cmpk_gt_i32 s11, 88
	s_cselect_b64 vcc, -1, 0
	v_max_f32_e32 v108, 0, v212
	v_max_f32_e32 v109, 0, v213
	v_pk_mul_f32 v[0:1], v[22:23], v[108:109]
	v_max_f32_e32 v210, 0, v214
	v_max_f32_e32 v211, 0, v215
	v_pk_fma_f32 v[0:1], v[24:25], v[210:211], v[0:1]
	v_max_f32_e32 v108, 0, v216
	v_max_f32_e32 v109, 0, v217
	v_pk_fma_f32 v[0:1], v[26:27], v[108:109], v[0:1]
	v_max_f32_e32 v210, 0, v218
	v_max_f32_e32 v211, 0, v219
	v_pk_fma_f32 v[0:1], v[28:29], v[210:211], v[0:1]
	v_max_f32_e32 v108, 0, v220
	v_max_f32_e32 v109, 0, v221
	v_pk_fma_f32 v[0:1], v[30:31], v[108:109], v[0:1]
	v_max_f32_e32 v210, 0, v222
	v_max_f32_e32 v211, 0, v223
	v_pk_fma_f32 v[0:1], v[32:33], v[210:211], v[0:1]
	v_max_f32_e32 v108, 0, v224
	v_max_f32_e32 v109, 0, v225
	v_pk_fma_f32 v[0:1], v[34:35], v[108:109], v[0:1]
	v_max_f32_e32 v210, 0, v226
	v_max_f32_e32 v211, 0, v227
	v_pk_fma_f32 v[0:1], v[36:37], v[210:211], v[0:1]
	v_add_f32_e32 v0, v0, v1
	v_ashrrev_i32_e32 v1, 31, v0
	v_or_b32_e32 v1, 0x80000000, v1
	v_xor_b32_e32 v0, v1, v0
	v_cndmask_b32_e32 v143, v123, v0, vcc
	s_add_i32 m0, s10, 98304
	s_nop 0
	global_load_lds_dwordx4 v102, s[6:7]
	s_add_i32 m0, s10, 99328
	s_nop 0
	global_load_lds_dwordx4 v110, s[6:7]
	s_add_i32 m0, s10, 100352
	s_nop 0
	global_load_lds_dwordx4 v112, s[6:7]
	s_add_i32 m0, s10, 101376
	s_nop 0
	global_load_lds_dwordx4 v193, s[6:7]
	s_add_u32 s6, s6, 0x8000
	s_addc_u32 s7, s7, 0
	s_waitcnt vmcnt(15)
	ds_read_b128 v[38:41], v5 offset:10496
	ds_read_b128 v[42:45], v52 offset:10496
	ds_read_b128 v[46:49], v55 offset:10496
	ds_read_b128 v[196:199], v56 offset:10496
	s_waitcnt lgkmcnt(3)
	v_mfma_f32_32x32x16_bf16 v[212:227], v[70:73], v[38:41], 0
	s_waitcnt lgkmcnt(2)
	v_mfma_f32_32x32x16_bf16 v[212:227], v[74:77], v[42:45], v[212:227]
	s_waitcnt lgkmcnt(1)
	v_mfma_f32_32x32x16_bf16 v[212:227], v[78:81], v[46:49], v[212:227]
	s_waitcnt lgkmcnt(0)
	v_mfma_f32_32x32x16_bf16 v[212:227], v[82:85], v[196:199], v[212:227]
	s_cmpk_gt_i32 s11, 88
	s_cselect_b64 vcc, -1, 0
	v_max_f32_e32 v108, 0, v6
	v_max_f32_e32 v109, 0, v7
	v_pk_mul_f32 v[50:51], v[244:245], v[108:109]
	v_max_f32_e32 v210, 0, v8
	v_max_f32_e32 v211, 0, v9
	v_pk_fma_f32 v[50:51], v[246:247], v[210:211], v[50:51]
	v_max_f32_e32 v108, 0, v10
	v_max_f32_e32 v109, 0, v11
	v_pk_fma_f32 v[50:51], v[248:249], v[108:109], v[50:51]
	v_max_f32_e32 v210, 0, v12
	v_max_f32_e32 v211, 0, v13
	v_pk_fma_f32 v[50:51], v[250:251], v[210:211], v[50:51]
	v_max_f32_e32 v108, 0, v14
	v_max_f32_e32 v109, 0, v15
	v_pk_fma_f32 v[50:51], v[252:253], v[108:109], v[50:51]
	v_max_f32_e32 v210, 0, v16
	v_max_f32_e32 v211, 0, v17
	v_pk_fma_f32 v[50:51], v[254:255], v[210:211], v[50:51]
	v_max_f32_e32 v108, 0, v18
	v_max_f32_e32 v109, 0, v19
	v_pk_fma_f32 v[50:51], v[200:201], v[108:109], v[50:51]
	v_max_f32_e32 v210, 0, v20
	v_max_f32_e32 v211, 0, v21
	v_pk_fma_f32 v[50:51], v[202:203], v[210:211], v[50:51]
	v_add_f32_e32 v50, v50, v51
	v_ashrrev_i32_e32 v51, 31, v50
	v_or_b32_e32 v51, 0x80000000, v51
	v_xor_b32_e32 v50, v51, v50
	v_cndmask_b32_e32 v50, v123, v50, vcc
	global_store_dword v243, v50, s[8:9] offset:2048
	s_add_u32 s8, s8, 0x1000
	s_addc_u32 s9, s9, 0
	v_mfma_f32_32x32x16_bf16 v[6:21], v[86:89], v[38:41], 0
	v_mfma_f32_32x32x16_bf16 v[6:21], v[90:93], v[42:45], v[6:21]
	v_mfma_f32_32x32x16_bf16 v[6:21], v[94:97], v[46:49], v[6:21]
	v_mfma_f32_32x32x16_bf16 v[6:21], v[98:101], v[196:199], v[6:21]
	s_cmpk_gt_i32 s11, 96
	s_cselect_b64 vcc, -1, 0
	v_max_f32_e32 v108, 0, v212
	v_max_f32_e32 v109, 0, v213
	v_pk_mul_f32 v[0:1], v[22:23], v[108:109]
	v_max_f32_e32 v210, 0, v214
	v_max_f32_e32 v211, 0, v215
	v_pk_fma_f32 v[0:1], v[24:25], v[210:211], v[0:1]
	v_max_f32_e32 v108, 0, v216
	v_max_f32_e32 v109, 0, v217
	v_pk_fma_f32 v[0:1], v[26:27], v[108:109], v[0:1]
	v_max_f32_e32 v210, 0, v218
	v_max_f32_e32 v211, 0, v219
	v_pk_fma_f32 v[0:1], v[28:29], v[210:211], v[0:1]
	v_max_f32_e32 v108, 0, v220
	v_max_f32_e32 v109, 0, v221
	v_pk_fma_f32 v[0:1], v[30:31], v[108:109], v[0:1]
	v_max_f32_e32 v210, 0, v222
	v_max_f32_e32 v211, 0, v223
	v_pk_fma_f32 v[0:1], v[32:33], v[210:211], v[0:1]
	v_max_f32_e32 v108, 0, v224
	v_max_f32_e32 v109, 0, v225
	v_pk_fma_f32 v[0:1], v[34:35], v[108:109], v[0:1]
	v_max_f32_e32 v210, 0, v226
	v_max_f32_e32 v211, 0, v227
	v_pk_fma_f32 v[0:1], v[36:37], v[210:211], v[0:1]
	v_add_f32_e32 v0, v0, v1
	v_ashrrev_i32_e32 v1, 31, v0
	v_or_b32_e32 v1, 0x80000000, v1
	v_xor_b32_e32 v0, v1, v0
	v_cndmask_b32_e32 v146, v123, v0, vcc
	s_add_i32 m0, s10, 0
	s_nop 0
	global_load_lds_dwordx4 v102, s[6:7]
	s_add_i32 m0, s10, 1024
	s_nop 0
	global_load_lds_dwordx4 v110, s[6:7]
	s_add_i32 m0, s10, 2048
	s_nop 0
	global_load_lds_dwordx4 v112, s[6:7]
	s_add_i32 m0, s10, 3072
	s_nop 0
	global_load_lds_dwordx4 v193, s[6:7]
	s_add_u32 s6, s6, 0x8000
	s_addc_u32 s7, s7, 0
	s_waitcnt vmcnt(15)
	ds_read_b128 v[38:41], v5 offset:43264
	ds_read_b128 v[42:45], v52 offset:43264
	ds_read_b128 v[46:49], v55 offset:43264
	ds_read_b128 v[196:199], v56 offset:43264
	s_waitcnt lgkmcnt(3)
	v_mfma_f32_32x32x16_bf16 v[212:227], v[70:73], v[38:41], 0
	s_waitcnt lgkmcnt(2)
	v_mfma_f32_32x32x16_bf16 v[212:227], v[74:77], v[42:45], v[212:227]
	s_waitcnt lgkmcnt(1)
	v_mfma_f32_32x32x16_bf16 v[212:227], v[78:81], v[46:49], v[212:227]
	s_waitcnt lgkmcnt(0)
	v_mfma_f32_32x32x16_bf16 v[212:227], v[82:85], v[196:199], v[212:227]
	s_cmpk_gt_i32 s11, 96
	s_cselect_b64 vcc, -1, 0
	v_max_f32_e32 v108, 0, v6
	v_max_f32_e32 v109, 0, v7
	v_pk_mul_f32 v[50:51], v[244:245], v[108:109]
	v_max_f32_e32 v210, 0, v8
	v_max_f32_e32 v211, 0, v9
	v_pk_fma_f32 v[50:51], v[246:247], v[210:211], v[50:51]
	v_max_f32_e32 v108, 0, v10
	v_max_f32_e32 v109, 0, v11
	v_pk_fma_f32 v[50:51], v[248:249], v[108:109], v[50:51]
	v_max_f32_e32 v210, 0, v12
	v_max_f32_e32 v211, 0, v13
	v_pk_fma_f32 v[50:51], v[250:251], v[210:211], v[50:51]
	v_max_f32_e32 v108, 0, v14
	v_max_f32_e32 v109, 0, v15
	v_pk_fma_f32 v[50:51], v[252:253], v[108:109], v[50:51]
	v_max_f32_e32 v210, 0, v16
	v_max_f32_e32 v211, 0, v17
	v_pk_fma_f32 v[50:51], v[254:255], v[210:211], v[50:51]
	v_max_f32_e32 v108, 0, v18
	v_max_f32_e32 v109, 0, v19
	v_pk_fma_f32 v[50:51], v[200:201], v[108:109], v[50:51]
	v_max_f32_e32 v210, 0, v20
	v_max_f32_e32 v211, 0, v21
	v_pk_fma_f32 v[50:51], v[202:203], v[210:211], v[50:51]
	v_add_f32_e32 v50, v50, v51
	v_ashrrev_i32_e32 v51, 31, v50
	v_or_b32_e32 v51, 0x80000000, v51
	v_xor_b32_e32 v50, v51, v50
	v_cndmask_b32_e32 v50, v123, v50, vcc
	global_store_dword v243, v50, s[8:9]
	v_mfma_f32_32x32x16_bf16 v[6:21], v[86:89], v[38:41], 0
	v_mfma_f32_32x32x16_bf16 v[6:21], v[90:93], v[42:45], v[6:21]
	v_mfma_f32_32x32x16_bf16 v[6:21], v[94:97], v[46:49], v[6:21]
	v_mfma_f32_32x32x16_bf16 v[6:21], v[98:101], v[196:199], v[6:21]
	s_cmpk_gt_i32 s11, 104
	s_cselect_b64 vcc, -1, 0
	v_max_f32_e32 v108, 0, v212
	v_max_f32_e32 v109, 0, v213
	v_pk_mul_f32 v[0:1], v[22:23], v[108:109]
	v_max_f32_e32 v210, 0, v214
	v_max_f32_e32 v211, 0, v215
	v_pk_fma_f32 v[0:1], v[24:25], v[210:211], v[0:1]
	v_max_f32_e32 v108, 0, v216
	v_max_f32_e32 v109, 0, v217
	v_pk_fma_f32 v[0:1], v[26:27], v[108:109], v[0:1]
	v_max_f32_e32 v210, 0, v218
	v_max_f32_e32 v211, 0, v219
	v_pk_fma_f32 v[0:1], v[28:29], v[210:211], v[0:1]
	v_max_f32_e32 v108, 0, v220
	v_max_f32_e32 v109, 0, v221
	v_pk_fma_f32 v[0:1], v[30:31], v[108:109], v[0:1]
	v_max_f32_e32 v210, 0, v222
	v_max_f32_e32 v211, 0, v223
	v_pk_fma_f32 v[0:1], v[32:33], v[210:211], v[0:1]
	v_max_f32_e32 v108, 0, v224
	v_max_f32_e32 v109, 0, v225
	v_pk_fma_f32 v[0:1], v[34:35], v[108:109], v[0:1]
	v_max_f32_e32 v210, 0, v226
	v_max_f32_e32 v211, 0, v227
	v_pk_fma_f32 v[0:1], v[36:37], v[210:211], v[0:1]
	v_add_f32_e32 v0, v0, v1
	v_ashrrev_i32_e32 v1, 31, v0
	v_or_b32_e32 v1, 0x80000000, v1
	v_xor_b32_e32 v0, v1, v0
	v_cndmask_b32_e32 v145, v123, v0, vcc
	s_add_i32 m0, s10, 32768
	s_nop 0
	global_load_lds_dwordx4 v102, s[6:7]
	s_add_i32 m0, s10, 33792
	s_nop 0
	global_load_lds_dwordx4 v110, s[6:7]
	s_add_i32 m0, s10, 34816
	s_nop 0
	global_load_lds_dwordx4 v112, s[6:7]
	s_add_i32 m0, s10, 35840
	s_nop 0
	global_load_lds_dwordx4 v193, s[6:7]
	s_add_u32 s6, s6, 0x8000
	s_addc_u32 s7, s7, 0
	s_waitcnt vmcnt(15)
	v_add_u32_e32 v228, 0x10000, v5
	ds_read_b128 v[38:41], v228 offset:10496
	v_add_u32_e32 v228, 0x10000, v52
	ds_read_b128 v[42:45], v228 offset:10496
	v_add_u32_e32 v228, 0x10000, v55
	ds_read_b128 v[46:49], v228 offset:10496
	v_add_u32_e32 v228, 0x10000, v56
	ds_read_b128 v[196:199], v228 offset:10496
	s_waitcnt lgkmcnt(3)
	v_mfma_f32_32x32x16_bf16 v[212:227], v[70:73], v[38:41], 0
	s_waitcnt lgkmcnt(2)
	v_mfma_f32_32x32x16_bf16 v[212:227], v[74:77], v[42:45], v[212:227]
	s_waitcnt lgkmcnt(1)
	v_mfma_f32_32x32x16_bf16 v[212:227], v[78:81], v[46:49], v[212:227]
	s_waitcnt lgkmcnt(0)
	v_mfma_f32_32x32x16_bf16 v[212:227], v[82:85], v[196:199], v[212:227]
	s_cmpk_gt_i32 s11, 104
	s_cselect_b64 vcc, -1, 0
	v_max_f32_e32 v108, 0, v6
	v_max_f32_e32 v109, 0, v7
	v_pk_mul_f32 v[50:51], v[244:245], v[108:109]
	v_max_f32_e32 v210, 0, v8
	v_max_f32_e32 v211, 0, v9
	v_pk_fma_f32 v[50:51], v[246:247], v[210:211], v[50:51]
	v_max_f32_e32 v108, 0, v10
	v_max_f32_e32 v109, 0, v11
	v_pk_fma_f32 v[50:51], v[248:249], v[108:109], v[50:51]
	v_max_f32_e32 v210, 0, v12
	v_max_f32_e32 v211, 0, v13
	v_pk_fma_f32 v[50:51], v[250:251], v[210:211], v[50:51]
	v_max_f32_e32 v108, 0, v14
	v_max_f32_e32 v109, 0, v15
	v_pk_fma_f32 v[50:51], v[252:253], v[108:109], v[50:51]
	v_max_f32_e32 v210, 0, v16
	v_max_f32_e32 v211, 0, v17
	v_pk_fma_f32 v[50:51], v[254:255], v[210:211], v[50:51]
	v_max_f32_e32 v108, 0, v18
	v_max_f32_e32 v109, 0, v19
	v_pk_fma_f32 v[50:51], v[200:201], v[108:109], v[50:51]
	v_max_f32_e32 v210, 0, v20
	v_max_f32_e32 v211, 0, v21
	v_pk_fma_f32 v[50:51], v[202:203], v[210:211], v[50:51]
	v_add_f32_e32 v50, v50, v51
	v_ashrrev_i32_e32 v51, 31, v50
	v_or_b32_e32 v51, 0x80000000, v51
	v_xor_b32_e32 v50, v51, v50
	v_cndmask_b32_e32 v50, v123, v50, vcc
	global_store_dword v243, v50, s[8:9] offset:2048
	s_add_u32 s8, s8, 0x1000
	s_addc_u32 s9, s9, 0
	v_mfma_f32_32x32x16_bf16 v[6:21], v[86:89], v[38:41], 0
	v_mfma_f32_32x32x16_bf16 v[6:21], v[90:93], v[42:45], v[6:21]
	v_mfma_f32_32x32x16_bf16 v[6:21], v[94:97], v[46:49], v[6:21]
	v_mfma_f32_32x32x16_bf16 v[6:21], v[98:101], v[196:199], v[6:21]
	s_cmpk_gt_i32 s11, 112
	s_cselect_b64 vcc, -1, 0
	v_max_f32_e32 v108, 0, v212
	v_max_f32_e32 v109, 0, v213
	v_pk_mul_f32 v[0:1], v[22:23], v[108:109]
	v_max_f32_e32 v210, 0, v214
	v_max_f32_e32 v211, 0, v215
	v_pk_fma_f32 v[0:1], v[24:25], v[210:211], v[0:1]
	v_max_f32_e32 v108, 0, v216
	v_max_f32_e32 v109, 0, v217
	v_pk_fma_f32 v[0:1], v[26:27], v[108:109], v[0:1]
	v_max_f32_e32 v210, 0, v218
	v_max_f32_e32 v211, 0, v219
	v_pk_fma_f32 v[0:1], v[28:29], v[210:211], v[0:1]
	v_max_f32_e32 v108, 0, v220
	v_max_f32_e32 v109, 0, v221
	v_pk_fma_f32 v[0:1], v[30:31], v[108:109], v[0:1]
	v_max_f32_e32 v210, 0, v222
	v_max_f32_e32 v211, 0, v223
	v_pk_fma_f32 v[0:1], v[32:33], v[210:211], v[0:1]
	v_max_f32_e32 v108, 0, v224
	v_max_f32_e32 v109, 0, v225
	v_pk_fma_f32 v[0:1], v[34:35], v[108:109], v[0:1]
	v_max_f32_e32 v210, 0, v226
	v_max_f32_e32 v211, 0, v227
	v_pk_fma_f32 v[0:1], v[36:37], v[210:211], v[0:1]
	v_add_f32_e32 v0, v0, v1
	v_ashrrev_i32_e32 v1, 31, v0
	v_or_b32_e32 v1, 0x80000000, v1
	v_xor_b32_e32 v0, v1, v0
	v_cndmask_b32_e32 v147, v123, v0, vcc
	s_add_i32 m0, s10, 65536
	s_nop 0
	global_load_lds_dwordx4 v102, s[6:7]
	s_add_i32 m0, s10, 66560
	s_nop 0
	global_load_lds_dwordx4 v110, s[6:7]
	s_add_i32 m0, s10, 67584
	s_nop 0
	global_load_lds_dwordx4 v112, s[6:7]
	s_add_i32 m0, s10, 68608
	s_nop 0
	global_load_lds_dwordx4 v193, s[6:7]
	s_add_u32 s6, s6, 0x8000
	s_addc_u32 s7, s7, 0
	s_waitcnt vmcnt(15)
	v_add_u32_e32 v228, 0x10000, v5
	ds_read_b128 v[38:41], v228 offset:43264
	v_add_u32_e32 v228, 0x10000, v52
	ds_read_b128 v[42:45], v228 offset:43264
	v_add_u32_e32 v228, 0x10000, v55
	ds_read_b128 v[46:49], v228 offset:43264
	v_add_u32_e32 v228, 0x10000, v56
	ds_read_b128 v[196:199], v228 offset:43264
	s_waitcnt lgkmcnt(3)
	v_mfma_f32_32x32x16_bf16 v[212:227], v[70:73], v[38:41], 0
	s_waitcnt lgkmcnt(2)
	v_mfma_f32_32x32x16_bf16 v[212:227], v[74:77], v[42:45], v[212:227]
	s_waitcnt lgkmcnt(1)
	v_mfma_f32_32x32x16_bf16 v[212:227], v[78:81], v[46:49], v[212:227]
	s_waitcnt lgkmcnt(0)
	v_mfma_f32_32x32x16_bf16 v[212:227], v[82:85], v[196:199], v[212:227]
	s_cmpk_gt_i32 s11, 112
	s_cselect_b64 vcc, -1, 0
	v_max_f32_e32 v108, 0, v6
	v_max_f32_e32 v109, 0, v7
	v_pk_mul_f32 v[50:51], v[244:245], v[108:109]
	v_max_f32_e32 v210, 0, v8
	v_max_f32_e32 v211, 0, v9
	v_pk_fma_f32 v[50:51], v[246:247], v[210:211], v[50:51]
	v_max_f32_e32 v108, 0, v10
	v_max_f32_e32 v109, 0, v11
	v_pk_fma_f32 v[50:51], v[248:249], v[108:109], v[50:51]
	v_max_f32_e32 v210, 0, v12
	v_max_f32_e32 v211, 0, v13
	v_pk_fma_f32 v[50:51], v[250:251], v[210:211], v[50:51]
	v_max_f32_e32 v108, 0, v14
	v_max_f32_e32 v109, 0, v15
	v_pk_fma_f32 v[50:51], v[252:253], v[108:109], v[50:51]
	v_max_f32_e32 v210, 0, v16
	v_max_f32_e32 v211, 0, v17
	v_pk_fma_f32 v[50:51], v[254:255], v[210:211], v[50:51]
	v_max_f32_e32 v108, 0, v18
	v_max_f32_e32 v109, 0, v19
	v_pk_fma_f32 v[50:51], v[200:201], v[108:109], v[50:51]
	v_max_f32_e32 v210, 0, v20
	v_max_f32_e32 v211, 0, v21
	v_pk_fma_f32 v[50:51], v[202:203], v[210:211], v[50:51]
	v_add_f32_e32 v50, v50, v51
	v_ashrrev_i32_e32 v51, 31, v50
	v_or_b32_e32 v51, 0x80000000, v51
	v_xor_b32_e32 v50, v51, v50
	v_cndmask_b32_e32 v50, v123, v50, vcc
	global_store_dword v243, v50, s[8:9]
	v_mfma_f32_32x32x16_bf16 v[6:21], v[86:89], v[38:41], 0
	v_mfma_f32_32x32x16_bf16 v[6:21], v[90:93], v[42:45], v[6:21]
	v_mfma_f32_32x32x16_bf16 v[6:21], v[94:97], v[46:49], v[6:21]
	v_mfma_f32_32x32x16_bf16 v[6:21], v[98:101], v[196:199], v[6:21]
	s_cmpk_gt_i32 s11, 120
	s_cselect_b64 vcc, -1, 0
	v_max_f32_e32 v108, 0, v212
	v_max_f32_e32 v109, 0, v213
	v_pk_mul_f32 v[0:1], v[22:23], v[108:109]
	v_max_f32_e32 v210, 0, v214
	v_max_f32_e32 v211, 0, v215
	v_pk_fma_f32 v[0:1], v[24:25], v[210:211], v[0:1]
	v_max_f32_e32 v108, 0, v216
	v_max_f32_e32 v109, 0, v217
	v_pk_fma_f32 v[0:1], v[26:27], v[108:109], v[0:1]
	v_max_f32_e32 v210, 0, v218
	v_max_f32_e32 v211, 0, v219
	v_pk_fma_f32 v[0:1], v[28:29], v[210:211], v[0:1]
	v_max_f32_e32 v108, 0, v220
	v_max_f32_e32 v109, 0, v221
	v_pk_fma_f32 v[0:1], v[30:31], v[108:109], v[0:1]
	v_max_f32_e32 v210, 0, v222
	v_max_f32_e32 v211, 0, v223
	v_pk_fma_f32 v[0:1], v[32:33], v[210:211], v[0:1]
	v_max_f32_e32 v108, 0, v224
	v_max_f32_e32 v109, 0, v225
	v_pk_fma_f32 v[0:1], v[34:35], v[108:109], v[0:1]
	v_max_f32_e32 v210, 0, v226
	v_max_f32_e32 v211, 0, v227
	v_pk_fma_f32 v[0:1], v[36:37], v[210:211], v[0:1]
	v_add_f32_e32 v0, v0, v1
	v_ashrrev_i32_e32 v1, 31, v0
	v_or_b32_e32 v1, 0x80000000, v1
	v_xor_b32_e32 v0, v1, v0
	v_cndmask_b32_e32 v136, v123, v0, vcc
	v_max_f32_e32 v108, 0, v6
	v_max_f32_e32 v109, 0, v7
	v_pk_mul_f32 v[50:51], v[244:245], v[108:109]
	v_max_f32_e32 v210, 0, v8
	v_max_f32_e32 v211, 0, v9
	v_pk_fma_f32 v[50:51], v[246:247], v[210:211], v[50:51]
	v_max_f32_e32 v108, 0, v10
	v_max_f32_e32 v109, 0, v11
	v_pk_fma_f32 v[50:51], v[248:249], v[108:109], v[50:51]
	v_max_f32_e32 v210, 0, v12
	v_max_f32_e32 v211, 0, v13
	v_pk_fma_f32 v[50:51], v[250:251], v[210:211], v[50:51]
	v_max_f32_e32 v108, 0, v14
	v_max_f32_e32 v109, 0, v15
	v_pk_fma_f32 v[50:51], v[252:253], v[108:109], v[50:51]
	v_max_f32_e32 v210, 0, v16
	v_max_f32_e32 v211, 0, v17
	v_pk_fma_f32 v[50:51], v[254:255], v[210:211], v[50:51]
	v_max_f32_e32 v108, 0, v18
	v_max_f32_e32 v109, 0, v19
	v_pk_fma_f32 v[50:51], v[200:201], v[108:109], v[50:51]
	v_max_f32_e32 v210, 0, v20
	v_max_f32_e32 v211, 0, v21
	v_pk_fma_f32 v[50:51], v[202:203], v[210:211], v[50:51]
	v_add_f32_e32 v50, v50, v51
	v_ashrrev_i32_e32 v51, 31, v50
	v_or_b32_e32 v51, 0x80000000, v51
	v_xor_b32_e32 v50, v51, v50
	v_cndmask_b32_e32 v50, v123, v50, vcc
	global_store_dword v243, v50, s[8:9] offset:2048
	s_add_u32 s8, s8, 0x1000
	s_addc_u32 s9, s9, 0
	s_cmpk_gt_i32 s81, 16
	s_cbranch_scc0 .Lix_fill_2
	s_add_i32 m0, s10, 98304
	s_nop 0
	global_load_lds_dwordx4 v102, s[6:7]
	s_add_i32 m0, s10, 99328
	s_nop 0
	global_load_lds_dwordx4 v110, s[6:7]
	s_add_i32 m0, s10, 100352
	s_nop 0
	global_load_lds_dwordx4 v112, s[6:7]
	s_add_i32 m0, s10, 101376
	s_nop 0
	global_load_lds_dwordx4 v193, s[6:7]
	s_add_u32 s6, s6, 0x8000
	s_addc_u32 s7, s7, 0
	s_waitcnt vmcnt(16)
	ds_read_b128 v[38:41], v5 offset:10496
	ds_read_b128 v[42:45], v52 offset:10496
	ds_read_b128 v[46:49], v55 offset:10496
	ds_read_b128 v[196:199], v56 offset:10496
	s_waitcnt lgkmcnt(3)
	v_mfma_f32_32x32x16_bf16 v[212:227], v[70:73], v[38:41], 0
	s_waitcnt lgkmcnt(2)
	v_mfma_f32_32x32x16_bf16 v[212:227], v[74:77], v[42:45], v[212:227]
	s_waitcnt lgkmcnt(1)
	v_mfma_f32_32x32x16_bf16 v[212:227], v[78:81], v[46:49], v[212:227]
	s_waitcnt lgkmcnt(0)
	v_mfma_f32_32x32x16_bf16 v[212:227], v[82:85], v[196:199], v[212:227]
	v_mfma_f32_32x32x16_bf16 v[6:21], v[86:89], v[38:41], 0
	v_mfma_f32_32x32x16_bf16 v[6:21], v[90:93], v[42:45], v[6:21]
	v_mfma_f32_32x32x16_bf16 v[6:21], v[94:97], v[46:49], v[6:21]
	v_mfma_f32_32x32x16_bf16 v[6:21], v[98:101], v[196:199], v[6:21]
	s_nop 7
	s_cmpk_gt_i32 s11, 128
	s_cselect_b64 vcc, -1, 0
	v_max_f32_e32 v108, 0, v212
	v_max_f32_e32 v109, 0, v213
	v_pk_mul_f32 v[0:1], v[22:23], v[108:109]
	v_max_f32_e32 v210, 0, v214
	v_max_f32_e32 v211, 0, v215
	v_pk_fma_f32 v[0:1], v[24:25], v[210:211], v[0:1]
	v_max_f32_e32 v108, 0, v216
	v_max_f32_e32 v109, 0, v217
	v_pk_fma_f32 v[0:1], v[26:27], v[108:109], v[0:1]
	v_max_f32_e32 v210, 0, v218
	v_max_f32_e32 v211, 0, v219
	v_pk_fma_f32 v[0:1], v[28:29], v[210:211], v[0:1]
	v_max_f32_e32 v108, 0, v220
	v_max_f32_e32 v109, 0, v221
	v_pk_fma_f32 v[0:1], v[30:31], v[108:109], v[0:1]
	v_max_f32_e32 v210, 0, v222
	v_max_f32_e32 v211, 0, v223
	v_pk_fma_f32 v[0:1], v[32:33], v[210:211], v[0:1]
	v_max_f32_e32 v108, 0, v224
	v_max_f32_e32 v109, 0, v225
	v_pk_fma_f32 v[0:1], v[34:35], v[108:109], v[0:1]
	v_max_f32_e32 v210, 0, v226
	v_max_f32_e32 v211, 0, v227
	v_pk_fma_f32 v[0:1], v[36:37], v[210:211], v[0:1]
	v_add_f32_e32 v0, v0, v1
	v_ashrrev_i32_e32 v1, 31, v0
	v_or_b32_e32 v1, 0x80000000, v1
	v_xor_b32_e32 v0, v1, v0
	v_cndmask_b32_e32 v149, v123, v0, vcc
	s_add_i32 m0, s10, 0
	s_nop 0
	global_load_lds_dwordx4 v102, s[6:7]
	s_add_i32 m0, s10, 1024
	s_nop 0
	global_load_lds_dwordx4 v110, s[6:7]
	s_add_i32 m0, s10, 2048
	s_nop 0
	global_load_lds_dwordx4 v112, s[6:7]
	s_add_i32 m0, s10, 3072
	s_nop 0
	global_load_lds_dwordx4 v193, s[6:7]
	s_add_u32 s6, s6, 0x8000
	s_addc_u32 s7, s7, 0
	s_waitcnt vmcnt(15)
	ds_read_b128 v[38:41], v5 offset:43264
	ds_read_b128 v[42:45], v52 offset:43264
	ds_read_b128 v[46:49], v55 offset:43264
	ds_read_b128 v[196:199], v56 offset:43264
	s_waitcnt lgkmcnt(3)
	v_mfma_f32_32x32x16_bf16 v[212:227], v[70:73], v[38:41], 0
	s_waitcnt lgkmcnt(2)
	v_mfma_f32_32x32x16_bf16 v[212:227], v[74:77], v[42:45], v[212:227]
	s_waitcnt lgkmcnt(1)
	v_mfma_f32_32x32x16_bf16 v[212:227], v[78:81], v[46:49], v[212:227]
	s_waitcnt lgkmcnt(0)
	v_mfma_f32_32x32x16_bf16 v[212:227], v[82:85], v[196:199], v[212:227]
	s_cmpk_gt_i32 s11, 128
	s_cselect_b64 vcc, -1, 0
	v_max_f32_e32 v108, 0, v6
	v_max_f32_e32 v109, 0, v7
	v_pk_mul_f32 v[50:51], v[244:245], v[108:109]
	v_max_f32_e32 v210, 0, v8
	v_max_f32_e32 v211, 0, v9
	v_pk_fma_f32 v[50:51], v[246:247], v[210:211], v[50:51]
	v_max_f32_e32 v108, 0, v10
	v_max_f32_e32 v109, 0, v11
	v_pk_fma_f32 v[50:51], v[248:249], v[108:109], v[50:51]
	v_max_f32_e32 v210, 0, v12
	v_max_f32_e32 v211, 0, v13
	v_pk_fma_f32 v[50:51], v[250:251], v[210:211], v[50:51]
	v_max_f32_e32 v108, 0, v14
	v_max_f32_e32 v109, 0, v15
	v_pk_fma_f32 v[50:51], v[252:253], v[108:109], v[50:51]
	v_max_f32_e32 v210, 0, v16
	v_max_f32_e32 v211, 0, v17
	v_pk_fma_f32 v[50:51], v[254:255], v[210:211], v[50:51]
	v_max_f32_e32 v108, 0, v18
	v_max_f32_e32 v109, 0, v19
	v_pk_fma_f32 v[50:51], v[200:201], v[108:109], v[50:51]
	v_max_f32_e32 v210, 0, v20
	v_max_f32_e32 v211, 0, v21
	v_pk_fma_f32 v[50:51], v[202:203], v[210:211], v[50:51]
	v_add_f32_e32 v50, v50, v51
	v_ashrrev_i32_e32 v51, 31, v50
	v_or_b32_e32 v51, 0x80000000, v51
	v_xor_b32_e32 v50, v51, v50
	v_cndmask_b32_e32 v50, v123, v50, vcc
	global_store_dword v243, v50, s[8:9]
	v_mfma_f32_32x32x16_bf16 v[6:21], v[86:89], v[38:41], 0
	v_mfma_f32_32x32x16_bf16 v[6:21], v[90:93], v[42:45], v[6:21]
	v_mfma_f32_32x32x16_bf16 v[6:21], v[94:97], v[46:49], v[6:21]
	v_mfma_f32_32x32x16_bf16 v[6:21], v[98:101], v[196:199], v[6:21]
	s_cmpk_gt_i32 s11, 136
	s_cselect_b64 vcc, -1, 0
	v_max_f32_e32 v108, 0, v212
	v_max_f32_e32 v109, 0, v213
	v_pk_mul_f32 v[0:1], v[22:23], v[108:109]
	v_max_f32_e32 v210, 0, v214
	v_max_f32_e32 v211, 0, v215
	v_pk_fma_f32 v[0:1], v[24:25], v[210:211], v[0:1]
	v_max_f32_e32 v108, 0, v216
	v_max_f32_e32 v109, 0, v217
	v_pk_fma_f32 v[0:1], v[26:27], v[108:109], v[0:1]
	v_max_f32_e32 v210, 0, v218
	v_max_f32_e32 v211, 0, v219
	v_pk_fma_f32 v[0:1], v[28:29], v[210:211], v[0:1]
	v_max_f32_e32 v108, 0, v220
	v_max_f32_e32 v109, 0, v221
	v_pk_fma_f32 v[0:1], v[30:31], v[108:109], v[0:1]
	v_max_f32_e32 v210, 0, v222
	v_max_f32_e32 v211, 0, v223
	v_pk_fma_f32 v[0:1], v[32:33], v[210:211], v[0:1]
	v_max_f32_e32 v108, 0, v224
	v_max_f32_e32 v109, 0, v225
	v_pk_fma_f32 v[0:1], v[34:35], v[108:109], v[0:1]
	v_max_f32_e32 v210, 0, v226
	v_max_f32_e32 v211, 0, v227
	v_pk_fma_f32 v[0:1], v[36:37], v[210:211], v[0:1]
	v_add_f32_e32 v0, v0, v1
	v_ashrrev_i32_e32 v1, 31, v0
	v_or_b32_e32 v1, 0x80000000, v1
	v_xor_b32_e32 v0, v1, v0
	v_cndmask_b32_e32 v148, v123, v0, vcc
	s_add_i32 m0, s10, 32768
	s_nop 0
	global_load_lds_dwordx4 v102, s[6:7]
	s_add_i32 m0, s10, 33792
	s_nop 0
	global_load_lds_dwordx4 v110, s[6:7]
	s_add_i32 m0, s10, 34816
	s_nop 0
	global_load_lds_dwordx4 v112, s[6:7]
	s_add_i32 m0, s10, 35840
	s_nop 0
	global_load_lds_dwordx4 v193, s[6:7]
	s_add_u32 s6, s6, 0x8000
	s_addc_u32 s7, s7, 0
	s_waitcnt vmcnt(15)
	v_add_u32_e32 v228, 0x10000, v5
	ds_read_b128 v[38:41], v228 offset:10496
	v_add_u32_e32 v228, 0x10000, v52
	ds_read_b128 v[42:45], v228 offset:10496
	v_add_u32_e32 v228, 0x10000, v55
	ds_read_b128 v[46:49], v228 offset:10496
	v_add_u32_e32 v228, 0x10000, v56
	ds_read_b128 v[196:199], v228 offset:10496
	s_waitcnt lgkmcnt(3)
	v_mfma_f32_32x32x16_bf16 v[212:227], v[70:73], v[38:41], 0
	s_waitcnt lgkmcnt(2)
	v_mfma_f32_32x32x16_bf16 v[212:227], v[74:77], v[42:45], v[212:227]
	s_waitcnt lgkmcnt(1)
	v_mfma_f32_32x32x16_bf16 v[212:227], v[78:81], v[46:49], v[212:227]
	s_waitcnt lgkmcnt(0)
	v_mfma_f32_32x32x16_bf16 v[212:227], v[82:85], v[196:199], v[212:227]
	s_cmpk_gt_i32 s11, 136
	s_cselect_b64 vcc, -1, 0
	v_max_f32_e32 v108, 0, v6
	v_max_f32_e32 v109, 0, v7
	v_pk_mul_f32 v[50:51], v[244:245], v[108:109]
	v_max_f32_e32 v210, 0, v8
	v_max_f32_e32 v211, 0, v9
	v_pk_fma_f32 v[50:51], v[246:247], v[210:211], v[50:51]
	v_max_f32_e32 v108, 0, v10
	v_max_f32_e32 v109, 0, v11
	v_pk_fma_f32 v[50:51], v[248:249], v[108:109], v[50:51]
	v_max_f32_e32 v210, 0, v12
	v_max_f32_e32 v211, 0, v13
	v_pk_fma_f32 v[50:51], v[250:251], v[210:211], v[50:51]
	v_max_f32_e32 v108, 0, v14
	v_max_f32_e32 v109, 0, v15
	v_pk_fma_f32 v[50:51], v[252:253], v[108:109], v[50:51]
	v_max_f32_e32 v210, 0, v16
	v_max_f32_e32 v211, 0, v17
	v_pk_fma_f32 v[50:51], v[254:255], v[210:211], v[50:51]
	v_max_f32_e32 v108, 0, v18
	v_max_f32_e32 v109, 0, v19
	v_pk_fma_f32 v[50:51], v[200:201], v[108:109], v[50:51]
	v_max_f32_e32 v210, 0, v20
	v_max_f32_e32 v211, 0, v21
	v_pk_fma_f32 v[50:51], v[202:203], v[210:211], v[50:51]
	v_add_f32_e32 v50, v50, v51
	v_ashrrev_i32_e32 v51, 31, v50
	v_or_b32_e32 v51, 0x80000000, v51
	v_xor_b32_e32 v50, v51, v50
	v_cndmask_b32_e32 v50, v123, v50, vcc
	global_store_dword v243, v50, s[8:9] offset:2048
	s_add_u32 s8, s8, 0x1000
	s_addc_u32 s9, s9, 0
	v_mfma_f32_32x32x16_bf16 v[6:21], v[86:89], v[38:41], 0
	v_mfma_f32_32x32x16_bf16 v[6:21], v[90:93], v[42:45], v[6:21]
	v_mfma_f32_32x32x16_bf16 v[6:21], v[94:97], v[46:49], v[6:21]
	v_mfma_f32_32x32x16_bf16 v[6:21], v[98:101], v[196:199], v[6:21]
	s_cmpk_gt_i32 s11, 144
	s_cselect_b64 vcc, -1, 0
	v_max_f32_e32 v108, 0, v212
	v_max_f32_e32 v109, 0, v213
	v_pk_mul_f32 v[0:1], v[22:23], v[108:109]
	v_max_f32_e32 v210, 0, v214
	v_max_f32_e32 v211, 0, v215
	v_pk_fma_f32 v[0:1], v[24:25], v[210:211], v[0:1]
	v_max_f32_e32 v108, 0, v216
	v_max_f32_e32 v109, 0, v217
	v_pk_fma_f32 v[0:1], v[26:27], v[108:109], v[0:1]
	v_max_f32_e32 v210, 0, v218
	v_max_f32_e32 v211, 0, v219
	v_pk_fma_f32 v[0:1], v[28:29], v[210:211], v[0:1]
	v_max_f32_e32 v108, 0, v220
	v_max_f32_e32 v109, 0, v221
	v_pk_fma_f32 v[0:1], v[30:31], v[108:109], v[0:1]
	v_max_f32_e32 v210, 0, v222
	v_max_f32_e32 v211, 0, v223
	v_pk_fma_f32 v[0:1], v[32:33], v[210:211], v[0:1]
	v_max_f32_e32 v108, 0, v224
	v_max_f32_e32 v109, 0, v225
	v_pk_fma_f32 v[0:1], v[34:35], v[108:109], v[0:1]
	v_max_f32_e32 v210, 0, v226
	v_max_f32_e32 v211, 0, v227
	v_pk_fma_f32 v[0:1], v[36:37], v[210:211], v[0:1]
	v_add_f32_e32 v0, v0, v1
	v_ashrrev_i32_e32 v1, 31, v0
	v_or_b32_e32 v1, 0x80000000, v1
	v_xor_b32_e32 v0, v1, v0
	v_cndmask_b32_e32 v151, v123, v0, vcc
	s_add_i32 m0, s10, 65536
	s_nop 0
	global_load_lds_dwordx4 v102, s[6:7]
	s_add_i32 m0, s10, 66560
	s_nop 0
	global_load_lds_dwordx4 v110, s[6:7]
	s_add_i32 m0, s10, 67584
	s_nop 0
	global_load_lds_dwordx4 v112, s[6:7]
	s_add_i32 m0, s10, 68608
	s_nop 0
	global_load_lds_dwordx4 v193, s[6:7]
	s_add_u32 s6, s6, 0x8000
	s_addc_u32 s7, s7, 0
	s_waitcnt vmcnt(14)
	v_add_u32_e32 v228, 0x10000, v5
	ds_read_b128 v[38:41], v228 offset:43264
	v_add_u32_e32 v228, 0x10000, v52
	ds_read_b128 v[42:45], v228 offset:43264
	v_add_u32_e32 v228, 0x10000, v55
	ds_read_b128 v[46:49], v228 offset:43264
	v_add_u32_e32 v228, 0x10000, v56
	ds_read_b128 v[196:199], v228 offset:43264
	s_waitcnt lgkmcnt(3)
	v_mfma_f32_32x32x16_bf16 v[212:227], v[70:73], v[38:41], 0
	s_waitcnt lgkmcnt(2)
	v_mfma_f32_32x32x16_bf16 v[212:227], v[74:77], v[42:45], v[212:227]
	s_waitcnt lgkmcnt(1)
	v_mfma_f32_32x32x16_bf16 v[212:227], v[78:81], v[46:49], v[212:227]
	s_waitcnt lgkmcnt(0)
	v_mfma_f32_32x32x16_bf16 v[212:227], v[82:85], v[196:199], v[212:227]
	s_cmpk_gt_i32 s11, 144
	s_cselect_b64 vcc, -1, 0
	v_max_f32_e32 v108, 0, v6
	v_max_f32_e32 v109, 0, v7
	v_pk_mul_f32 v[50:51], v[244:245], v[108:109]
	v_max_f32_e32 v210, 0, v8
	v_max_f32_e32 v211, 0, v9
	v_pk_fma_f32 v[50:51], v[246:247], v[210:211], v[50:51]
	v_max_f32_e32 v108, 0, v10
	v_max_f32_e32 v109, 0, v11
	v_pk_fma_f32 v[50:51], v[248:249], v[108:109], v[50:51]
	v_max_f32_e32 v210, 0, v12
	v_max_f32_e32 v211, 0, v13
	v_pk_fma_f32 v[50:51], v[250:251], v[210:211], v[50:51]
	v_max_f32_e32 v108, 0, v14
	v_max_f32_e32 v109, 0, v15
	v_pk_fma_f32 v[50:51], v[252:253], v[108:109], v[50:51]
	v_max_f32_e32 v210, 0, v16
	v_max_f32_e32 v211, 0, v17
	v_pk_fma_f32 v[50:51], v[254:255], v[210:211], v[50:51]
	v_max_f32_e32 v108, 0, v18
	v_max_f32_e32 v109, 0, v19
	v_pk_fma_f32 v[50:51], v[200:201], v[108:109], v[50:51]
	v_max_f32_e32 v210, 0, v20
	v_max_f32_e32 v211, 0, v21
	v_pk_fma_f32 v[50:51], v[202:203], v[210:211], v[50:51]
	v_add_f32_e32 v50, v50, v51
	v_ashrrev_i32_e32 v51, 31, v50
	v_or_b32_e32 v51, 0x80000000, v51
	v_xor_b32_e32 v50, v51, v50
	v_cndmask_b32_e32 v50, v123, v50, vcc
	global_store_dword v243, v50, s[8:9]
	v_mfma_f32_32x32x16_bf16 v[6:21], v[86:89], v[38:41], 0
	v_mfma_f32_32x32x16_bf16 v[6:21], v[90:93], v[42:45], v[6:21]
	v_mfma_f32_32x32x16_bf16 v[6:21], v[94:97], v[46:49], v[6:21]
	v_mfma_f32_32x32x16_bf16 v[6:21], v[98:101], v[196:199], v[6:21]
	s_cmpk_gt_i32 s11, 152
	s_cselect_b64 vcc, -1, 0
	v_max_f32_e32 v108, 0, v212
	v_max_f32_e32 v109, 0, v213
	v_pk_mul_f32 v[0:1], v[22:23], v[108:109]
	v_max_f32_e32 v210, 0, v214
	v_max_f32_e32 v211, 0, v215
	v_pk_fma_f32 v[0:1], v[24:25], v[210:211], v[0:1]
	v_max_f32_e32 v108, 0, v216
	v_max_f32_e32 v109, 0, v217
	v_pk_fma_f32 v[0:1], v[26:27], v[108:109], v[0:1]
	v_max_f32_e32 v210, 0, v218
	v_max_f32_e32 v211, 0, v219
	v_pk_fma_f32 v[0:1], v[28:29], v[210:211], v[0:1]
	v_max_f32_e32 v108, 0, v220
	v_max_f32_e32 v109, 0, v221
	v_pk_fma_f32 v[0:1], v[30:31], v[108:109], v[0:1]
	v_max_f32_e32 v210, 0, v222
	v_max_f32_e32 v211, 0, v223
	v_pk_fma_f32 v[0:1], v[32:33], v[210:211], v[0:1]
	v_max_f32_e32 v108, 0, v224
	v_max_f32_e32 v109, 0, v225
	v_pk_fma_f32 v[0:1], v[34:35], v[108:109], v[0:1]
	v_max_f32_e32 v210, 0, v226
	v_max_f32_e32 v211, 0, v227
	v_pk_fma_f32 v[0:1], v[36:37], v[210:211], v[0:1]
	v_add_f32_e32 v0, v0, v1
	v_ashrrev_i32_e32 v1, 31, v0
	v_or_b32_e32 v1, 0x80000000, v1
	v_xor_b32_e32 v0, v1, v0
	v_cndmask_b32_e32 v150, v123, v0, vcc
	s_add_i32 m0, s10, 98304
	s_nop 0
	global_load_lds_dwordx4 v102, s[6:7]
	s_add_i32 m0, s10, 99328
	s_nop 0
	global_load_lds_dwordx4 v110, s[6:7]
	s_add_i32 m0, s10, 100352
	s_nop 0
	global_load_lds_dwordx4 v112, s[6:7]
	s_add_i32 m0, s10, 101376
	s_nop 0
	global_load_lds_dwordx4 v193, s[6:7]
	s_add_u32 s6, s6, 0x8000
	s_addc_u32 s7, s7, 0
	s_waitcnt vmcnt(15)
	ds_read_b128 v[38:41], v5 offset:10496
	ds_read_b128 v[42:45], v52 offset:10496
	ds_read_b128 v[46:49], v55 offset:10496
	ds_read_b128 v[196:199], v56 offset:10496
	s_waitcnt lgkmcnt(3)
	v_mfma_f32_32x32x16_bf16 v[212:227], v[70:73], v[38:41], 0
	s_waitcnt lgkmcnt(2)
	v_mfma_f32_32x32x16_bf16 v[212:227], v[74:77], v[42:45], v[212:227]
	s_waitcnt lgkmcnt(1)
	v_mfma_f32_32x32x16_bf16 v[212:227], v[78:81], v[46:49], v[212:227]
	s_waitcnt lgkmcnt(0)
	v_mfma_f32_32x32x16_bf16 v[212:227], v[82:85], v[196:199], v[212:227]
	s_cmpk_gt_i32 s11, 152
	s_cselect_b64 vcc, -1, 0
	v_max_f32_e32 v108, 0, v6
	v_max_f32_e32 v109, 0, v7
	v_pk_mul_f32 v[50:51], v[244:245], v[108:109]
	v_max_f32_e32 v210, 0, v8
	v_max_f32_e32 v211, 0, v9
	v_pk_fma_f32 v[50:51], v[246:247], v[210:211], v[50:51]
	v_max_f32_e32 v108, 0, v10
	v_max_f32_e32 v109, 0, v11
	v_pk_fma_f32 v[50:51], v[248:249], v[108:109], v[50:51]
	v_max_f32_e32 v210, 0, v12
	v_max_f32_e32 v211, 0, v13
	v_pk_fma_f32 v[50:51], v[250:251], v[210:211], v[50:51]
	v_max_f32_e32 v108, 0, v14
	v_max_f32_e32 v109, 0, v15
	v_pk_fma_f32 v[50:51], v[252:253], v[108:109], v[50:51]
	v_max_f32_e32 v210, 0, v16
	v_max_f32_e32 v211, 0, v17
	v_pk_fma_f32 v[50:51], v[254:255], v[210:211], v[50:51]
	v_max_f32_e32 v108, 0, v18
	v_max_f32_e32 v109, 0, v19
	v_pk_fma_f32 v[50:51], v[200:201], v[108:109], v[50:51]
	v_max_f32_e32 v210, 0, v20
	v_max_f32_e32 v211, 0, v21
	v_pk_fma_f32 v[50:51], v[202:203], v[210:211], v[50:51]
	v_add_f32_e32 v50, v50, v51
	v_ashrrev_i32_e32 v51, 31, v50
	v_or_b32_e32 v51, 0x80000000, v51
	v_xor_b32_e32 v50, v51, v50
	v_cndmask_b32_e32 v50, v123, v50, vcc
	global_store_dword v243, v50, s[8:9] offset:2048
	s_add_u32 s8, s8, 0x1000
	s_addc_u32 s9, s9, 0
	v_mfma_f32_32x32x16_bf16 v[6:21], v[86:89], v[38:41], 0
	v_mfma_f32_32x32x16_bf16 v[6:21], v[90:93], v[42:45], v[6:21]
	v_mfma_f32_32x32x16_bf16 v[6:21], v[94:97], v[46:49], v[6:21]
	v_mfma_f32_32x32x16_bf16 v[6:21], v[98:101], v[196:199], v[6:21]
	s_cmpk_gt_i32 s11, 160
	s_cselect_b64 vcc, -1, 0
	v_max_f32_e32 v108, 0, v212
	v_max_f32_e32 v109, 0, v213
	v_pk_mul_f32 v[0:1], v[22:23], v[108:109]
	v_max_f32_e32 v210, 0, v214
	v_max_f32_e32 v211, 0, v215
	v_pk_fma_f32 v[0:1], v[24:25], v[210:211], v[0:1]
	v_max_f32_e32 v108, 0, v216
	v_max_f32_e32 v109, 0, v217
	v_pk_fma_f32 v[0:1], v[26:27], v[108:109], v[0:1]
	v_max_f32_e32 v210, 0, v218
	v_max_f32_e32 v211, 0, v219
	v_pk_fma_f32 v[0:1], v[28:29], v[210:211], v[0:1]
	v_max_f32_e32 v108, 0, v220
	v_max_f32_e32 v109, 0, v221
	v_pk_fma_f32 v[0:1], v[30:31], v[108:109], v[0:1]
	v_max_f32_e32 v210, 0, v222
	v_max_f32_e32 v211, 0, v223
	v_pk_fma_f32 v[0:1], v[32:33], v[210:211], v[0:1]
	v_max_f32_e32 v108, 0, v224
	v_max_f32_e32 v109, 0, v225
	v_pk_fma_f32 v[0:1], v[34:35], v[108:109], v[0:1]
	v_max_f32_e32 v210, 0, v226
	v_max_f32_e32 v211, 0, v227
	v_pk_fma_f32 v[0:1], v[36:37], v[210:211], v[0:1]
	v_add_f32_e32 v0, v0, v1
	v_ashrrev_i32_e32 v1, 31, v0
	v_or_b32_e32 v1, 0x80000000, v1
	v_xor_b32_e32 v0, v1, v0
	v_cndmask_b32_e32 v154, v123, v0, vcc
	s_add_i32 m0, s10, 0
	s_nop 0
	global_load_lds_dwordx4 v102, s[6:7]
	s_add_i32 m0, s10, 1024
	s_nop 0
	global_load_lds_dwordx4 v110, s[6:7]
	s_add_i32 m0, s10, 2048
	s_nop 0
	global_load_lds_dwordx4 v112, s[6:7]
	s_add_i32 m0, s10, 3072
	s_nop 0
	global_load_lds_dwordx4 v193, s[6:7]
	s_add_u32 s6, s6, 0x8000
	s_addc_u32 s7, s7, 0
	s_waitcnt vmcnt(15)
	ds_read_b128 v[38:41], v5 offset:43264
	ds_read_b128 v[42:45], v52 offset:43264
	ds_read_b128 v[46:49], v55 offset:43264
	ds_read_b128 v[196:199], v56 offset:43264
	s_waitcnt lgkmcnt(3)
	v_mfma_f32_32x32x16_bf16 v[212:227], v[70:73], v[38:41], 0
	s_waitcnt lgkmcnt(2)
	v_mfma_f32_32x32x16_bf16 v[212:227], v[74:77], v[42:45], v[212:227]
	s_waitcnt lgkmcnt(1)
	v_mfma_f32_32x32x16_bf16 v[212:227], v[78:81], v[46:49], v[212:227]
	s_waitcnt lgkmcnt(0)
	v_mfma_f32_32x32x16_bf16 v[212:227], v[82:85], v[196:199], v[212:227]
	s_cmpk_gt_i32 s11, 160
	s_cselect_b64 vcc, -1, 0
	v_max_f32_e32 v108, 0, v6
	v_max_f32_e32 v109, 0, v7
	v_pk_mul_f32 v[50:51], v[244:245], v[108:109]
	v_max_f32_e32 v210, 0, v8
	v_max_f32_e32 v211, 0, v9
	v_pk_fma_f32 v[50:51], v[246:247], v[210:211], v[50:51]
	v_max_f32_e32 v108, 0, v10
	v_max_f32_e32 v109, 0, v11
	v_pk_fma_f32 v[50:51], v[248:249], v[108:109], v[50:51]
	v_max_f32_e32 v210, 0, v12
	v_max_f32_e32 v211, 0, v13
	v_pk_fma_f32 v[50:51], v[250:251], v[210:211], v[50:51]
	v_max_f32_e32 v108, 0, v14
	v_max_f32_e32 v109, 0, v15
	v_pk_fma_f32 v[50:51], v[252:253], v[108:109], v[50:51]
	v_max_f32_e32 v210, 0, v16
	v_max_f32_e32 v211, 0, v17
	v_pk_fma_f32 v[50:51], v[254:255], v[210:211], v[50:51]
	v_max_f32_e32 v108, 0, v18
	v_max_f32_e32 v109, 0, v19
	v_pk_fma_f32 v[50:51], v[200:201], v[108:109], v[50:51]
	v_max_f32_e32 v210, 0, v20
	v_max_f32_e32 v211, 0, v21
	v_pk_fma_f32 v[50:51], v[202:203], v[210:211], v[50:51]
	v_add_f32_e32 v50, v50, v51
	v_ashrrev_i32_e32 v51, 31, v50
	v_or_b32_e32 v51, 0x80000000, v51
	v_xor_b32_e32 v50, v51, v50
	v_cndmask_b32_e32 v50, v123, v50, vcc
	global_store_dword v243, v50, s[8:9]
	v_mfma_f32_32x32x16_bf16 v[6:21], v[86:89], v[38:41], 0
	v_mfma_f32_32x32x16_bf16 v[6:21], v[90:93], v[42:45], v[6:21]
	v_mfma_f32_32x32x16_bf16 v[6:21], v[94:97], v[46:49], v[6:21]
	v_mfma_f32_32x32x16_bf16 v[6:21], v[98:101], v[196:199], v[6:21]
	s_cmpk_gt_i32 s11, 168
	s_cselect_b64 vcc, -1, 0
	v_max_f32_e32 v108, 0, v212
	v_max_f32_e32 v109, 0, v213
	v_pk_mul_f32 v[0:1], v[22:23], v[108:109]
	v_max_f32_e32 v210, 0, v214
	v_max_f32_e32 v211, 0, v215
	v_pk_fma_f32 v[0:1], v[24:25], v[210:211], v[0:1]
	v_max_f32_e32 v108, 0, v216
	v_max_f32_e32 v109, 0, v217
	v_pk_fma_f32 v[0:1], v[26:27], v[108:109], v[0:1]
	v_max_f32_e32 v210, 0, v218
	v_max_f32_e32 v211, 0, v219
	v_pk_fma_f32 v[0:1], v[28:29], v[210:211], v[0:1]
	v_max_f32_e32 v108, 0, v220
	v_max_f32_e32 v109, 0, v221
	v_pk_fma_f32 v[0:1], v[30:31], v[108:109], v[0:1]
	v_max_f32_e32 v210, 0, v222
	v_max_f32_e32 v211, 0, v223
	v_pk_fma_f32 v[0:1], v[32:33], v[210:211], v[0:1]
	v_max_f32_e32 v108, 0, v224
	v_max_f32_e32 v109, 0, v225
	v_pk_fma_f32 v[0:1], v[34:35], v[108:109], v[0:1]
	v_max_f32_e32 v210, 0, v226
	v_max_f32_e32 v211, 0, v227
	v_pk_fma_f32 v[0:1], v[36:37], v[210:211], v[0:1]
	v_add_f32_e32 v0, v0, v1
	v_ashrrev_i32_e32 v1, 31, v0
	v_or_b32_e32 v1, 0x80000000, v1
	v_xor_b32_e32 v0, v1, v0
	v_cndmask_b32_e32 v153, v123, v0, vcc
	s_add_i32 m0, s10, 32768
	s_nop 0
	global_load_lds_dwordx4 v102, s[6:7]
	s_add_i32 m0, s10, 33792
	s_nop 0
	global_load_lds_dwordx4 v110, s[6:7]
	s_add_i32 m0, s10, 34816
	s_nop 0
	global_load_lds_dwordx4 v112, s[6:7]
	s_add_i32 m0, s10, 35840
	s_nop 0
	global_load_lds_dwordx4 v193, s[6:7]
	s_add_u32 s6, s6, 0x8000
	s_addc_u32 s7, s7, 0
	s_waitcnt vmcnt(15)
	v_add_u32_e32 v228, 0x10000, v5
	ds_read_b128 v[38:41], v228 offset:10496
	v_add_u32_e32 v228, 0x10000, v52
	ds_read_b128 v[42:45], v228 offset:10496
	v_add_u32_e32 v228, 0x10000, v55
	ds_read_b128 v[46:49], v228 offset:10496
	v_add_u32_e32 v228, 0x10000, v56
	ds_read_b128 v[196:199], v228 offset:10496
	s_waitcnt lgkmcnt(3)
	v_mfma_f32_32x32x16_bf16 v[212:227], v[70:73], v[38:41], 0
	s_waitcnt lgkmcnt(2)
	v_mfma_f32_32x32x16_bf16 v[212:227], v[74:77], v[42:45], v[212:227]
	s_waitcnt lgkmcnt(1)
	v_mfma_f32_32x32x16_bf16 v[212:227], v[78:81], v[46:49], v[212:227]
	s_waitcnt lgkmcnt(0)
	v_mfma_f32_32x32x16_bf16 v[212:227], v[82:85], v[196:199], v[212:227]
	s_cmpk_gt_i32 s11, 168
	s_cselect_b64 vcc, -1, 0
	v_max_f32_e32 v108, 0, v6
	v_max_f32_e32 v109, 0, v7
	v_pk_mul_f32 v[50:51], v[244:245], v[108:109]
	v_max_f32_e32 v210, 0, v8
	v_max_f32_e32 v211, 0, v9
	v_pk_fma_f32 v[50:51], v[246:247], v[210:211], v[50:51]
	v_max_f32_e32 v108, 0, v10
	v_max_f32_e32 v109, 0, v11
	v_pk_fma_f32 v[50:51], v[248:249], v[108:109], v[50:51]
	v_max_f32_e32 v210, 0, v12
	v_max_f32_e32 v211, 0, v13
	v_pk_fma_f32 v[50:51], v[250:251], v[210:211], v[50:51]
	v_max_f32_e32 v108, 0, v14
	v_max_f32_e32 v109, 0, v15
	v_pk_fma_f32 v[50:51], v[252:253], v[108:109], v[50:51]
	v_max_f32_e32 v210, 0, v16
	v_max_f32_e32 v211, 0, v17
	v_pk_fma_f32 v[50:51], v[254:255], v[210:211], v[50:51]
	v_max_f32_e32 v108, 0, v18
	v_max_f32_e32 v109, 0, v19
	v_pk_fma_f32 v[50:51], v[200:201], v[108:109], v[50:51]
	v_max_f32_e32 v210, 0, v20
	v_max_f32_e32 v211, 0, v21
	v_pk_fma_f32 v[50:51], v[202:203], v[210:211], v[50:51]
	v_add_f32_e32 v50, v50, v51
	v_ashrrev_i32_e32 v51, 31, v50
	v_or_b32_e32 v51, 0x80000000, v51
	v_xor_b32_e32 v50, v51, v50
	v_cndmask_b32_e32 v50, v123, v50, vcc
	global_store_dword v243, v50, s[8:9] offset:2048
	s_add_u32 s8, s8, 0x1000
	s_addc_u32 s9, s9, 0
	v_mfma_f32_32x32x16_bf16 v[6:21], v[86:89], v[38:41], 0
	v_mfma_f32_32x32x16_bf16 v[6:21], v[90:93], v[42:45], v[6:21]
	v_mfma_f32_32x32x16_bf16 v[6:21], v[94:97], v[46:49], v[6:21]
	v_mfma_f32_32x32x16_bf16 v[6:21], v[98:101], v[196:199], v[6:21]
	s_cmpk_gt_i32 s11, 176
	s_cselect_b64 vcc, -1, 0
	v_max_f32_e32 v108, 0, v212
	v_max_f32_e32 v109, 0, v213
	v_pk_mul_f32 v[0:1], v[22:23], v[108:109]
	v_max_f32_e32 v210, 0, v214
	v_max_f32_e32 v211, 0, v215
	v_pk_fma_f32 v[0:1], v[24:25], v[210:211], v[0:1]
	v_max_f32_e32 v108, 0, v216
	v_max_f32_e32 v109, 0, v217
	v_pk_fma_f32 v[0:1], v[26:27], v[108:109], v[0:1]
	v_max_f32_e32 v210, 0, v218
	v_max_f32_e32 v211, 0, v219
	v_pk_fma_f32 v[0:1], v[28:29], v[210:211], v[0:1]
	v_max_f32_e32 v108, 0, v220
	v_max_f32_e32 v109, 0, v221
	v_pk_fma_f32 v[0:1], v[30:31], v[108:109], v[0:1]
	v_max_f32_e32 v210, 0, v222
	v_max_f32_e32 v211, 0, v223
	v_pk_fma_f32 v[0:1], v[32:33], v[210:211], v[0:1]
	v_max_f32_e32 v108, 0, v224
	v_max_f32_e32 v109, 0, v225
	v_pk_fma_f32 v[0:1], v[34:35], v[108:109], v[0:1]
	v_max_f32_e32 v210, 0, v226
	v_max_f32_e32 v211, 0, v227
	v_pk_fma_f32 v[0:1], v[36:37], v[210:211], v[0:1]
	v_add_f32_e32 v0, v0, v1
	v_ashrrev_i32_e32 v1, 31, v0
	v_or_b32_e32 v1, 0x80000000, v1
	v_xor_b32_e32 v0, v1, v0
	v_cndmask_b32_e32 v156, v123, v0, vcc
	s_add_i32 m0, s10, 65536
	s_nop 0
	global_load_lds_dwordx4 v102, s[6:7]
	s_add_i32 m0, s10, 66560
	s_nop 0
	global_load_lds_dwordx4 v110, s[6:7]
	s_add_i32 m0, s10, 67584
	s_nop 0
	global_load_lds_dwordx4 v112, s[6:7]
	s_add_i32 m0, s10, 68608
	s_nop 0
	global_load_lds_dwordx4 v193, s[6:7]
	s_add_u32 s6, s6, 0x8000
	s_addc_u32 s7, s7, 0
	s_waitcnt vmcnt(15)
	v_add_u32_e32 v228, 0x10000, v5
	ds_read_b128 v[38:41], v228 offset:43264
	v_add_u32_e32 v228, 0x10000, v52
	ds_read_b128 v[42:45], v228 offset:43264
	v_add_u32_e32 v228, 0x10000, v55
	ds_read_b128 v[46:49], v228 offset:43264
	v_add_u32_e32 v228, 0x10000, v56
	ds_read_b128 v[196:199], v228 offset:43264
	s_waitcnt lgkmcnt(3)
	v_mfma_f32_32x32x16_bf16 v[212:227], v[70:73], v[38:41], 0
	s_waitcnt lgkmcnt(2)
	v_mfma_f32_32x32x16_bf16 v[212:227], v[74:77], v[42:45], v[212:227]
	s_waitcnt lgkmcnt(1)
	v_mfma_f32_32x32x16_bf16 v[212:227], v[78:81], v[46:49], v[212:227]
	s_waitcnt lgkmcnt(0)
	v_mfma_f32_32x32x16_bf16 v[212:227], v[82:85], v[196:199], v[212:227]
	s_cmpk_gt_i32 s11, 176
	s_cselect_b64 vcc, -1, 0
	v_max_f32_e32 v108, 0, v6
	v_max_f32_e32 v109, 0, v7
	v_pk_mul_f32 v[50:51], v[244:245], v[108:109]
	v_max_f32_e32 v210, 0, v8
	v_max_f32_e32 v211, 0, v9
	v_pk_fma_f32 v[50:51], v[246:247], v[210:211], v[50:51]
	v_max_f32_e32 v108, 0, v10
	v_max_f32_e32 v109, 0, v11
	v_pk_fma_f32 v[50:51], v[248:249], v[108:109], v[50:51]
	v_max_f32_e32 v210, 0, v12
	v_max_f32_e32 v211, 0, v13
	v_pk_fma_f32 v[50:51], v[250:251], v[210:211], v[50:51]
	v_max_f32_e32 v108, 0, v14
	v_max_f32_e32 v109, 0, v15
	v_pk_fma_f32 v[50:51], v[252:253], v[108:109], v[50:51]
	v_max_f32_e32 v210, 0, v16
	v_max_f32_e32 v211, 0, v17
	v_pk_fma_f32 v[50:51], v[254:255], v[210:211], v[50:51]
	v_max_f32_e32 v108, 0, v18
	v_max_f32_e32 v109, 0, v19
	v_pk_fma_f32 v[50:51], v[200:201], v[108:109], v[50:51]
	v_max_f32_e32 v210, 0, v20
	v_max_f32_e32 v211, 0, v21
	v_pk_fma_f32 v[50:51], v[202:203], v[210:211], v[50:51]
	v_add_f32_e32 v50, v50, v51
	v_ashrrev_i32_e32 v51, 31, v50
	v_or_b32_e32 v51, 0x80000000, v51
	v_xor_b32_e32 v50, v51, v50
	v_cndmask_b32_e32 v50, v123, v50, vcc
	global_store_dword v243, v50, s[8:9]
	v_mfma_f32_32x32x16_bf16 v[6:21], v[86:89], v[38:41], 0
	v_mfma_f32_32x32x16_bf16 v[6:21], v[90:93], v[42:45], v[6:21]
	v_mfma_f32_32x32x16_bf16 v[6:21], v[94:97], v[46:49], v[6:21]
	v_mfma_f32_32x32x16_bf16 v[6:21], v[98:101], v[196:199], v[6:21]
	s_cmpk_gt_i32 s11, 184
	s_cselect_b64 vcc, -1, 0
	v_max_f32_e32 v108, 0, v212
	v_max_f32_e32 v109, 0, v213
	v_pk_mul_f32 v[0:1], v[22:23], v[108:109]
	v_max_f32_e32 v210, 0, v214
	v_max_f32_e32 v211, 0, v215
	v_pk_fma_f32 v[0:1], v[24:25], v[210:211], v[0:1]
	v_max_f32_e32 v108, 0, v216
	v_max_f32_e32 v109, 0, v217
	v_pk_fma_f32 v[0:1], v[26:27], v[108:109], v[0:1]
	v_max_f32_e32 v210, 0, v218
	v_max_f32_e32 v211, 0, v219
	v_pk_fma_f32 v[0:1], v[28:29], v[210:211], v[0:1]
	v_max_f32_e32 v108, 0, v220
	v_max_f32_e32 v109, 0, v221
	v_pk_fma_f32 v[0:1], v[30:31], v[108:109], v[0:1]
	v_max_f32_e32 v210, 0, v222
	v_max_f32_e32 v211, 0, v223
	v_pk_fma_f32 v[0:1], v[32:33], v[210:211], v[0:1]
	v_max_f32_e32 v108, 0, v224
	v_max_f32_e32 v109, 0, v225
	v_pk_fma_f32 v[0:1], v[34:35], v[108:109], v[0:1]
	v_max_f32_e32 v210, 0, v226
	v_max_f32_e32 v211, 0, v227
	v_pk_fma_f32 v[0:1], v[36:37], v[210:211], v[0:1]
	v_add_f32_e32 v0, v0, v1
	v_ashrrev_i32_e32 v1, 31, v0
	v_or_b32_e32 v1, 0x80000000, v1
	v_xor_b32_e32 v0, v1, v0
	v_cndmask_b32_e32 v155, v123, v0, vcc
	v_max_f32_e32 v108, 0, v6
	v_max_f32_e32 v109, 0, v7
	v_pk_mul_f32 v[50:51], v[244:245], v[108:109]
	v_max_f32_e32 v210, 0, v8
	v_max_f32_e32 v211, 0, v9
	v_pk_fma_f32 v[50:51], v[246:247], v[210:211], v[50:51]
	v_max_f32_e32 v108, 0, v10
	v_max_f32_e32 v109, 0, v11
	v_pk_fma_f32 v[50:51], v[248:249], v[108:109], v[50:51]
	v_max_f32_e32 v210, 0, v12
	v_max_f32_e32 v211, 0, v13
	v_pk_fma_f32 v[50:51], v[250:251], v[210:211], v[50:51]
	v_max_f32_e32 v108, 0, v14
	v_max_f32_e32 v109, 0, v15
	v_pk_fma_f32 v[50:51], v[252:253], v[108:109], v[50:51]
	v_max_f32_e32 v210, 0, v16
	v_max_f32_e32 v211, 0, v17
	v_pk_fma_f32 v[50:51], v[254:255], v[210:211], v[50:51]
	v_max_f32_e32 v108, 0, v18
	v_max_f32_e32 v109, 0, v19
	v_pk_fma_f32 v[50:51], v[200:201], v[108:109], v[50:51]
	v_max_f32_e32 v210, 0, v20
	v_max_f32_e32 v211, 0, v21
	v_pk_fma_f32 v[50:51], v[202:203], v[210:211], v[50:51]
	v_add_f32_e32 v50, v50, v51
	v_ashrrev_i32_e32 v51, 31, v50
	v_or_b32_e32 v51, 0x80000000, v51
	v_xor_b32_e32 v50, v51, v50
	v_cndmask_b32_e32 v50, v123, v50, vcc
	global_store_dword v243, v50, s[8:9] offset:2048
	s_add_u32 s8, s8, 0x1000
	s_addc_u32 s9, s9, 0
	s_cmpk_gt_i32 s81, 24
	s_cbranch_scc0 .Lix_fill_3
	s_add_i32 m0, s10, 98304
	s_nop 0
	global_load_lds_dwordx4 v102, s[6:7]
	s_add_i32 m0, s10, 99328
	s_nop 0
	global_load_lds_dwordx4 v110, s[6:7]
	s_add_i32 m0, s10, 100352
	s_nop 0
	global_load_lds_dwordx4 v112, s[6:7]
	s_add_i32 m0, s10, 101376
	s_nop 0
	global_load_lds_dwordx4 v193, s[6:7]
	s_add_u32 s6, s6, 0x8000
	s_addc_u32 s7, s7, 0
	s_waitcnt vmcnt(16)
	ds_read_b128 v[38:41], v5 offset:10496
	ds_read_b128 v[42:45], v52 offset:10496
	ds_read_b128 v[46:49], v55 offset:10496
	ds_read_b128 v[196:199], v56 offset:10496
	s_waitcnt lgkmcnt(3)
	v_mfma_f32_32x32x16_bf16 v[212:227], v[70:73], v[38:41], 0
	s_waitcnt lgkmcnt(2)
	v_mfma_f32_32x32x16_bf16 v[212:227], v[74:77], v[42:45], v[212:227]
	s_waitcnt lgkmcnt(1)
	v_mfma_f32_32x32x16_bf16 v[212:227], v[78:81], v[46:49], v[212:227]
	s_waitcnt lgkmcnt(0)
	v_mfma_f32_32x32x16_bf16 v[212:227], v[82:85], v[196:199], v[212:227]
	v_mfma_f32_32x32x16_bf16 v[6:21], v[86:89], v[38:41], 0
	v_mfma_f32_32x32x16_bf16 v[6:21], v[90:93], v[42:45], v[6:21]
	v_mfma_f32_32x32x16_bf16 v[6:21], v[94:97], v[46:49], v[6:21]
	v_mfma_f32_32x32x16_bf16 v[6:21], v[98:101], v[196:199], v[6:21]
	s_nop 7
	s_cmpk_gt_i32 s11, 192
	s_cselect_b64 vcc, -1, 0
	v_max_f32_e32 v108, 0, v212
	v_max_f32_e32 v109, 0, v213
	v_pk_mul_f32 v[0:1], v[22:23], v[108:109]
	v_max_f32_e32 v210, 0, v214
	v_max_f32_e32 v211, 0, v215
	v_pk_fma_f32 v[0:1], v[24:25], v[210:211], v[0:1]
	v_max_f32_e32 v108, 0, v216
	v_max_f32_e32 v109, 0, v217
	v_pk_fma_f32 v[0:1], v[26:27], v[108:109], v[0:1]
	v_max_f32_e32 v210, 0, v218
	v_max_f32_e32 v211, 0, v219
	v_pk_fma_f32 v[0:1], v[28:29], v[210:211], v[0:1]
	v_max_f32_e32 v108, 0, v220
	v_max_f32_e32 v109, 0, v221
	v_pk_fma_f32 v[0:1], v[30:31], v[108:109], v[0:1]
	v_max_f32_e32 v210, 0, v222
	v_max_f32_e32 v211, 0, v223
	v_pk_fma_f32 v[0:1], v[32:33], v[210:211], v[0:1]
	v_max_f32_e32 v108, 0, v224
	v_max_f32_e32 v109, 0, v225
	v_pk_fma_f32 v[0:1], v[34:35], v[108:109], v[0:1]
	v_max_f32_e32 v210, 0, v226
	v_max_f32_e32 v211, 0, v227
	v_pk_fma_f32 v[0:1], v[36:37], v[210:211], v[0:1]
	v_add_f32_e32 v0, v0, v1
	v_ashrrev_i32_e32 v1, 31, v0
	v_or_b32_e32 v1, 0x80000000, v1
	v_xor_b32_e32 v0, v1, v0
	v_cndmask_b32_e32 v158, v123, v0, vcc
	s_add_i32 m0, s10, 0
	s_nop 0
	global_load_lds_dwordx4 v102, s[6:7]
	s_add_i32 m0, s10, 1024
	s_nop 0
	global_load_lds_dwordx4 v110, s[6:7]
	s_add_i32 m0, s10, 2048
	s_nop 0
	global_load_lds_dwordx4 v112, s[6:7]
	s_add_i32 m0, s10, 3072
	s_nop 0
	global_load_lds_dwordx4 v193, s[6:7]
	s_add_u32 s6, s6, 0x8000
	s_addc_u32 s7, s7, 0
	s_waitcnt vmcnt(15)
	ds_read_b128 v[38:41], v5 offset:43264
	ds_read_b128 v[42:45], v52 offset:43264
	ds_read_b128 v[46:49], v55 offset:43264
	ds_read_b128 v[196:199], v56 offset:43264
	s_waitcnt lgkmcnt(3)
	v_mfma_f32_32x32x16_bf16 v[212:227], v[70:73], v[38:41], 0
	s_waitcnt lgkmcnt(2)
	v_mfma_f32_32x32x16_bf16 v[212:227], v[74:77], v[42:45], v[212:227]
	s_waitcnt lgkmcnt(1)
	v_mfma_f32_32x32x16_bf16 v[212:227], v[78:81], v[46:49], v[212:227]
	s_waitcnt lgkmcnt(0)
	v_mfma_f32_32x32x16_bf16 v[212:227], v[82:85], v[196:199], v[212:227]
	s_cmpk_gt_i32 s11, 192
	s_cselect_b64 vcc, -1, 0
	v_max_f32_e32 v108, 0, v6
	v_max_f32_e32 v109, 0, v7
	v_pk_mul_f32 v[50:51], v[244:245], v[108:109]
	v_max_f32_e32 v210, 0, v8
	v_max_f32_e32 v211, 0, v9
	v_pk_fma_f32 v[50:51], v[246:247], v[210:211], v[50:51]
	v_max_f32_e32 v108, 0, v10
	v_max_f32_e32 v109, 0, v11
	v_pk_fma_f32 v[50:51], v[248:249], v[108:109], v[50:51]
	v_max_f32_e32 v210, 0, v12
	v_max_f32_e32 v211, 0, v13
	v_pk_fma_f32 v[50:51], v[250:251], v[210:211], v[50:51]
	v_max_f32_e32 v108, 0, v14
	v_max_f32_e32 v109, 0, v15
	v_pk_fma_f32 v[50:51], v[252:253], v[108:109], v[50:51]
	v_max_f32_e32 v210, 0, v16
	v_max_f32_e32 v211, 0, v17
	v_pk_fma_f32 v[50:51], v[254:255], v[210:211], v[50:51]
	v_max_f32_e32 v108, 0, v18
	v_max_f32_e32 v109, 0, v19
	v_pk_fma_f32 v[50:51], v[200:201], v[108:109], v[50:51]
	v_max_f32_e32 v210, 0, v20
	v_max_f32_e32 v211, 0, v21
	v_pk_fma_f32 v[50:51], v[202:203], v[210:211], v[50:51]
	v_add_f32_e32 v50, v50, v51
	v_ashrrev_i32_e32 v51, 31, v50
	v_or_b32_e32 v51, 0x80000000, v51
	v_xor_b32_e32 v50, v51, v50
	v_cndmask_b32_e32 v50, v123, v50, vcc
	global_store_dword v243, v50, s[8:9]
	v_mfma_f32_32x32x16_bf16 v[6:21], v[86:89], v[38:41], 0
	v_mfma_f32_32x32x16_bf16 v[6:21], v[90:93], v[42:45], v[6:21]
	v_mfma_f32_32x32x16_bf16 v[6:21], v[94:97], v[46:49], v[6:21]
	v_mfma_f32_32x32x16_bf16 v[6:21], v[98:101], v[196:199], v[6:21]
	s_cmpk_gt_i32 s11, 200
	s_cselect_b64 vcc, -1, 0
	v_max_f32_e32 v108, 0, v212
	v_max_f32_e32 v109, 0, v213
	v_pk_mul_f32 v[0:1], v[22:23], v[108:109]
	v_max_f32_e32 v210, 0, v214
	v_max_f32_e32 v211, 0, v215
	v_pk_fma_f32 v[0:1], v[24:25], v[210:211], v[0:1]
	v_max_f32_e32 v108, 0, v216
	v_max_f32_e32 v109, 0, v217
	v_pk_fma_f32 v[0:1], v[26:27], v[108:109], v[0:1]
	v_max_f32_e32 v210, 0, v218
	v_max_f32_e32 v211, 0, v219
	v_pk_fma_f32 v[0:1], v[28:29], v[210:211], v[0:1]
	v_max_f32_e32 v108, 0, v220
	v_max_f32_e32 v109, 0, v221
	v_pk_fma_f32 v[0:1], v[30:31], v[108:109], v[0:1]
	v_max_f32_e32 v210, 0, v222
	v_max_f32_e32 v211, 0, v223
	v_pk_fma_f32 v[0:1], v[32:33], v[210:211], v[0:1]
	v_max_f32_e32 v108, 0, v224
	v_max_f32_e32 v109, 0, v225
	v_pk_fma_f32 v[0:1], v[34:35], v[108:109], v[0:1]
	v_max_f32_e32 v210, 0, v226
	v_max_f32_e32 v211, 0, v227
	v_pk_fma_f32 v[0:1], v[36:37], v[210:211], v[0:1]
	v_add_f32_e32 v0, v0, v1
	v_ashrrev_i32_e32 v1, 31, v0
	v_or_b32_e32 v1, 0x80000000, v1
	v_xor_b32_e32 v0, v1, v0
	v_cndmask_b32_e32 v157, v123, v0, vcc
	s_add_i32 m0, s10, 32768
	s_nop 0
	global_load_lds_dwordx4 v102, s[6:7]
	s_add_i32 m0, s10, 33792
	s_nop 0
	global_load_lds_dwordx4 v110, s[6:7]
	s_add_i32 m0, s10, 34816
	s_nop 0
	global_load_lds_dwordx4 v112, s[6:7]
	s_add_i32 m0, s10, 35840
	s_nop 0
	global_load_lds_dwordx4 v193, s[6:7]
	s_add_u32 s6, s6, 0x8000
	s_addc_u32 s7, s7, 0
	s_waitcnt vmcnt(15)
	v_add_u32_e32 v228, 0x10000, v5
	ds_read_b128 v[38:41], v228 offset:10496
	v_add_u32_e32 v228, 0x10000, v52
	ds_read_b128 v[42:45], v228 offset:10496
	v_add_u32_e32 v228, 0x10000, v55
	ds_read_b128 v[46:49], v228 offset:10496
	v_add_u32_e32 v228, 0x10000, v56
	ds_read_b128 v[196:199], v228 offset:10496
	s_waitcnt lgkmcnt(3)
	v_mfma_f32_32x32x16_bf16 v[212:227], v[70:73], v[38:41], 0
	s_waitcnt lgkmcnt(2)
	v_mfma_f32_32x32x16_bf16 v[212:227], v[74:77], v[42:45], v[212:227]
	s_waitcnt lgkmcnt(1)
	v_mfma_f32_32x32x16_bf16 v[212:227], v[78:81], v[46:49], v[212:227]
	s_waitcnt lgkmcnt(0)
	v_mfma_f32_32x32x16_bf16 v[212:227], v[82:85], v[196:199], v[212:227]
	s_cmpk_gt_i32 s11, 200
	s_cselect_b64 vcc, -1, 0
	v_max_f32_e32 v108, 0, v6
	v_max_f32_e32 v109, 0, v7
	v_pk_mul_f32 v[50:51], v[244:245], v[108:109]
	v_max_f32_e32 v210, 0, v8
	v_max_f32_e32 v211, 0, v9
	v_pk_fma_f32 v[50:51], v[246:247], v[210:211], v[50:51]
	v_max_f32_e32 v108, 0, v10
	v_max_f32_e32 v109, 0, v11
	v_pk_fma_f32 v[50:51], v[248:249], v[108:109], v[50:51]
	v_max_f32_e32 v210, 0, v12
	v_max_f32_e32 v211, 0, v13
	v_pk_fma_f32 v[50:51], v[250:251], v[210:211], v[50:51]
	v_max_f32_e32 v108, 0, v14
	v_max_f32_e32 v109, 0, v15
	v_pk_fma_f32 v[50:51], v[252:253], v[108:109], v[50:51]
	v_max_f32_e32 v210, 0, v16
	v_max_f32_e32 v211, 0, v17
	v_pk_fma_f32 v[50:51], v[254:255], v[210:211], v[50:51]
	v_max_f32_e32 v108, 0, v18
	v_max_f32_e32 v109, 0, v19
	v_pk_fma_f32 v[50:51], v[200:201], v[108:109], v[50:51]
	v_max_f32_e32 v210, 0, v20
	v_max_f32_e32 v211, 0, v21
	v_pk_fma_f32 v[50:51], v[202:203], v[210:211], v[50:51]
	v_add_f32_e32 v50, v50, v51
	v_ashrrev_i32_e32 v51, 31, v50
	v_or_b32_e32 v51, 0x80000000, v51
	v_xor_b32_e32 v50, v51, v50
	v_cndmask_b32_e32 v50, v123, v50, vcc
	global_store_dword v243, v50, s[8:9] offset:2048
	s_add_u32 s8, s8, 0x1000
	s_addc_u32 s9, s9, 0
	v_mfma_f32_32x32x16_bf16 v[6:21], v[86:89], v[38:41], 0
	v_mfma_f32_32x32x16_bf16 v[6:21], v[90:93], v[42:45], v[6:21]
	v_mfma_f32_32x32x16_bf16 v[6:21], v[94:97], v[46:49], v[6:21]
	v_mfma_f32_32x32x16_bf16 v[6:21], v[98:101], v[196:199], v[6:21]
	s_cmpk_gt_i32 s11, 208
	s_cselect_b64 vcc, -1, 0
	v_max_f32_e32 v108, 0, v212
	v_max_f32_e32 v109, 0, v213
	v_pk_mul_f32 v[0:1], v[22:23], v[108:109]
	v_max_f32_e32 v210, 0, v214
	v_max_f32_e32 v211, 0, v215
	v_pk_fma_f32 v[0:1], v[24:25], v[210:211], v[0:1]
	v_max_f32_e32 v108, 0, v216
	v_max_f32_e32 v109, 0, v217
	v_pk_fma_f32 v[0:1], v[26:27], v[108:109], v[0:1]
	v_max_f32_e32 v210, 0, v218
	v_max_f32_e32 v211, 0, v219
	v_pk_fma_f32 v[0:1], v[28:29], v[210:211], v[0:1]
	v_max_f32_e32 v108, 0, v220
	v_max_f32_e32 v109, 0, v221
	v_pk_fma_f32 v[0:1], v[30:31], v[108:109], v[0:1]
	v_max_f32_e32 v210, 0, v222
	v_max_f32_e32 v211, 0, v223
	v_pk_fma_f32 v[0:1], v[32:33], v[210:211], v[0:1]
	v_max_f32_e32 v108, 0, v224
	v_max_f32_e32 v109, 0, v225
	v_pk_fma_f32 v[0:1], v[34:35], v[108:109], v[0:1]
	v_max_f32_e32 v210, 0, v226
	v_max_f32_e32 v211, 0, v227
	v_pk_fma_f32 v[0:1], v[36:37], v[210:211], v[0:1]
	v_add_f32_e32 v0, v0, v1
	v_ashrrev_i32_e32 v1, 31, v0
	v_or_b32_e32 v1, 0x80000000, v1
	v_xor_b32_e32 v0, v1, v0
	v_cndmask_b32_e32 v160, v123, v0, vcc
	s_add_i32 m0, s10, 65536
	s_nop 0
	global_load_lds_dwordx4 v102, s[6:7]
	s_add_i32 m0, s10, 66560
	s_nop 0
	global_load_lds_dwordx4 v110, s[6:7]
	s_add_i32 m0, s10, 67584
	s_nop 0
	global_load_lds_dwordx4 v112, s[6:7]
	s_add_i32 m0, s10, 68608
	s_nop 0
	global_load_lds_dwordx4 v193, s[6:7]
	s_add_u32 s6, s6, 0x8000
	s_addc_u32 s7, s7, 0
	s_waitcnt vmcnt(14)
	v_add_u32_e32 v228, 0x10000, v5
	ds_read_b128 v[38:41], v228 offset:43264
	v_add_u32_e32 v228, 0x10000, v52
	ds_read_b128 v[42:45], v228 offset:43264
	v_add_u32_e32 v228, 0x10000, v55
	ds_read_b128 v[46:49], v228 offset:43264
	v_add_u32_e32 v228, 0x10000, v56
	ds_read_b128 v[196:199], v228 offset:43264
	s_waitcnt lgkmcnt(3)
	v_mfma_f32_32x32x16_bf16 v[212:227], v[70:73], v[38:41], 0
	s_waitcnt lgkmcnt(2)
	v_mfma_f32_32x32x16_bf16 v[212:227], v[74:77], v[42:45], v[212:227]
	s_waitcnt lgkmcnt(1)
	v_mfma_f32_32x32x16_bf16 v[212:227], v[78:81], v[46:49], v[212:227]
	s_waitcnt lgkmcnt(0)
	v_mfma_f32_32x32x16_bf16 v[212:227], v[82:85], v[196:199], v[212:227]
	s_cmpk_gt_i32 s11, 208
	s_cselect_b64 vcc, -1, 0
	v_max_f32_e32 v108, 0, v6
	v_max_f32_e32 v109, 0, v7
	v_pk_mul_f32 v[50:51], v[244:245], v[108:109]
	v_max_f32_e32 v210, 0, v8
	v_max_f32_e32 v211, 0, v9
	v_pk_fma_f32 v[50:51], v[246:247], v[210:211], v[50:51]
	v_max_f32_e32 v108, 0, v10
	v_max_f32_e32 v109, 0, v11
	v_pk_fma_f32 v[50:51], v[248:249], v[108:109], v[50:51]
	v_max_f32_e32 v210, 0, v12
	v_max_f32_e32 v211, 0, v13
	v_pk_fma_f32 v[50:51], v[250:251], v[210:211], v[50:51]
	v_max_f32_e32 v108, 0, v14
	v_max_f32_e32 v109, 0, v15
	v_pk_fma_f32 v[50:51], v[252:253], v[108:109], v[50:51]
	v_max_f32_e32 v210, 0, v16
	v_max_f32_e32 v211, 0, v17
	v_pk_fma_f32 v[50:51], v[254:255], v[210:211], v[50:51]
	v_max_f32_e32 v108, 0, v18
	v_max_f32_e32 v109, 0, v19
	v_pk_fma_f32 v[50:51], v[200:201], v[108:109], v[50:51]
	v_max_f32_e32 v210, 0, v20
	v_max_f32_e32 v211, 0, v21
	v_pk_fma_f32 v[50:51], v[202:203], v[210:211], v[50:51]
	v_add_f32_e32 v50, v50, v51
	v_ashrrev_i32_e32 v51, 31, v50
	v_or_b32_e32 v51, 0x80000000, v51
	v_xor_b32_e32 v50, v51, v50
	v_cndmask_b32_e32 v50, v123, v50, vcc
	global_store_dword v243, v50, s[8:9]
	v_mfma_f32_32x32x16_bf16 v[6:21], v[86:89], v[38:41], 0
	v_mfma_f32_32x32x16_bf16 v[6:21], v[90:93], v[42:45], v[6:21]
	v_mfma_f32_32x32x16_bf16 v[6:21], v[94:97], v[46:49], v[6:21]
	v_mfma_f32_32x32x16_bf16 v[6:21], v[98:101], v[196:199], v[6:21]
	s_cmpk_gt_i32 s11, 216
	s_cselect_b64 vcc, -1, 0
	v_max_f32_e32 v108, 0, v212
	v_max_f32_e32 v109, 0, v213
	v_pk_mul_f32 v[0:1], v[22:23], v[108:109]
	v_max_f32_e32 v210, 0, v214
	v_max_f32_e32 v211, 0, v215
	v_pk_fma_f32 v[0:1], v[24:25], v[210:211], v[0:1]
	v_max_f32_e32 v108, 0, v216
	v_max_f32_e32 v109, 0, v217
	v_pk_fma_f32 v[0:1], v[26:27], v[108:109], v[0:1]
	v_max_f32_e32 v210, 0, v218
	v_max_f32_e32 v211, 0, v219
	v_pk_fma_f32 v[0:1], v[28:29], v[210:211], v[0:1]
	v_max_f32_e32 v108, 0, v220
	v_max_f32_e32 v109, 0, v221
	v_pk_fma_f32 v[0:1], v[30:31], v[108:109], v[0:1]
	v_max_f32_e32 v210, 0, v222
	v_max_f32_e32 v211, 0, v223
	v_pk_fma_f32 v[0:1], v[32:33], v[210:211], v[0:1]
	v_max_f32_e32 v108, 0, v224
	v_max_f32_e32 v109, 0, v225
	v_pk_fma_f32 v[0:1], v[34:35], v[108:109], v[0:1]
	v_max_f32_e32 v210, 0, v226
	v_max_f32_e32 v211, 0, v227
	v_pk_fma_f32 v[0:1], v[36:37], v[210:211], v[0:1]
	v_add_f32_e32 v0, v0, v1
	v_ashrrev_i32_e32 v1, 31, v0
	v_or_b32_e32 v1, 0x80000000, v1
	v_xor_b32_e32 v0, v1, v0
	v_cndmask_b32_e32 v159, v123, v0, vcc
	s_add_i32 m0, s10, 98304
	s_nop 0
	global_load_lds_dwordx4 v102, s[6:7]
	s_add_i32 m0, s10, 99328
	s_nop 0
	global_load_lds_dwordx4 v110, s[6:7]
	s_add_i32 m0, s10, 100352
	s_nop 0
	global_load_lds_dwordx4 v112, s[6:7]
	s_add_i32 m0, s10, 101376
	s_nop 0
	global_load_lds_dwordx4 v193, s[6:7]
	s_add_u32 s6, s6, 0x8000
	s_addc_u32 s7, s7, 0
	s_waitcnt vmcnt(15)
	ds_read_b128 v[38:41], v5 offset:10496
	ds_read_b128 v[42:45], v52 offset:10496
	ds_read_b128 v[46:49], v55 offset:10496
	ds_read_b128 v[196:199], v56 offset:10496
	s_waitcnt lgkmcnt(3)
	v_mfma_f32_32x32x16_bf16 v[212:227], v[70:73], v[38:41], 0
	s_waitcnt lgkmcnt(2)
	v_mfma_f32_32x32x16_bf16 v[212:227], v[74:77], v[42:45], v[212:227]
	s_waitcnt lgkmcnt(1)
	v_mfma_f32_32x32x16_bf16 v[212:227], v[78:81], v[46:49], v[212:227]
	s_waitcnt lgkmcnt(0)
	v_mfma_f32_32x32x16_bf16 v[212:227], v[82:85], v[196:199], v[212:227]
	s_cmpk_gt_i32 s11, 216
	s_cselect_b64 vcc, -1, 0
	v_max_f32_e32 v108, 0, v6
	v_max_f32_e32 v109, 0, v7
	v_pk_mul_f32 v[50:51], v[244:245], v[108:109]
	v_max_f32_e32 v210, 0, v8
	v_max_f32_e32 v211, 0, v9
	v_pk_fma_f32 v[50:51], v[246:247], v[210:211], v[50:51]
	v_max_f32_e32 v108, 0, v10
	v_max_f32_e32 v109, 0, v11
	v_pk_fma_f32 v[50:51], v[248:249], v[108:109], v[50:51]
	v_max_f32_e32 v210, 0, v12
	v_max_f32_e32 v211, 0, v13
	v_pk_fma_f32 v[50:51], v[250:251], v[210:211], v[50:51]
	v_max_f32_e32 v108, 0, v14
	v_max_f32_e32 v109, 0, v15
	v_pk_fma_f32 v[50:51], v[252:253], v[108:109], v[50:51]
	v_max_f32_e32 v210, 0, v16
	v_max_f32_e32 v211, 0, v17
	v_pk_fma_f32 v[50:51], v[254:255], v[210:211], v[50:51]
	v_max_f32_e32 v108, 0, v18
	v_max_f32_e32 v109, 0, v19
	v_pk_fma_f32 v[50:51], v[200:201], v[108:109], v[50:51]
	v_max_f32_e32 v210, 0, v20
	v_max_f32_e32 v211, 0, v21
	v_pk_fma_f32 v[50:51], v[202:203], v[210:211], v[50:51]
	v_add_f32_e32 v50, v50, v51
	v_ashrrev_i32_e32 v51, 31, v50
	v_or_b32_e32 v51, 0x80000000, v51
	v_xor_b32_e32 v50, v51, v50
	v_cndmask_b32_e32 v50, v123, v50, vcc
	global_store_dword v243, v50, s[8:9] offset:2048
	s_add_u32 s8, s8, 0x1000
	s_addc_u32 s9, s9, 0
	v_mfma_f32_32x32x16_bf16 v[6:21], v[86:89], v[38:41], 0
	v_mfma_f32_32x32x16_bf16 v[6:21], v[90:93], v[42:45], v[6:21]
	v_mfma_f32_32x32x16_bf16 v[6:21], v[94:97], v[46:49], v[6:21]
	v_mfma_f32_32x32x16_bf16 v[6:21], v[98:101], v[196:199], v[6:21]
	s_cmpk_gt_i32 s11, 224
	s_cselect_b64 vcc, -1, 0
	v_max_f32_e32 v108, 0, v212
	v_max_f32_e32 v109, 0, v213
	v_pk_mul_f32 v[0:1], v[22:23], v[108:109]
	v_max_f32_e32 v210, 0, v214
	v_max_f32_e32 v211, 0, v215
	v_pk_fma_f32 v[0:1], v[24:25], v[210:211], v[0:1]
	v_max_f32_e32 v108, 0, v216
	v_max_f32_e32 v109, 0, v217
	v_pk_fma_f32 v[0:1], v[26:27], v[108:109], v[0:1]
	v_max_f32_e32 v210, 0, v218
	v_max_f32_e32 v211, 0, v219
	v_pk_fma_f32 v[0:1], v[28:29], v[210:211], v[0:1]
	v_max_f32_e32 v108, 0, v220
	v_max_f32_e32 v109, 0, v221
	v_pk_fma_f32 v[0:1], v[30:31], v[108:109], v[0:1]
	v_max_f32_e32 v210, 0, v222
	v_max_f32_e32 v211, 0, v223
	v_pk_fma_f32 v[0:1], v[32:33], v[210:211], v[0:1]
	v_max_f32_e32 v108, 0, v224
	v_max_f32_e32 v109, 0, v225
	v_pk_fma_f32 v[0:1], v[34:35], v[108:109], v[0:1]
	v_max_f32_e32 v210, 0, v226
	v_max_f32_e32 v211, 0, v227
	v_pk_fma_f32 v[0:1], v[36:37], v[210:211], v[0:1]
	v_add_f32_e32 v0, v0, v1
	v_ashrrev_i32_e32 v1, 31, v0
	v_or_b32_e32 v1, 0x80000000, v1
	v_xor_b32_e32 v0, v1, v0
	v_cndmask_b32_e32 v162, v123, v0, vcc
	s_add_i32 m0, s10, 0
	s_nop 0
	global_load_lds_dwordx4 v102, s[6:7]
	s_add_i32 m0, s10, 1024
	s_nop 0
	global_load_lds_dwordx4 v110, s[6:7]
	s_add_i32 m0, s10, 2048
	s_nop 0
	global_load_lds_dwordx4 v112, s[6:7]
	s_add_i32 m0, s10, 3072
	s_nop 0
	global_load_lds_dwordx4 v193, s[6:7]
	s_add_u32 s6, s6, 0x8000
	s_addc_u32 s7, s7, 0
	s_waitcnt vmcnt(15)
	ds_read_b128 v[38:41], v5 offset:43264
	ds_read_b128 v[42:45], v52 offset:43264
	ds_read_b128 v[46:49], v55 offset:43264
	ds_read_b128 v[196:199], v56 offset:43264
	s_waitcnt lgkmcnt(3)
	v_mfma_f32_32x32x16_bf16 v[212:227], v[70:73], v[38:41], 0
	s_waitcnt lgkmcnt(2)
	v_mfma_f32_32x32x16_bf16 v[212:227], v[74:77], v[42:45], v[212:227]
	s_waitcnt lgkmcnt(1)
	v_mfma_f32_32x32x16_bf16 v[212:227], v[78:81], v[46:49], v[212:227]
	s_waitcnt lgkmcnt(0)
	v_mfma_f32_32x32x16_bf16 v[212:227], v[82:85], v[196:199], v[212:227]
	s_cmpk_gt_i32 s11, 224
	s_cselect_b64 vcc, -1, 0
	v_max_f32_e32 v108, 0, v6
	v_max_f32_e32 v109, 0, v7
	v_pk_mul_f32 v[50:51], v[244:245], v[108:109]
	v_max_f32_e32 v210, 0, v8
	v_max_f32_e32 v211, 0, v9
	v_pk_fma_f32 v[50:51], v[246:247], v[210:211], v[50:51]
	v_max_f32_e32 v108, 0, v10
	v_max_f32_e32 v109, 0, v11
	v_pk_fma_f32 v[50:51], v[248:249], v[108:109], v[50:51]
	v_max_f32_e32 v210, 0, v12
	v_max_f32_e32 v211, 0, v13
	v_pk_fma_f32 v[50:51], v[250:251], v[210:211], v[50:51]
	v_max_f32_e32 v108, 0, v14
	v_max_f32_e32 v109, 0, v15
	v_pk_fma_f32 v[50:51], v[252:253], v[108:109], v[50:51]
	v_max_f32_e32 v210, 0, v16
	v_max_f32_e32 v211, 0, v17
	v_pk_fma_f32 v[50:51], v[254:255], v[210:211], v[50:51]
	v_max_f32_e32 v108, 0, v18
	v_max_f32_e32 v109, 0, v19
	v_pk_fma_f32 v[50:51], v[200:201], v[108:109], v[50:51]
	v_max_f32_e32 v210, 0, v20
	v_max_f32_e32 v211, 0, v21
	v_pk_fma_f32 v[50:51], v[202:203], v[210:211], v[50:51]
	v_add_f32_e32 v50, v50, v51
	v_ashrrev_i32_e32 v51, 31, v50
	v_or_b32_e32 v51, 0x80000000, v51
	v_xor_b32_e32 v50, v51, v50
	v_cndmask_b32_e32 v50, v123, v50, vcc
	global_store_dword v243, v50, s[8:9]
	v_mfma_f32_32x32x16_bf16 v[6:21], v[86:89], v[38:41], 0
	v_mfma_f32_32x32x16_bf16 v[6:21], v[90:93], v[42:45], v[6:21]
	v_mfma_f32_32x32x16_bf16 v[6:21], v[94:97], v[46:49], v[6:21]
	v_mfma_f32_32x32x16_bf16 v[6:21], v[98:101], v[196:199], v[6:21]
	s_cmpk_gt_i32 s11, 232
	s_cselect_b64 vcc, -1, 0
	v_max_f32_e32 v108, 0, v212
	v_max_f32_e32 v109, 0, v213
	v_pk_mul_f32 v[0:1], v[22:23], v[108:109]
	v_max_f32_e32 v210, 0, v214
	v_max_f32_e32 v211, 0, v215
	v_pk_fma_f32 v[0:1], v[24:25], v[210:211], v[0:1]
	v_max_f32_e32 v108, 0, v216
	v_max_f32_e32 v109, 0, v217
	v_pk_fma_f32 v[0:1], v[26:27], v[108:109], v[0:1]
	v_max_f32_e32 v210, 0, v218
	v_max_f32_e32 v211, 0, v219
	v_pk_fma_f32 v[0:1], v[28:29], v[210:211], v[0:1]
	v_max_f32_e32 v108, 0, v220
	v_max_f32_e32 v109, 0, v221
	v_pk_fma_f32 v[0:1], v[30:31], v[108:109], v[0:1]
	v_max_f32_e32 v210, 0, v222
	v_max_f32_e32 v211, 0, v223
	v_pk_fma_f32 v[0:1], v[32:33], v[210:211], v[0:1]
	v_max_f32_e32 v108, 0, v224
	v_max_f32_e32 v109, 0, v225
	v_pk_fma_f32 v[0:1], v[34:35], v[108:109], v[0:1]
	v_max_f32_e32 v210, 0, v226
	v_max_f32_e32 v211, 0, v227
	v_pk_fma_f32 v[0:1], v[36:37], v[210:211], v[0:1]
	v_add_f32_e32 v0, v0, v1
	v_ashrrev_i32_e32 v1, 31, v0
	v_or_b32_e32 v1, 0x80000000, v1
	v_xor_b32_e32 v0, v1, v0
	v_cndmask_b32_e32 v161, v123, v0, vcc
	s_add_i32 m0, s10, 32768
	s_nop 0
	global_load_lds_dwordx4 v102, s[6:7]
	s_add_i32 m0, s10, 33792
	s_nop 0
	global_load_lds_dwordx4 v110, s[6:7]
	s_add_i32 m0, s10, 34816
	s_nop 0
	global_load_lds_dwordx4 v112, s[6:7]
	s_add_i32 m0, s10, 35840
	s_nop 0
	global_load_lds_dwordx4 v193, s[6:7]
	s_add_u32 s6, s6, 0x8000
	s_addc_u32 s7, s7, 0
	s_waitcnt vmcnt(15)
	v_add_u32_e32 v228, 0x10000, v5
	ds_read_b128 v[38:41], v228 offset:10496
	v_add_u32_e32 v228, 0x10000, v52
	ds_read_b128 v[42:45], v228 offset:10496
	v_add_u32_e32 v228, 0x10000, v55
	ds_read_b128 v[46:49], v228 offset:10496
	v_add_u32_e32 v228, 0x10000, v56
	ds_read_b128 v[196:199], v228 offset:10496
	s_waitcnt lgkmcnt(3)
	v_mfma_f32_32x32x16_bf16 v[212:227], v[70:73], v[38:41], 0
	s_waitcnt lgkmcnt(2)
	v_mfma_f32_32x32x16_bf16 v[212:227], v[74:77], v[42:45], v[212:227]
	s_waitcnt lgkmcnt(1)
	v_mfma_f32_32x32x16_bf16 v[212:227], v[78:81], v[46:49], v[212:227]
	s_waitcnt lgkmcnt(0)
	v_mfma_f32_32x32x16_bf16 v[212:227], v[82:85], v[196:199], v[212:227]
	s_cmpk_gt_i32 s11, 232
	s_cselect_b64 vcc, -1, 0
	v_max_f32_e32 v108, 0, v6
	v_max_f32_e32 v109, 0, v7
	v_pk_mul_f32 v[50:51], v[244:245], v[108:109]
	v_max_f32_e32 v210, 0, v8
	v_max_f32_e32 v211, 0, v9
	v_pk_fma_f32 v[50:51], v[246:247], v[210:211], v[50:51]
	v_max_f32_e32 v108, 0, v10
	v_max_f32_e32 v109, 0, v11
	v_pk_fma_f32 v[50:51], v[248:249], v[108:109], v[50:51]
	v_max_f32_e32 v210, 0, v12
	v_max_f32_e32 v211, 0, v13
	v_pk_fma_f32 v[50:51], v[250:251], v[210:211], v[50:51]
	v_max_f32_e32 v108, 0, v14
	v_max_f32_e32 v109, 0, v15
	v_pk_fma_f32 v[50:51], v[252:253], v[108:109], v[50:51]
	v_max_f32_e32 v210, 0, v16
	v_max_f32_e32 v211, 0, v17
	v_pk_fma_f32 v[50:51], v[254:255], v[210:211], v[50:51]
	v_max_f32_e32 v108, 0, v18
	v_max_f32_e32 v109, 0, v19
	v_pk_fma_f32 v[50:51], v[200:201], v[108:109], v[50:51]
	v_max_f32_e32 v210, 0, v20
	v_max_f32_e32 v211, 0, v21
	v_pk_fma_f32 v[50:51], v[202:203], v[210:211], v[50:51]
	v_add_f32_e32 v50, v50, v51
	v_ashrrev_i32_e32 v51, 31, v50
	v_or_b32_e32 v51, 0x80000000, v51
	v_xor_b32_e32 v50, v51, v50
	v_cndmask_b32_e32 v50, v123, v50, vcc
	global_store_dword v243, v50, s[8:9] offset:2048
	s_add_u32 s8, s8, 0x1000
	s_addc_u32 s9, s9, 0
	v_mfma_f32_32x32x16_bf16 v[6:21], v[86:89], v[38:41], 0
	v_mfma_f32_32x32x16_bf16 v[6:21], v[90:93], v[42:45], v[6:21]
	v_mfma_f32_32x32x16_bf16 v[6:21], v[94:97], v[46:49], v[6:21]
	v_mfma_f32_32x32x16_bf16 v[6:21], v[98:101], v[196:199], v[6:21]
	s_cmpk_gt_i32 s11, 240
	s_cselect_b64 vcc, -1, 0
	v_max_f32_e32 v108, 0, v212
	v_max_f32_e32 v109, 0, v213
	v_pk_mul_f32 v[0:1], v[22:23], v[108:109]
	v_max_f32_e32 v210, 0, v214
	v_max_f32_e32 v211, 0, v215
	v_pk_fma_f32 v[0:1], v[24:25], v[210:211], v[0:1]
	v_max_f32_e32 v108, 0, v216
	v_max_f32_e32 v109, 0, v217
	v_pk_fma_f32 v[0:1], v[26:27], v[108:109], v[0:1]
	v_max_f32_e32 v210, 0, v218
	v_max_f32_e32 v211, 0, v219
	v_pk_fma_f32 v[0:1], v[28:29], v[210:211], v[0:1]
	v_max_f32_e32 v108, 0, v220
	v_max_f32_e32 v109, 0, v221
	v_pk_fma_f32 v[0:1], v[30:31], v[108:109], v[0:1]
	v_max_f32_e32 v210, 0, v222
	v_max_f32_e32 v211, 0, v223
	v_pk_fma_f32 v[0:1], v[32:33], v[210:211], v[0:1]
	v_max_f32_e32 v108, 0, v224
	v_max_f32_e32 v109, 0, v225
	v_pk_fma_f32 v[0:1], v[34:35], v[108:109], v[0:1]
	v_max_f32_e32 v210, 0, v226
	v_max_f32_e32 v211, 0, v227
	v_pk_fma_f32 v[0:1], v[36:37], v[210:211], v[0:1]
	v_add_f32_e32 v0, v0, v1
	v_ashrrev_i32_e32 v1, 31, v0
	v_or_b32_e32 v1, 0x80000000, v1
	v_xor_b32_e32 v0, v1, v0
	v_cndmask_b32_e32 v163, v123, v0, vcc
	s_add_i32 m0, s10, 65536
	s_nop 0
	global_load_lds_dwordx4 v102, s[6:7]
	s_add_i32 m0, s10, 66560
	s_nop 0
	global_load_lds_dwordx4 v110, s[6:7]
	s_add_i32 m0, s10, 67584
	s_nop 0
	global_load_lds_dwordx4 v112, s[6:7]
	s_add_i32 m0, s10, 68608
	s_nop 0
	global_load_lds_dwordx4 v193, s[6:7]
	s_add_u32 s6, s6, 0x8000
	s_addc_u32 s7, s7, 0
	s_waitcnt vmcnt(15)
	v_add_u32_e32 v228, 0x10000, v5
	ds_read_b128 v[38:41], v228 offset:43264
	v_add_u32_e32 v228, 0x10000, v52
	ds_read_b128 v[42:45], v228 offset:43264
	v_add_u32_e32 v228, 0x10000, v55
	ds_read_b128 v[46:49], v228 offset:43264
	v_add_u32_e32 v228, 0x10000, v56
	ds_read_b128 v[196:199], v228 offset:43264
	s_waitcnt lgkmcnt(3)
	v_mfma_f32_32x32x16_bf16 v[212:227], v[70:73], v[38:41], 0
	s_waitcnt lgkmcnt(2)
	v_mfma_f32_32x32x16_bf16 v[212:227], v[74:77], v[42:45], v[212:227]
	s_waitcnt lgkmcnt(1)
	v_mfma_f32_32x32x16_bf16 v[212:227], v[78:81], v[46:49], v[212:227]
	s_waitcnt lgkmcnt(0)
	v_mfma_f32_32x32x16_bf16 v[212:227], v[82:85], v[196:199], v[212:227]
	s_cmpk_gt_i32 s11, 240
	s_cselect_b64 vcc, -1, 0
	v_max_f32_e32 v108, 0, v6
	v_max_f32_e32 v109, 0, v7
	v_pk_mul_f32 v[50:51], v[244:245], v[108:109]
	v_max_f32_e32 v210, 0, v8
	v_max_f32_e32 v211, 0, v9
	v_pk_fma_f32 v[50:51], v[246:247], v[210:211], v[50:51]
	v_max_f32_e32 v108, 0, v10
	v_max_f32_e32 v109, 0, v11
	v_pk_fma_f32 v[50:51], v[248:249], v[108:109], v[50:51]
	v_max_f32_e32 v210, 0, v12
	v_max_f32_e32 v211, 0, v13
	v_pk_fma_f32 v[50:51], v[250:251], v[210:211], v[50:51]
	v_max_f32_e32 v108, 0, v14
	v_max_f32_e32 v109, 0, v15
	v_pk_fma_f32 v[50:51], v[252:253], v[108:109], v[50:51]
	v_max_f32_e32 v210, 0, v16
	v_max_f32_e32 v211, 0, v17
	v_pk_fma_f32 v[50:51], v[254:255], v[210:211], v[50:51]
	v_max_f32_e32 v108, 0, v18
	v_max_f32_e32 v109, 0, v19
	v_pk_fma_f32 v[50:51], v[200:201], v[108:109], v[50:51]
	v_max_f32_e32 v210, 0, v20
	v_max_f32_e32 v211, 0, v21
	v_pk_fma_f32 v[50:51], v[202:203], v[210:211], v[50:51]
	v_add_f32_e32 v50, v50, v51
	v_ashrrev_i32_e32 v51, 31, v50
	v_or_b32_e32 v51, 0x80000000, v51
	v_xor_b32_e32 v50, v51, v50
	v_cndmask_b32_e32 v50, v123, v50, vcc
	global_store_dword v243, v50, s[8:9]
	v_mfma_f32_32x32x16_bf16 v[6:21], v[86:89], v[38:41], 0
	v_mfma_f32_32x32x16_bf16 v[6:21], v[90:93], v[42:45], v[6:21]
	v_mfma_f32_32x32x16_bf16 v[6:21], v[94:97], v[46:49], v[6:21]
	v_mfma_f32_32x32x16_bf16 v[6:21], v[98:101], v[196:199], v[6:21]
	s_cmpk_gt_i32 s11, 248
	s_cselect_b64 vcc, -1, 0
	v_max_f32_e32 v108, 0, v212
	v_max_f32_e32 v109, 0, v213
	v_pk_mul_f32 v[0:1], v[22:23], v[108:109]
	v_max_f32_e32 v210, 0, v214
	v_max_f32_e32 v211, 0, v215
	v_pk_fma_f32 v[0:1], v[24:25], v[210:211], v[0:1]
	v_max_f32_e32 v108, 0, v216
	v_max_f32_e32 v109, 0, v217
	v_pk_fma_f32 v[0:1], v[26:27], v[108:109], v[0:1]
	v_max_f32_e32 v210, 0, v218
	v_max_f32_e32 v211, 0, v219
	v_pk_fma_f32 v[0:1], v[28:29], v[210:211], v[0:1]
	v_max_f32_e32 v108, 0, v220
	v_max_f32_e32 v109, 0, v221
	v_pk_fma_f32 v[0:1], v[30:31], v[108:109], v[0:1]
	v_max_f32_e32 v210, 0, v222
	v_max_f32_e32 v211, 0, v223
	v_pk_fma_f32 v[0:1], v[32:33], v[210:211], v[0:1]
	v_max_f32_e32 v108, 0, v224
	v_max_f32_e32 v109, 0, v225
	v_pk_fma_f32 v[0:1], v[34:35], v[108:109], v[0:1]
	v_max_f32_e32 v210, 0, v226
	v_max_f32_e32 v211, 0, v227
	v_pk_fma_f32 v[0:1], v[36:37], v[210:211], v[0:1]
	v_add_f32_e32 v0, v0, v1
	v_ashrrev_i32_e32 v1, 31, v0
	v_or_b32_e32 v1, 0x80000000, v1
	v_xor_b32_e32 v0, v1, v0
	v_cndmask_b32_e32 v152, v123, v0, vcc
	v_max_f32_e32 v108, 0, v6
	v_max_f32_e32 v109, 0, v7
	v_pk_mul_f32 v[50:51], v[244:245], v[108:109]
	v_max_f32_e32 v210, 0, v8
	v_max_f32_e32 v211, 0, v9
	v_pk_fma_f32 v[50:51], v[246:247], v[210:211], v[50:51]
	v_max_f32_e32 v108, 0, v10
	v_max_f32_e32 v109, 0, v11
	v_pk_fma_f32 v[50:51], v[248:249], v[108:109], v[50:51]
	v_max_f32_e32 v210, 0, v12
	v_max_f32_e32 v211, 0, v13
	v_pk_fma_f32 v[50:51], v[250:251], v[210:211], v[50:51]
	v_max_f32_e32 v108, 0, v14
	v_max_f32_e32 v109, 0, v15
	v_pk_fma_f32 v[50:51], v[252:253], v[108:109], v[50:51]
	v_max_f32_e32 v210, 0, v16
	v_max_f32_e32 v211, 0, v17
	v_pk_fma_f32 v[50:51], v[254:255], v[210:211], v[50:51]
	v_max_f32_e32 v108, 0, v18
	v_max_f32_e32 v109, 0, v19
	v_pk_fma_f32 v[50:51], v[200:201], v[108:109], v[50:51]
	v_max_f32_e32 v210, 0, v20
	v_max_f32_e32 v211, 0, v21
	v_pk_fma_f32 v[50:51], v[202:203], v[210:211], v[50:51]
	v_add_f32_e32 v50, v50, v51
	v_ashrrev_i32_e32 v51, 31, v50
	v_or_b32_e32 v51, 0x80000000, v51
	v_xor_b32_e32 v50, v51, v50
	v_cndmask_b32_e32 v50, v123, v50, vcc
	global_store_dword v243, v50, s[8:9] offset:2048
	s_add_u32 s8, s8, 0x1000
	s_addc_u32 s9, s9, 0
	s_cmpk_gt_i32 s81, 32
	s_cbranch_scc0 .Lix_fill_4
	s_add_i32 m0, s10, 98304
	s_nop 0
	global_load_lds_dwordx4 v102, s[6:7]
	s_add_i32 m0, s10, 99328
	s_nop 0
	global_load_lds_dwordx4 v110, s[6:7]
	s_add_i32 m0, s10, 100352
	s_nop 0
	global_load_lds_dwordx4 v112, s[6:7]
	s_add_i32 m0, s10, 101376
	s_nop 0
	global_load_lds_dwordx4 v193, s[6:7]
	s_add_u32 s6, s6, 0x8000
	s_addc_u32 s7, s7, 0
	s_waitcnt vmcnt(16)
	ds_read_b128 v[38:41], v5 offset:10496
	ds_read_b128 v[42:45], v52 offset:10496
	ds_read_b128 v[46:49], v55 offset:10496
	ds_read_b128 v[196:199], v56 offset:10496
	s_waitcnt lgkmcnt(3)
	v_mfma_f32_32x32x16_bf16 v[212:227], v[70:73], v[38:41], 0
	s_waitcnt lgkmcnt(2)
	v_mfma_f32_32x32x16_bf16 v[212:227], v[74:77], v[42:45], v[212:227]
	s_waitcnt lgkmcnt(1)
	v_mfma_f32_32x32x16_bf16 v[212:227], v[78:81], v[46:49], v[212:227]
	s_waitcnt lgkmcnt(0)
	v_mfma_f32_32x32x16_bf16 v[212:227], v[82:85], v[196:199], v[212:227]
	v_mfma_f32_32x32x16_bf16 v[6:21], v[86:89], v[38:41], 0
	v_mfma_f32_32x32x16_bf16 v[6:21], v[90:93], v[42:45], v[6:21]
	v_mfma_f32_32x32x16_bf16 v[6:21], v[94:97], v[46:49], v[6:21]
	v_mfma_f32_32x32x16_bf16 v[6:21], v[98:101], v[196:199], v[6:21]
	s_nop 7
	s_cmpk_gt_i32 s11, 256
	s_cselect_b64 vcc, -1, 0
	v_max_f32_e32 v108, 0, v212
	v_max_f32_e32 v109, 0, v213
	v_pk_mul_f32 v[0:1], v[22:23], v[108:109]
	v_max_f32_e32 v210, 0, v214
	v_max_f32_e32 v211, 0, v215
	v_pk_fma_f32 v[0:1], v[24:25], v[210:211], v[0:1]
	v_max_f32_e32 v108, 0, v216
	v_max_f32_e32 v109, 0, v217
	v_pk_fma_f32 v[0:1], v[26:27], v[108:109], v[0:1]
	v_max_f32_e32 v210, 0, v218
	v_max_f32_e32 v211, 0, v219
	v_pk_fma_f32 v[0:1], v[28:29], v[210:211], v[0:1]
	v_max_f32_e32 v108, 0, v220
	v_max_f32_e32 v109, 0, v221
	v_pk_fma_f32 v[0:1], v[30:31], v[108:109], v[0:1]
	v_max_f32_e32 v210, 0, v222
	v_max_f32_e32 v211, 0, v223
	v_pk_fma_f32 v[0:1], v[32:33], v[210:211], v[0:1]
	v_max_f32_e32 v108, 0, v224
	v_max_f32_e32 v109, 0, v225
	v_pk_fma_f32 v[0:1], v[34:35], v[108:109], v[0:1]
	v_max_f32_e32 v210, 0, v226
	v_max_f32_e32 v211, 0, v227
	v_pk_fma_f32 v[0:1], v[36:37], v[210:211], v[0:1]
	v_add_f32_e32 v0, v0, v1
	v_ashrrev_i32_e32 v1, 31, v0
	v_or_b32_e32 v1, 0x80000000, v1
	v_xor_b32_e32 v0, v1, v0
	v_cndmask_b32_e32 v165, v123, v0, vcc
	s_add_i32 m0, s10, 0
	s_nop 0
	global_load_lds_dwordx4 v102, s[6:7]
	s_add_i32 m0, s10, 1024
	s_nop 0
	global_load_lds_dwordx4 v110, s[6:7]
	s_add_i32 m0, s10, 2048
	s_nop 0
	global_load_lds_dwordx4 v112, s[6:7]
	s_add_i32 m0, s10, 3072
	s_nop 0
	global_load_lds_dwordx4 v193, s[6:7]
	s_add_u32 s6, s6, 0x8000
	s_addc_u32 s7, s7, 0
	s_waitcnt vmcnt(15)
	ds_read_b128 v[38:41], v5 offset:43264
	ds_read_b128 v[42:45], v52 offset:43264
	ds_read_b128 v[46:49], v55 offset:43264
	ds_read_b128 v[196:199], v56 offset:43264
	s_waitcnt lgkmcnt(3)
	v_mfma_f32_32x32x16_bf16 v[212:227], v[70:73], v[38:41], 0
	s_waitcnt lgkmcnt(2)
	v_mfma_f32_32x32x16_bf16 v[212:227], v[74:77], v[42:45], v[212:227]
	s_waitcnt lgkmcnt(1)
	v_mfma_f32_32x32x16_bf16 v[212:227], v[78:81], v[46:49], v[212:227]
	s_waitcnt lgkmcnt(0)
	v_mfma_f32_32x32x16_bf16 v[212:227], v[82:85], v[196:199], v[212:227]
	s_cmpk_gt_i32 s11, 256
	s_cselect_b64 vcc, -1, 0
	v_max_f32_e32 v108, 0, v6
	v_max_f32_e32 v109, 0, v7
	v_pk_mul_f32 v[50:51], v[244:245], v[108:109]
	v_max_f32_e32 v210, 0, v8
	v_max_f32_e32 v211, 0, v9
	v_pk_fma_f32 v[50:51], v[246:247], v[210:211], v[50:51]
	v_max_f32_e32 v108, 0, v10
	v_max_f32_e32 v109, 0, v11
	v_pk_fma_f32 v[50:51], v[248:249], v[108:109], v[50:51]
	v_max_f32_e32 v210, 0, v12
	v_max_f32_e32 v211, 0, v13
	v_pk_fma_f32 v[50:51], v[250:251], v[210:211], v[50:51]
	v_max_f32_e32 v108, 0, v14
	v_max_f32_e32 v109, 0, v15
	v_pk_fma_f32 v[50:51], v[252:253], v[108:109], v[50:51]
	v_max_f32_e32 v210, 0, v16
	v_max_f32_e32 v211, 0, v17
	v_pk_fma_f32 v[50:51], v[254:255], v[210:211], v[50:51]
	v_max_f32_e32 v108, 0, v18
	v_max_f32_e32 v109, 0, v19
	v_pk_fma_f32 v[50:51], v[200:201], v[108:109], v[50:51]
	v_max_f32_e32 v210, 0, v20
	v_max_f32_e32 v211, 0, v21
	v_pk_fma_f32 v[50:51], v[202:203], v[210:211], v[50:51]
	v_add_f32_e32 v50, v50, v51
	v_ashrrev_i32_e32 v51, 31, v50
	v_or_b32_e32 v51, 0x80000000, v51
	v_xor_b32_e32 v50, v51, v50
	v_cndmask_b32_e32 v50, v123, v50, vcc
	global_store_dword v243, v50, s[8:9]
	v_mfma_f32_32x32x16_bf16 v[6:21], v[86:89], v[38:41], 0
	v_mfma_f32_32x32x16_bf16 v[6:21], v[90:93], v[42:45], v[6:21]
	v_mfma_f32_32x32x16_bf16 v[6:21], v[94:97], v[46:49], v[6:21]
	v_mfma_f32_32x32x16_bf16 v[6:21], v[98:101], v[196:199], v[6:21]
	s_cmpk_gt_i32 s11, 264
	s_cselect_b64 vcc, -1, 0
	v_max_f32_e32 v108, 0, v212
	v_max_f32_e32 v109, 0, v213
	v_pk_mul_f32 v[0:1], v[22:23], v[108:109]
	v_max_f32_e32 v210, 0, v214
	v_max_f32_e32 v211, 0, v215
	v_pk_fma_f32 v[0:1], v[24:25], v[210:211], v[0:1]
	v_max_f32_e32 v108, 0, v216
	v_max_f32_e32 v109, 0, v217
	v_pk_fma_f32 v[0:1], v[26:27], v[108:109], v[0:1]
	v_max_f32_e32 v210, 0, v218
	v_max_f32_e32 v211, 0, v219
	v_pk_fma_f32 v[0:1], v[28:29], v[210:211], v[0:1]
	v_max_f32_e32 v108, 0, v220
	v_max_f32_e32 v109, 0, v221
	v_pk_fma_f32 v[0:1], v[30:31], v[108:109], v[0:1]
	v_max_f32_e32 v210, 0, v222
	v_max_f32_e32 v211, 0, v223
	v_pk_fma_f32 v[0:1], v[32:33], v[210:211], v[0:1]
	v_max_f32_e32 v108, 0, v224
	v_max_f32_e32 v109, 0, v225
	v_pk_fma_f32 v[0:1], v[34:35], v[108:109], v[0:1]
	v_max_f32_e32 v210, 0, v226
	v_max_f32_e32 v211, 0, v227
	v_pk_fma_f32 v[0:1], v[36:37], v[210:211], v[0:1]
	v_add_f32_e32 v0, v0, v1
	v_ashrrev_i32_e32 v1, 31, v0
	v_or_b32_e32 v1, 0x80000000, v1
	v_xor_b32_e32 v0, v1, v0
	v_cndmask_b32_e32 v164, v123, v0, vcc
	s_add_i32 m0, s10, 32768
	s_nop 0
	global_load_lds_dwordx4 v102, s[6:7]
	s_add_i32 m0, s10, 33792
	s_nop 0
	global_load_lds_dwordx4 v110, s[6:7]
	s_add_i32 m0, s10, 34816
	s_nop 0
	global_load_lds_dwordx4 v112, s[6:7]
	s_add_i32 m0, s10, 35840
	s_nop 0
	global_load_lds_dwordx4 v193, s[6:7]
	s_add_u32 s6, s6, 0x8000
	s_addc_u32 s7, s7, 0
	s_waitcnt vmcnt(15)
	v_add_u32_e32 v228, 0x10000, v5
	ds_read_b128 v[38:41], v228 offset:10496
	v_add_u32_e32 v228, 0x10000, v52
	ds_read_b128 v[42:45], v228 offset:10496
	v_add_u32_e32 v228, 0x10000, v55
	ds_read_b128 v[46:49], v228 offset:10496
	v_add_u32_e32 v228, 0x10000, v56
	ds_read_b128 v[196:199], v228 offset:10496
	s_waitcnt lgkmcnt(3)
	v_mfma_f32_32x32x16_bf16 v[212:227], v[70:73], v[38:41], 0
	s_waitcnt lgkmcnt(2)
	v_mfma_f32_32x32x16_bf16 v[212:227], v[74:77], v[42:45], v[212:227]
	s_waitcnt lgkmcnt(1)
	v_mfma_f32_32x32x16_bf16 v[212:227], v[78:81], v[46:49], v[212:227]
	s_waitcnt lgkmcnt(0)
	v_mfma_f32_32x32x16_bf16 v[212:227], v[82:85], v[196:199], v[212:227]
	s_cmpk_gt_i32 s11, 264
	s_cselect_b64 vcc, -1, 0
	v_max_f32_e32 v108, 0, v6
	v_max_f32_e32 v109, 0, v7
	v_pk_mul_f32 v[50:51], v[244:245], v[108:109]
	v_max_f32_e32 v210, 0, v8
	v_max_f32_e32 v211, 0, v9
	v_pk_fma_f32 v[50:51], v[246:247], v[210:211], v[50:51]
	v_max_f32_e32 v108, 0, v10
	v_max_f32_e32 v109, 0, v11
	v_pk_fma_f32 v[50:51], v[248:249], v[108:109], v[50:51]
	v_max_f32_e32 v210, 0, v12
	v_max_f32_e32 v211, 0, v13
	v_pk_fma_f32 v[50:51], v[250:251], v[210:211], v[50:51]
	v_max_f32_e32 v108, 0, v14
	v_max_f32_e32 v109, 0, v15
	v_pk_fma_f32 v[50:51], v[252:253], v[108:109], v[50:51]
	v_max_f32_e32 v210, 0, v16
	v_max_f32_e32 v211, 0, v17
	v_pk_fma_f32 v[50:51], v[254:255], v[210:211], v[50:51]
	v_max_f32_e32 v108, 0, v18
	v_max_f32_e32 v109, 0, v19
	v_pk_fma_f32 v[50:51], v[200:201], v[108:109], v[50:51]
	v_max_f32_e32 v210, 0, v20
	v_max_f32_e32 v211, 0, v21
	v_pk_fma_f32 v[50:51], v[202:203], v[210:211], v[50:51]
	v_add_f32_e32 v50, v50, v51
	v_ashrrev_i32_e32 v51, 31, v50
	v_or_b32_e32 v51, 0x80000000, v51
	v_xor_b32_e32 v50, v51, v50
	v_cndmask_b32_e32 v50, v123, v50, vcc
	global_store_dword v243, v50, s[8:9] offset:2048
	s_add_u32 s8, s8, 0x1000
	s_addc_u32 s9, s9, 0
	v_mfma_f32_32x32x16_bf16 v[6:21], v[86:89], v[38:41], 0
	v_mfma_f32_32x32x16_bf16 v[6:21], v[90:93], v[42:45], v[6:21]
	v_mfma_f32_32x32x16_bf16 v[6:21], v[94:97], v[46:49], v[6:21]
	v_mfma_f32_32x32x16_bf16 v[6:21], v[98:101], v[196:199], v[6:21]
	s_cmpk_gt_i32 s11, 272
	s_cselect_b64 vcc, -1, 0
	v_max_f32_e32 v108, 0, v212
	v_max_f32_e32 v109, 0, v213
	v_pk_mul_f32 v[0:1], v[22:23], v[108:109]
	v_max_f32_e32 v210, 0, v214
	v_max_f32_e32 v211, 0, v215
	v_pk_fma_f32 v[0:1], v[24:25], v[210:211], v[0:1]
	v_max_f32_e32 v108, 0, v216
	v_max_f32_e32 v109, 0, v217
	v_pk_fma_f32 v[0:1], v[26:27], v[108:109], v[0:1]
	v_max_f32_e32 v210, 0, v218
	v_max_f32_e32 v211, 0, v219
	v_pk_fma_f32 v[0:1], v[28:29], v[210:211], v[0:1]
	v_max_f32_e32 v108, 0, v220
	v_max_f32_e32 v109, 0, v221
	v_pk_fma_f32 v[0:1], v[30:31], v[108:109], v[0:1]
	v_max_f32_e32 v210, 0, v222
	v_max_f32_e32 v211, 0, v223
	v_pk_fma_f32 v[0:1], v[32:33], v[210:211], v[0:1]
	v_max_f32_e32 v108, 0, v224
	v_max_f32_e32 v109, 0, v225
	v_pk_fma_f32 v[0:1], v[34:35], v[108:109], v[0:1]
	v_max_f32_e32 v210, 0, v226
	v_max_f32_e32 v211, 0, v227
	v_pk_fma_f32 v[0:1], v[36:37], v[210:211], v[0:1]
	v_add_f32_e32 v0, v0, v1
	v_ashrrev_i32_e32 v1, 31, v0
	v_or_b32_e32 v1, 0x80000000, v1
	v_xor_b32_e32 v0, v1, v0
	v_cndmask_b32_e32 v167, v123, v0, vcc
	s_add_i32 m0, s10, 65536
	s_nop 0
	global_load_lds_dwordx4 v102, s[6:7]
	s_add_i32 m0, s10, 66560
	s_nop 0
	global_load_lds_dwordx4 v110, s[6:7]
	s_add_i32 m0, s10, 67584
	s_nop 0
	global_load_lds_dwordx4 v112, s[6:7]
	s_add_i32 m0, s10, 68608
	s_nop 0
	global_load_lds_dwordx4 v193, s[6:7]
	s_add_u32 s6, s6, 0x8000
	s_addc_u32 s7, s7, 0
	s_waitcnt vmcnt(14)
	v_add_u32_e32 v228, 0x10000, v5
	ds_read_b128 v[38:41], v228 offset:43264
	v_add_u32_e32 v228, 0x10000, v52
	ds_read_b128 v[42:45], v228 offset:43264
	v_add_u32_e32 v228, 0x10000, v55
	ds_read_b128 v[46:49], v228 offset:43264
	v_add_u32_e32 v228, 0x10000, v56
	ds_read_b128 v[196:199], v228 offset:43264
	s_waitcnt lgkmcnt(3)
	v_mfma_f32_32x32x16_bf16 v[212:227], v[70:73], v[38:41], 0
	s_waitcnt lgkmcnt(2)
	v_mfma_f32_32x32x16_bf16 v[212:227], v[74:77], v[42:45], v[212:227]
	s_waitcnt lgkmcnt(1)
	v_mfma_f32_32x32x16_bf16 v[212:227], v[78:81], v[46:49], v[212:227]
	s_waitcnt lgkmcnt(0)
	v_mfma_f32_32x32x16_bf16 v[212:227], v[82:85], v[196:199], v[212:227]
	s_cmpk_gt_i32 s11, 272
	s_cselect_b64 vcc, -1, 0
	v_max_f32_e32 v108, 0, v6
	v_max_f32_e32 v109, 0, v7
	v_pk_mul_f32 v[50:51], v[244:245], v[108:109]
	v_max_f32_e32 v210, 0, v8
	v_max_f32_e32 v211, 0, v9
	v_pk_fma_f32 v[50:51], v[246:247], v[210:211], v[50:51]
	v_max_f32_e32 v108, 0, v10
	v_max_f32_e32 v109, 0, v11
	v_pk_fma_f32 v[50:51], v[248:249], v[108:109], v[50:51]
	v_max_f32_e32 v210, 0, v12
	v_max_f32_e32 v211, 0, v13
	v_pk_fma_f32 v[50:51], v[250:251], v[210:211], v[50:51]
	v_max_f32_e32 v108, 0, v14
	v_max_f32_e32 v109, 0, v15
	v_pk_fma_f32 v[50:51], v[252:253], v[108:109], v[50:51]
	v_max_f32_e32 v210, 0, v16
	v_max_f32_e32 v211, 0, v17
	v_pk_fma_f32 v[50:51], v[254:255], v[210:211], v[50:51]
	v_max_f32_e32 v108, 0, v18
	v_max_f32_e32 v109, 0, v19
	v_pk_fma_f32 v[50:51], v[200:201], v[108:109], v[50:51]
	v_max_f32_e32 v210, 0, v20
	v_max_f32_e32 v211, 0, v21
	v_pk_fma_f32 v[50:51], v[202:203], v[210:211], v[50:51]
	v_add_f32_e32 v50, v50, v51
	v_ashrrev_i32_e32 v51, 31, v50
	v_or_b32_e32 v51, 0x80000000, v51
	v_xor_b32_e32 v50, v51, v50
	v_cndmask_b32_e32 v50, v123, v50, vcc
	global_store_dword v243, v50, s[8:9]
	v_mfma_f32_32x32x16_bf16 v[6:21], v[86:89], v[38:41], 0
	v_mfma_f32_32x32x16_bf16 v[6:21], v[90:93], v[42:45], v[6:21]
	v_mfma_f32_32x32x16_bf16 v[6:21], v[94:97], v[46:49], v[6:21]
	v_mfma_f32_32x32x16_bf16 v[6:21], v[98:101], v[196:199], v[6:21]
	s_cmpk_gt_i32 s11, 280
	s_cselect_b64 vcc, -1, 0
	v_max_f32_e32 v108, 0, v212
	v_max_f32_e32 v109, 0, v213
	v_pk_mul_f32 v[0:1], v[22:23], v[108:109]
	v_max_f32_e32 v210, 0, v214
	v_max_f32_e32 v211, 0, v215
	v_pk_fma_f32 v[0:1], v[24:25], v[210:211], v[0:1]
	v_max_f32_e32 v108, 0, v216
	v_max_f32_e32 v109, 0, v217
	v_pk_fma_f32 v[0:1], v[26:27], v[108:109], v[0:1]
	v_max_f32_e32 v210, 0, v218
	v_max_f32_e32 v211, 0, v219
	v_pk_fma_f32 v[0:1], v[28:29], v[210:211], v[0:1]
	v_max_f32_e32 v108, 0, v220
	v_max_f32_e32 v109, 0, v221
	v_pk_fma_f32 v[0:1], v[30:31], v[108:109], v[0:1]
	v_max_f32_e32 v210, 0, v222
	v_max_f32_e32 v211, 0, v223
	v_pk_fma_f32 v[0:1], v[32:33], v[210:211], v[0:1]
	v_max_f32_e32 v108, 0, v224
	v_max_f32_e32 v109, 0, v225
	v_pk_fma_f32 v[0:1], v[34:35], v[108:109], v[0:1]
	v_max_f32_e32 v210, 0, v226
	v_max_f32_e32 v211, 0, v227
	v_pk_fma_f32 v[0:1], v[36:37], v[210:211], v[0:1]
	v_add_f32_e32 v0, v0, v1
	v_ashrrev_i32_e32 v1, 31, v0
	v_or_b32_e32 v1, 0x80000000, v1
	v_xor_b32_e32 v0, v1, v0
	v_cndmask_b32_e32 v166, v123, v0, vcc
	s_add_i32 m0, s10, 98304
	s_nop 0
	global_load_lds_dwordx4 v102, s[6:7]
	s_add_i32 m0, s10, 99328
	s_nop 0
	global_load_lds_dwordx4 v110, s[6:7]
	s_add_i32 m0, s10, 100352
	s_nop 0
	global_load_lds_dwordx4 v112, s[6:7]
	s_add_i32 m0, s10, 101376
	s_nop 0
	global_load_lds_dwordx4 v193, s[6:7]
	s_add_u32 s6, s6, 0x8000
	s_addc_u32 s7, s7, 0
	s_waitcnt vmcnt(15)
	ds_read_b128 v[38:41], v5 offset:10496
	ds_read_b128 v[42:45], v52 offset:10496
	ds_read_b128 v[46:49], v55 offset:10496
	ds_read_b128 v[196:199], v56 offset:10496
	s_waitcnt lgkmcnt(3)
	v_mfma_f32_32x32x16_bf16 v[212:227], v[70:73], v[38:41], 0
	s_waitcnt lgkmcnt(2)
	v_mfma_f32_32x32x16_bf16 v[212:227], v[74:77], v[42:45], v[212:227]
	s_waitcnt lgkmcnt(1)
	v_mfma_f32_32x32x16_bf16 v[212:227], v[78:81], v[46:49], v[212:227]
	s_waitcnt lgkmcnt(0)
	v_mfma_f32_32x32x16_bf16 v[212:227], v[82:85], v[196:199], v[212:227]
	s_cmpk_gt_i32 s11, 280
	s_cselect_b64 vcc, -1, 0
	v_max_f32_e32 v108, 0, v6
	v_max_f32_e32 v109, 0, v7
	v_pk_mul_f32 v[50:51], v[244:245], v[108:109]
	v_max_f32_e32 v210, 0, v8
	v_max_f32_e32 v211, 0, v9
	v_pk_fma_f32 v[50:51], v[246:247], v[210:211], v[50:51]
	v_max_f32_e32 v108, 0, v10
	v_max_f32_e32 v109, 0, v11
	v_pk_fma_f32 v[50:51], v[248:249], v[108:109], v[50:51]
	v_max_f32_e32 v210, 0, v12
	v_max_f32_e32 v211, 0, v13
	v_pk_fma_f32 v[50:51], v[250:251], v[210:211], v[50:51]
	v_max_f32_e32 v108, 0, v14
	v_max_f32_e32 v109, 0, v15
	v_pk_fma_f32 v[50:51], v[252:253], v[108:109], v[50:51]
	v_max_f32_e32 v210, 0, v16
	v_max_f32_e32 v211, 0, v17
	v_pk_fma_f32 v[50:51], v[254:255], v[210:211], v[50:51]
	v_max_f32_e32 v108, 0, v18
	v_max_f32_e32 v109, 0, v19
	v_pk_fma_f32 v[50:51], v[200:201], v[108:109], v[50:51]
	v_max_f32_e32 v210, 0, v20
	v_max_f32_e32 v211, 0, v21
	v_pk_fma_f32 v[50:51], v[202:203], v[210:211], v[50:51]
	v_add_f32_e32 v50, v50, v51
	v_ashrrev_i32_e32 v51, 31, v50
	v_or_b32_e32 v51, 0x80000000, v51
	v_xor_b32_e32 v50, v51, v50
	v_cndmask_b32_e32 v50, v123, v50, vcc
	global_store_dword v243, v50, s[8:9] offset:2048
	s_add_u32 s8, s8, 0x1000
	s_addc_u32 s9, s9, 0
	v_mfma_f32_32x32x16_bf16 v[6:21], v[86:89], v[38:41], 0
	v_mfma_f32_32x32x16_bf16 v[6:21], v[90:93], v[42:45], v[6:21]
	v_mfma_f32_32x32x16_bf16 v[6:21], v[94:97], v[46:49], v[6:21]
	v_mfma_f32_32x32x16_bf16 v[6:21], v[98:101], v[196:199], v[6:21]
	s_cmpk_gt_i32 s11, 288
	s_cselect_b64 vcc, -1, 0
	v_max_f32_e32 v108, 0, v212
	v_max_f32_e32 v109, 0, v213
	v_pk_mul_f32 v[0:1], v[22:23], v[108:109]
	v_max_f32_e32 v210, 0, v214
	v_max_f32_e32 v211, 0, v215
	v_pk_fma_f32 v[0:1], v[24:25], v[210:211], v[0:1]
	v_max_f32_e32 v108, 0, v216
	v_max_f32_e32 v109, 0, v217
	v_pk_fma_f32 v[0:1], v[26:27], v[108:109], v[0:1]
	v_max_f32_e32 v210, 0, v218
	v_max_f32_e32 v211, 0, v219
	v_pk_fma_f32 v[0:1], v[28:29], v[210:211], v[0:1]
	v_max_f32_e32 v108, 0, v220
	v_max_f32_e32 v109, 0, v221
	v_pk_fma_f32 v[0:1], v[30:31], v[108:109], v[0:1]
	v_max_f32_e32 v210, 0, v222
	v_max_f32_e32 v211, 0, v223
	v_pk_fma_f32 v[0:1], v[32:33], v[210:211], v[0:1]
	v_max_f32_e32 v108, 0, v224
	v_max_f32_e32 v109, 0, v225
	v_pk_fma_f32 v[0:1], v[34:35], v[108:109], v[0:1]
	v_max_f32_e32 v210, 0, v226
	v_max_f32_e32 v211, 0, v227
	v_pk_fma_f32 v[0:1], v[36:37], v[210:211], v[0:1]
	v_add_f32_e32 v0, v0, v1
	v_ashrrev_i32_e32 v1, 31, v0
	v_or_b32_e32 v1, 0x80000000, v1
	v_xor_b32_e32 v0, v1, v0
	v_cndmask_b32_e32 v170, v123, v0, vcc
	s_add_i32 m0, s10, 0
	s_nop 0
	global_load_lds_dwordx4 v102, s[6:7]
	s_add_i32 m0, s10, 1024
	s_nop 0
	global_load_lds_dwordx4 v110, s[6:7]
	s_add_i32 m0, s10, 2048
	s_nop 0
	global_load_lds_dwordx4 v112, s[6:7]
	s_add_i32 m0, s10, 3072
	s_nop 0
	global_load_lds_dwordx4 v193, s[6:7]
	s_add_u32 s6, s6, 0x8000
	s_addc_u32 s7, s7, 0
	s_waitcnt vmcnt(15)
	ds_read_b128 v[38:41], v5 offset:43264
	ds_read_b128 v[42:45], v52 offset:43264
	ds_read_b128 v[46:49], v55 offset:43264
	ds_read_b128 v[196:199], v56 offset:43264
	s_waitcnt lgkmcnt(3)
	v_mfma_f32_32x32x16_bf16 v[212:227], v[70:73], v[38:41], 0
	s_waitcnt lgkmcnt(2)
	v_mfma_f32_32x32x16_bf16 v[212:227], v[74:77], v[42:45], v[212:227]
	s_waitcnt lgkmcnt(1)
	v_mfma_f32_32x32x16_bf16 v[212:227], v[78:81], v[46:49], v[212:227]
	s_waitcnt lgkmcnt(0)
	v_mfma_f32_32x32x16_bf16 v[212:227], v[82:85], v[196:199], v[212:227]
	s_cmpk_gt_i32 s11, 288
	s_cselect_b64 vcc, -1, 0
	v_max_f32_e32 v108, 0, v6
	v_max_f32_e32 v109, 0, v7
	v_pk_mul_f32 v[50:51], v[244:245], v[108:109]
	v_max_f32_e32 v210, 0, v8
	v_max_f32_e32 v211, 0, v9
	v_pk_fma_f32 v[50:51], v[246:247], v[210:211], v[50:51]
	v_max_f32_e32 v108, 0, v10
	v_max_f32_e32 v109, 0, v11
	v_pk_fma_f32 v[50:51], v[248:249], v[108:109], v[50:51]
	v_max_f32_e32 v210, 0, v12
	v_max_f32_e32 v211, 0, v13
	v_pk_fma_f32 v[50:51], v[250:251], v[210:211], v[50:51]
	v_max_f32_e32 v108, 0, v14
	v_max_f32_e32 v109, 0, v15
	v_pk_fma_f32 v[50:51], v[252:253], v[108:109], v[50:51]
	v_max_f32_e32 v210, 0, v16
	v_max_f32_e32 v211, 0, v17
	v_pk_fma_f32 v[50:51], v[254:255], v[210:211], v[50:51]
	v_max_f32_e32 v108, 0, v18
	v_max_f32_e32 v109, 0, v19
	v_pk_fma_f32 v[50:51], v[200:201], v[108:109], v[50:51]
	v_max_f32_e32 v210, 0, v20
	v_max_f32_e32 v211, 0, v21
	v_pk_fma_f32 v[50:51], v[202:203], v[210:211], v[50:51]
	v_add_f32_e32 v50, v50, v51
	v_ashrrev_i32_e32 v51, 31, v50
	v_or_b32_e32 v51, 0x80000000, v51
	v_xor_b32_e32 v50, v51, v50
	v_cndmask_b32_e32 v50, v123, v50, vcc
	global_store_dword v243, v50, s[8:9]
	v_mfma_f32_32x32x16_bf16 v[6:21], v[86:89], v[38:41], 0
	v_mfma_f32_32x32x16_bf16 v[6:21], v[90:93], v[42:45], v[6:21]
	v_mfma_f32_32x32x16_bf16 v[6:21], v[94:97], v[46:49], v[6:21]
	v_mfma_f32_32x32x16_bf16 v[6:21], v[98:101], v[196:199], v[6:21]
	s_cmpk_gt_i32 s11, 296
	s_cselect_b64 vcc, -1, 0
	v_max_f32_e32 v108, 0, v212
	v_max_f32_e32 v109, 0, v213
	v_pk_mul_f32 v[0:1], v[22:23], v[108:109]
	v_max_f32_e32 v210, 0, v214
	v_max_f32_e32 v211, 0, v215
	v_pk_fma_f32 v[0:1], v[24:25], v[210:211], v[0:1]
	v_max_f32_e32 v108, 0, v216
	v_max_f32_e32 v109, 0, v217
	v_pk_fma_f32 v[0:1], v[26:27], v[108:109], v[0:1]
	v_max_f32_e32 v210, 0, v218
	v_max_f32_e32 v211, 0, v219
	v_pk_fma_f32 v[0:1], v[28:29], v[210:211], v[0:1]
	v_max_f32_e32 v108, 0, v220
	v_max_f32_e32 v109, 0, v221
	v_pk_fma_f32 v[0:1], v[30:31], v[108:109], v[0:1]
	v_max_f32_e32 v210, 0, v222
	v_max_f32_e32 v211, 0, v223
	v_pk_fma_f32 v[0:1], v[32:33], v[210:211], v[0:1]
	v_max_f32_e32 v108, 0, v224
	v_max_f32_e32 v109, 0, v225
	v_pk_fma_f32 v[0:1], v[34:35], v[108:109], v[0:1]
	v_max_f32_e32 v210, 0, v226
	v_max_f32_e32 v211, 0, v227
	v_pk_fma_f32 v[0:1], v[36:37], v[210:211], v[0:1]
	v_add_f32_e32 v0, v0, v1
	v_ashrrev_i32_e32 v1, 31, v0
	v_or_b32_e32 v1, 0x80000000, v1
	v_xor_b32_e32 v0, v1, v0
	v_cndmask_b32_e32 v169, v123, v0, vcc
	s_add_i32 m0, s10, 32768
	s_nop 0
	global_load_lds_dwordx4 v102, s[6:7]
	s_add_i32 m0, s10, 33792
	s_nop 0
	global_load_lds_dwordx4 v110, s[6:7]
	s_add_i32 m0, s10, 34816
	s_nop 0
	global_load_lds_dwordx4 v112, s[6:7]
	s_add_i32 m0, s10, 35840
	s_nop 0
	global_load_lds_dwordx4 v193, s[6:7]
	s_add_u32 s6, s6, 0x8000
	s_addc_u32 s7, s7, 0
	s_waitcnt vmcnt(15)
	v_add_u32_e32 v228, 0x10000, v5
	ds_read_b128 v[38:41], v228 offset:10496
	v_add_u32_e32 v228, 0x10000, v52
	ds_read_b128 v[42:45], v228 offset:10496
	v_add_u32_e32 v228, 0x10000, v55
	ds_read_b128 v[46:49], v228 offset:10496
	v_add_u32_e32 v228, 0x10000, v56
	ds_read_b128 v[196:199], v228 offset:10496
	s_waitcnt lgkmcnt(3)
	v_mfma_f32_32x32x16_bf16 v[212:227], v[70:73], v[38:41], 0
	s_waitcnt lgkmcnt(2)
	v_mfma_f32_32x32x16_bf16 v[212:227], v[74:77], v[42:45], v[212:227]
	s_waitcnt lgkmcnt(1)
	v_mfma_f32_32x32x16_bf16 v[212:227], v[78:81], v[46:49], v[212:227]
	s_waitcnt lgkmcnt(0)
	v_mfma_f32_32x32x16_bf16 v[212:227], v[82:85], v[196:199], v[212:227]
	s_cmpk_gt_i32 s11, 296
	s_cselect_b64 vcc, -1, 0
	v_max_f32_e32 v108, 0, v6
	v_max_f32_e32 v109, 0, v7
	v_pk_mul_f32 v[50:51], v[244:245], v[108:109]
	v_max_f32_e32 v210, 0, v8
	v_max_f32_e32 v211, 0, v9
	v_pk_fma_f32 v[50:51], v[246:247], v[210:211], v[50:51]
	v_max_f32_e32 v108, 0, v10
	v_max_f32_e32 v109, 0, v11
	v_pk_fma_f32 v[50:51], v[248:249], v[108:109], v[50:51]
	v_max_f32_e32 v210, 0, v12
	v_max_f32_e32 v211, 0, v13
	v_pk_fma_f32 v[50:51], v[250:251], v[210:211], v[50:51]
	v_max_f32_e32 v108, 0, v14
	v_max_f32_e32 v109, 0, v15
	v_pk_fma_f32 v[50:51], v[252:253], v[108:109], v[50:51]
	v_max_f32_e32 v210, 0, v16
	v_max_f32_e32 v211, 0, v17
	v_pk_fma_f32 v[50:51], v[254:255], v[210:211], v[50:51]
	v_max_f32_e32 v108, 0, v18
	v_max_f32_e32 v109, 0, v19
	v_pk_fma_f32 v[50:51], v[200:201], v[108:109], v[50:51]
	v_max_f32_e32 v210, 0, v20
	v_max_f32_e32 v211, 0, v21
	v_pk_fma_f32 v[50:51], v[202:203], v[210:211], v[50:51]
	v_add_f32_e32 v50, v50, v51
	v_ashrrev_i32_e32 v51, 31, v50
	v_or_b32_e32 v51, 0x80000000, v51
	v_xor_b32_e32 v50, v51, v50
	v_cndmask_b32_e32 v50, v123, v50, vcc
	global_store_dword v243, v50, s[8:9] offset:2048
	s_add_u32 s8, s8, 0x1000
	s_addc_u32 s9, s9, 0
	v_mfma_f32_32x32x16_bf16 v[6:21], v[86:89], v[38:41], 0
	v_mfma_f32_32x32x16_bf16 v[6:21], v[90:93], v[42:45], v[6:21]
	v_mfma_f32_32x32x16_bf16 v[6:21], v[94:97], v[46:49], v[6:21]
	v_mfma_f32_32x32x16_bf16 v[6:21], v[98:101], v[196:199], v[6:21]
	s_cmpk_gt_i32 s11, 304
	s_cselect_b64 vcc, -1, 0
	v_max_f32_e32 v108, 0, v212
	v_max_f32_e32 v109, 0, v213
	v_pk_mul_f32 v[0:1], v[22:23], v[108:109]
	v_max_f32_e32 v210, 0, v214
	v_max_f32_e32 v211, 0, v215
	v_pk_fma_f32 v[0:1], v[24:25], v[210:211], v[0:1]
	v_max_f32_e32 v108, 0, v216
	v_max_f32_e32 v109, 0, v217
	v_pk_fma_f32 v[0:1], v[26:27], v[108:109], v[0:1]
	v_max_f32_e32 v210, 0, v218
	v_max_f32_e32 v211, 0, v219
	v_pk_fma_f32 v[0:1], v[28:29], v[210:211], v[0:1]
	v_max_f32_e32 v108, 0, v220
	v_max_f32_e32 v109, 0, v221
	v_pk_fma_f32 v[0:1], v[30:31], v[108:109], v[0:1]
	v_max_f32_e32 v210, 0, v222
	v_max_f32_e32 v211, 0, v223
	v_pk_fma_f32 v[0:1], v[32:33], v[210:211], v[0:1]
	v_max_f32_e32 v108, 0, v224
	v_max_f32_e32 v109, 0, v225
	v_pk_fma_f32 v[0:1], v[34:35], v[108:109], v[0:1]
	v_max_f32_e32 v210, 0, v226
	v_max_f32_e32 v211, 0, v227
	v_pk_fma_f32 v[0:1], v[36:37], v[210:211], v[0:1]
	v_add_f32_e32 v0, v0, v1
	v_ashrrev_i32_e32 v1, 31, v0
	v_or_b32_e32 v1, 0x80000000, v1
	v_xor_b32_e32 v0, v1, v0
	v_cndmask_b32_e32 v172, v123, v0, vcc
	s_add_i32 m0, s10, 65536
	s_nop 0
	global_load_lds_dwordx4 v102, s[6:7]
	s_add_i32 m0, s10, 66560
	s_nop 0
	global_load_lds_dwordx4 v110, s[6:7]
	s_add_i32 m0, s10, 67584
	s_nop 0
	global_load_lds_dwordx4 v112, s[6:7]
	s_add_i32 m0, s10, 68608
	s_nop 0
	global_load_lds_dwordx4 v193, s[6:7]
	s_add_u32 s6, s6, 0x8000
	s_addc_u32 s7, s7, 0
	s_waitcnt vmcnt(15)
	v_add_u32_e32 v228, 0x10000, v5
	ds_read_b128 v[38:41], v228 offset:43264
	v_add_u32_e32 v228, 0x10000, v52
	ds_read_b128 v[42:45], v228 offset:43264
	v_add_u32_e32 v228, 0x10000, v55
	ds_read_b128 v[46:49], v228 offset:43264
	v_add_u32_e32 v228, 0x10000, v56
	ds_read_b128 v[196:199], v228 offset:43264
	s_waitcnt lgkmcnt(3)
	v_mfma_f32_32x32x16_bf16 v[212:227], v[70:73], v[38:41], 0
	s_waitcnt lgkmcnt(2)
	v_mfma_f32_32x32x16_bf16 v[212:227], v[74:77], v[42:45], v[212:227]
	s_waitcnt lgkmcnt(1)
	v_mfma_f32_32x32x16_bf16 v[212:227], v[78:81], v[46:49], v[212:227]
	s_waitcnt lgkmcnt(0)
	v_mfma_f32_32x32x16_bf16 v[212:227], v[82:85], v[196:199], v[212:227]
	s_cmpk_gt_i32 s11, 304
	s_cselect_b64 vcc, -1, 0
	v_max_f32_e32 v108, 0, v6
	v_max_f32_e32 v109, 0, v7
	v_pk_mul_f32 v[50:51], v[244:245], v[108:109]
	v_max_f32_e32 v210, 0, v8
	v_max_f32_e32 v211, 0, v9
	v_pk_fma_f32 v[50:51], v[246:247], v[210:211], v[50:51]
	v_max_f32_e32 v108, 0, v10
	v_max_f32_e32 v109, 0, v11
	v_pk_fma_f32 v[50:51], v[248:249], v[108:109], v[50:51]
	v_max_f32_e32 v210, 0, v12
	v_max_f32_e32 v211, 0, v13
	v_pk_fma_f32 v[50:51], v[250:251], v[210:211], v[50:51]
	v_max_f32_e32 v108, 0, v14
	v_max_f32_e32 v109, 0, v15
	v_pk_fma_f32 v[50:51], v[252:253], v[108:109], v[50:51]
	v_max_f32_e32 v210, 0, v16
	v_max_f32_e32 v211, 0, v17
	v_pk_fma_f32 v[50:51], v[254:255], v[210:211], v[50:51]
	v_max_f32_e32 v108, 0, v18
	v_max_f32_e32 v109, 0, v19
	v_pk_fma_f32 v[50:51], v[200:201], v[108:109], v[50:51]
	v_max_f32_e32 v210, 0, v20
	v_max_f32_e32 v211, 0, v21
	v_pk_fma_f32 v[50:51], v[202:203], v[210:211], v[50:51]
	v_add_f32_e32 v50, v50, v51
	v_ashrrev_i32_e32 v51, 31, v50
	v_or_b32_e32 v51, 0x80000000, v51
	v_xor_b32_e32 v50, v51, v50
	v_cndmask_b32_e32 v50, v123, v50, vcc
	global_store_dword v243, v50, s[8:9]
	v_mfma_f32_32x32x16_bf16 v[6:21], v[86:89], v[38:41], 0
	v_mfma_f32_32x32x16_bf16 v[6:21], v[90:93], v[42:45], v[6:21]
	v_mfma_f32_32x32x16_bf16 v[6:21], v[94:97], v[46:49], v[6:21]
	v_mfma_f32_32x32x16_bf16 v[6:21], v[98:101], v[196:199], v[6:21]
	s_cmpk_gt_i32 s11, 312
	s_cselect_b64 vcc, -1, 0
	v_max_f32_e32 v108, 0, v212
	v_max_f32_e32 v109, 0, v213
	v_pk_mul_f32 v[0:1], v[22:23], v[108:109]
	v_max_f32_e32 v210, 0, v214
	v_max_f32_e32 v211, 0, v215
	v_pk_fma_f32 v[0:1], v[24:25], v[210:211], v[0:1]
	v_max_f32_e32 v108, 0, v216
	v_max_f32_e32 v109, 0, v217
	v_pk_fma_f32 v[0:1], v[26:27], v[108:109], v[0:1]
	v_max_f32_e32 v210, 0, v218
	v_max_f32_e32 v211, 0, v219
	v_pk_fma_f32 v[0:1], v[28:29], v[210:211], v[0:1]
	v_max_f32_e32 v108, 0, v220
	v_max_f32_e32 v109, 0, v221
	v_pk_fma_f32 v[0:1], v[30:31], v[108:109], v[0:1]
	v_max_f32_e32 v210, 0, v222
	v_max_f32_e32 v211, 0, v223
	v_pk_fma_f32 v[0:1], v[32:33], v[210:211], v[0:1]
	v_max_f32_e32 v108, 0, v224
	v_max_f32_e32 v109, 0, v225
	v_pk_fma_f32 v[0:1], v[34:35], v[108:109], v[0:1]
	v_max_f32_e32 v210, 0, v226
	v_max_f32_e32 v211, 0, v227
	v_pk_fma_f32 v[0:1], v[36:37], v[210:211], v[0:1]
	v_add_f32_e32 v0, v0, v1
	v_ashrrev_i32_e32 v1, 31, v0
	v_or_b32_e32 v1, 0x80000000, v1
	v_xor_b32_e32 v0, v1, v0
	v_cndmask_b32_e32 v171, v123, v0, vcc
	v_max_f32_e32 v108, 0, v6
	v_max_f32_e32 v109, 0, v7
	v_pk_mul_f32 v[50:51], v[244:245], v[108:109]
	v_max_f32_e32 v210, 0, v8
	v_max_f32_e32 v211, 0, v9
	v_pk_fma_f32 v[50:51], v[246:247], v[210:211], v[50:51]
	v_max_f32_e32 v108, 0, v10
	v_max_f32_e32 v109, 0, v11
	v_pk_fma_f32 v[50:51], v[248:249], v[108:109], v[50:51]
	v_max_f32_e32 v210, 0, v12
	v_max_f32_e32 v211, 0, v13
	v_pk_fma_f32 v[50:51], v[250:251], v[210:211], v[50:51]
	v_max_f32_e32 v108, 0, v14
	v_max_f32_e32 v109, 0, v15
	v_pk_fma_f32 v[50:51], v[252:253], v[108:109], v[50:51]
	v_max_f32_e32 v210, 0, v16
	v_max_f32_e32 v211, 0, v17
	v_pk_fma_f32 v[50:51], v[254:255], v[210:211], v[50:51]
	v_max_f32_e32 v108, 0, v18
	v_max_f32_e32 v109, 0, v19
	v_pk_fma_f32 v[50:51], v[200:201], v[108:109], v[50:51]
	v_max_f32_e32 v210, 0, v20
	v_max_f32_e32 v211, 0, v21
	v_pk_fma_f32 v[50:51], v[202:203], v[210:211], v[50:51]
	v_add_f32_e32 v50, v50, v51
	v_ashrrev_i32_e32 v51, 31, v50
	v_or_b32_e32 v51, 0x80000000, v51
	v_xor_b32_e32 v50, v51, v50
	v_cndmask_b32_e32 v50, v123, v50, vcc
	global_store_dword v243, v50, s[8:9] offset:2048
	s_add_u32 s8, s8, 0x1000
	s_addc_u32 s9, s9, 0
	s_cmpk_gt_i32 s81, 40
	s_cbranch_scc0 .Lix_fill_5
	s_add_i32 m0, s10, 98304
	s_nop 0
	global_load_lds_dwordx4 v102, s[6:7]
	s_add_i32 m0, s10, 99328
	s_nop 0
	global_load_lds_dwordx4 v110, s[6:7]
	s_add_i32 m0, s10, 100352
	s_nop 0
	global_load_lds_dwordx4 v112, s[6:7]
	s_add_i32 m0, s10, 101376
	s_nop 0
	global_load_lds_dwordx4 v193, s[6:7]
	s_add_u32 s6, s6, 0x8000
	s_addc_u32 s7, s7, 0
	s_waitcnt vmcnt(16)
	ds_read_b128 v[38:41], v5 offset:10496
	ds_read_b128 v[42:45], v52 offset:10496
	ds_read_b128 v[46:49], v55 offset:10496
	ds_read_b128 v[196:199], v56 offset:10496
	s_waitcnt lgkmcnt(3)
	v_mfma_f32_32x32x16_bf16 v[212:227], v[70:73], v[38:41], 0
	s_waitcnt lgkmcnt(2)
	v_mfma_f32_32x32x16_bf16 v[212:227], v[74:77], v[42:45], v[212:227]
	s_waitcnt lgkmcnt(1)
	v_mfma_f32_32x32x16_bf16 v[212:227], v[78:81], v[46:49], v[212:227]
	s_waitcnt lgkmcnt(0)
	v_mfma_f32_32x32x16_bf16 v[212:227], v[82:85], v[196:199], v[212:227]
	v_mfma_f32_32x32x16_bf16 v[6:21], v[86:89], v[38:41], 0
	v_mfma_f32_32x32x16_bf16 v[6:21], v[90:93], v[42:45], v[6:21]
	v_mfma_f32_32x32x16_bf16 v[6:21], v[94:97], v[46:49], v[6:21]
	v_mfma_f32_32x32x16_bf16 v[6:21], v[98:101], v[196:199], v[6:21]
	s_nop 7
	s_cmpk_gt_i32 s11, 320
	s_cselect_b64 vcc, -1, 0
	v_max_f32_e32 v108, 0, v212
	v_max_f32_e32 v109, 0, v213
	v_pk_mul_f32 v[0:1], v[22:23], v[108:109]
	v_max_f32_e32 v210, 0, v214
	v_max_f32_e32 v211, 0, v215
	v_pk_fma_f32 v[0:1], v[24:25], v[210:211], v[0:1]
	v_max_f32_e32 v108, 0, v216
	v_max_f32_e32 v109, 0, v217
	v_pk_fma_f32 v[0:1], v[26:27], v[108:109], v[0:1]
	v_max_f32_e32 v210, 0, v218
	v_max_f32_e32 v211, 0, v219
	v_pk_fma_f32 v[0:1], v[28:29], v[210:211], v[0:1]
	v_max_f32_e32 v108, 0, v220
	v_max_f32_e32 v109, 0, v221
	v_pk_fma_f32 v[0:1], v[30:31], v[108:109], v[0:1]
	v_max_f32_e32 v210, 0, v222
	v_max_f32_e32 v211, 0, v223
	v_pk_fma_f32 v[0:1], v[32:33], v[210:211], v[0:1]
	v_max_f32_e32 v108, 0, v224
	v_max_f32_e32 v109, 0, v225
	v_pk_fma_f32 v[0:1], v[34:35], v[108:109], v[0:1]
	v_max_f32_e32 v210, 0, v226
	v_max_f32_e32 v211, 0, v227
	v_pk_fma_f32 v[0:1], v[36:37], v[210:211], v[0:1]
	v_add_f32_e32 v0, v0, v1
	v_ashrrev_i32_e32 v1, 31, v0
	v_or_b32_e32 v1, 0x80000000, v1
	v_xor_b32_e32 v0, v1, v0
	v_cndmask_b32_e32 v174, v123, v0, vcc
	s_add_i32 m0, s10, 0
	s_nop 0
	global_load_lds_dwordx4 v102, s[6:7]
	s_add_i32 m0, s10, 1024
	s_nop 0
	global_load_lds_dwordx4 v110, s[6:7]
	s_add_i32 m0, s10, 2048
	s_nop 0
	global_load_lds_dwordx4 v112, s[6:7]
	s_add_i32 m0, s10, 3072
	s_nop 0
	global_load_lds_dwordx4 v193, s[6:7]
	s_add_u32 s6, s6, 0x8000
	s_addc_u32 s7, s7, 0
	s_waitcnt vmcnt(15)
	ds_read_b128 v[38:41], v5 offset:43264
	ds_read_b128 v[42:45], v52 offset:43264
	ds_read_b128 v[46:49], v55 offset:43264
	ds_read_b128 v[196:199], v56 offset:43264
	s_waitcnt lgkmcnt(3)
	v_mfma_f32_32x32x16_bf16 v[212:227], v[70:73], v[38:41], 0
	s_waitcnt lgkmcnt(2)
	v_mfma_f32_32x32x16_bf16 v[212:227], v[74:77], v[42:45], v[212:227]
	s_waitcnt lgkmcnt(1)
	v_mfma_f32_32x32x16_bf16 v[212:227], v[78:81], v[46:49], v[212:227]
	s_waitcnt lgkmcnt(0)
	v_mfma_f32_32x32x16_bf16 v[212:227], v[82:85], v[196:199], v[212:227]
	s_cmpk_gt_i32 s11, 320
	s_cselect_b64 vcc, -1, 0
	v_max_f32_e32 v108, 0, v6
	v_max_f32_e32 v109, 0, v7
	v_pk_mul_f32 v[50:51], v[244:245], v[108:109]
	v_max_f32_e32 v210, 0, v8
	v_max_f32_e32 v211, 0, v9
	v_pk_fma_f32 v[50:51], v[246:247], v[210:211], v[50:51]
	v_max_f32_e32 v108, 0, v10
	v_max_f32_e32 v109, 0, v11
	v_pk_fma_f32 v[50:51], v[248:249], v[108:109], v[50:51]
	v_max_f32_e32 v210, 0, v12
	v_max_f32_e32 v211, 0, v13
	v_pk_fma_f32 v[50:51], v[250:251], v[210:211], v[50:51]
	v_max_f32_e32 v108, 0, v14
	v_max_f32_e32 v109, 0, v15
	v_pk_fma_f32 v[50:51], v[252:253], v[108:109], v[50:51]
	v_max_f32_e32 v210, 0, v16
	v_max_f32_e32 v211, 0, v17
	v_pk_fma_f32 v[50:51], v[254:255], v[210:211], v[50:51]
	v_max_f32_e32 v108, 0, v18
	v_max_f32_e32 v109, 0, v19
	v_pk_fma_f32 v[50:51], v[200:201], v[108:109], v[50:51]
	v_max_f32_e32 v210, 0, v20
	v_max_f32_e32 v211, 0, v21
	v_pk_fma_f32 v[50:51], v[202:203], v[210:211], v[50:51]
	v_add_f32_e32 v50, v50, v51
	v_ashrrev_i32_e32 v51, 31, v50
	v_or_b32_e32 v51, 0x80000000, v51
	v_xor_b32_e32 v50, v51, v50
	v_cndmask_b32_e32 v50, v123, v50, vcc
	global_store_dword v243, v50, s[8:9]
	v_mfma_f32_32x32x16_bf16 v[6:21], v[86:89], v[38:41], 0
	v_mfma_f32_32x32x16_bf16 v[6:21], v[90:93], v[42:45], v[6:21]
	v_mfma_f32_32x32x16_bf16 v[6:21], v[94:97], v[46:49], v[6:21]
	v_mfma_f32_32x32x16_bf16 v[6:21], v[98:101], v[196:199], v[6:21]
	s_cmpk_gt_i32 s11, 328
	s_cselect_b64 vcc, -1, 0
	v_max_f32_e32 v108, 0, v212
	v_max_f32_e32 v109, 0, v213
	v_pk_mul_f32 v[0:1], v[22:23], v[108:109]
	v_max_f32_e32 v210, 0, v214
	v_max_f32_e32 v211, 0, v215
	v_pk_fma_f32 v[0:1], v[24:25], v[210:211], v[0:1]
	v_max_f32_e32 v108, 0, v216
	v_max_f32_e32 v109, 0, v217
	v_pk_fma_f32 v[0:1], v[26:27], v[108:109], v[0:1]
	v_max_f32_e32 v210, 0, v218
	v_max_f32_e32 v211, 0, v219
	v_pk_fma_f32 v[0:1], v[28:29], v[210:211], v[0:1]
	v_max_f32_e32 v108, 0, v220
	v_max_f32_e32 v109, 0, v221
	v_pk_fma_f32 v[0:1], v[30:31], v[108:109], v[0:1]
	v_max_f32_e32 v210, 0, v222
	v_max_f32_e32 v211, 0, v223
	v_pk_fma_f32 v[0:1], v[32:33], v[210:211], v[0:1]
	v_max_f32_e32 v108, 0, v224
	v_max_f32_e32 v109, 0, v225
	v_pk_fma_f32 v[0:1], v[34:35], v[108:109], v[0:1]
	v_max_f32_e32 v210, 0, v226
	v_max_f32_e32 v211, 0, v227
	v_pk_fma_f32 v[0:1], v[36:37], v[210:211], v[0:1]
	v_add_f32_e32 v0, v0, v1
	v_ashrrev_i32_e32 v1, 31, v0
	v_or_b32_e32 v1, 0x80000000, v1
	v_xor_b32_e32 v0, v1, v0
	v_cndmask_b32_e32 v173, v123, v0, vcc
	s_add_i32 m0, s10, 32768
	s_nop 0
	global_load_lds_dwordx4 v102, s[6:7]
	s_add_i32 m0, s10, 33792
	s_nop 0
	global_load_lds_dwordx4 v110, s[6:7]
	s_add_i32 m0, s10, 34816
	s_nop 0
	global_load_lds_dwordx4 v112, s[6:7]
	s_add_i32 m0, s10, 35840
	s_nop 0
	global_load_lds_dwordx4 v193, s[6:7]
	s_add_u32 s6, s6, 0x8000
	s_addc_u32 s7, s7, 0
	s_waitcnt vmcnt(15)
	v_add_u32_e32 v228, 0x10000, v5
	ds_read_b128 v[38:41], v228 offset:10496
	v_add_u32_e32 v228, 0x10000, v52
	ds_read_b128 v[42:45], v228 offset:10496
	v_add_u32_e32 v228, 0x10000, v55
	ds_read_b128 v[46:49], v228 offset:10496
	v_add_u32_e32 v228, 0x10000, v56
	ds_read_b128 v[196:199], v228 offset:10496
	s_waitcnt lgkmcnt(3)
	v_mfma_f32_32x32x16_bf16 v[212:227], v[70:73], v[38:41], 0
	s_waitcnt lgkmcnt(2)
	v_mfma_f32_32x32x16_bf16 v[212:227], v[74:77], v[42:45], v[212:227]
	s_waitcnt lgkmcnt(1)
	v_mfma_f32_32x32x16_bf16 v[212:227], v[78:81], v[46:49], v[212:227]
	s_waitcnt lgkmcnt(0)
	v_mfma_f32_32x32x16_bf16 v[212:227], v[82:85], v[196:199], v[212:227]
	s_cmpk_gt_i32 s11, 328
	s_cselect_b64 vcc, -1, 0
	v_max_f32_e32 v108, 0, v6
	v_max_f32_e32 v109, 0, v7
	v_pk_mul_f32 v[50:51], v[244:245], v[108:109]
	v_max_f32_e32 v210, 0, v8
	v_max_f32_e32 v211, 0, v9
	v_pk_fma_f32 v[50:51], v[246:247], v[210:211], v[50:51]
	v_max_f32_e32 v108, 0, v10
	v_max_f32_e32 v109, 0, v11
	v_pk_fma_f32 v[50:51], v[248:249], v[108:109], v[50:51]
	v_max_f32_e32 v210, 0, v12
	v_max_f32_e32 v211, 0, v13
	v_pk_fma_f32 v[50:51], v[250:251], v[210:211], v[50:51]
	v_max_f32_e32 v108, 0, v14
	v_max_f32_e32 v109, 0, v15
	v_pk_fma_f32 v[50:51], v[252:253], v[108:109], v[50:51]
	v_max_f32_e32 v210, 0, v16
	v_max_f32_e32 v211, 0, v17
	v_pk_fma_f32 v[50:51], v[254:255], v[210:211], v[50:51]
	v_max_f32_e32 v108, 0, v18
	v_max_f32_e32 v109, 0, v19
	v_pk_fma_f32 v[50:51], v[200:201], v[108:109], v[50:51]
	v_max_f32_e32 v210, 0, v20
	v_max_f32_e32 v211, 0, v21
	v_pk_fma_f32 v[50:51], v[202:203], v[210:211], v[50:51]
	v_add_f32_e32 v50, v50, v51
	v_ashrrev_i32_e32 v51, 31, v50
	v_or_b32_e32 v51, 0x80000000, v51
	v_xor_b32_e32 v50, v51, v50
	v_cndmask_b32_e32 v50, v123, v50, vcc
	global_store_dword v243, v50, s[8:9] offset:2048
	s_add_u32 s8, s8, 0x1000
	s_addc_u32 s9, s9, 0
	v_mfma_f32_32x32x16_bf16 v[6:21], v[86:89], v[38:41], 0
	v_mfma_f32_32x32x16_bf16 v[6:21], v[90:93], v[42:45], v[6:21]
	v_mfma_f32_32x32x16_bf16 v[6:21], v[94:97], v[46:49], v[6:21]
	v_mfma_f32_32x32x16_bf16 v[6:21], v[98:101], v[196:199], v[6:21]
	s_cmpk_gt_i32 s11, 336
	s_cselect_b64 vcc, -1, 0
	v_max_f32_e32 v108, 0, v212
	v_max_f32_e32 v109, 0, v213
	v_pk_mul_f32 v[0:1], v[22:23], v[108:109]
	v_max_f32_e32 v210, 0, v214
	v_max_f32_e32 v211, 0, v215
	v_pk_fma_f32 v[0:1], v[24:25], v[210:211], v[0:1]
	v_max_f32_e32 v108, 0, v216
	v_max_f32_e32 v109, 0, v217
	v_pk_fma_f32 v[0:1], v[26:27], v[108:109], v[0:1]
	v_max_f32_e32 v210, 0, v218
	v_max_f32_e32 v211, 0, v219
	v_pk_fma_f32 v[0:1], v[28:29], v[210:211], v[0:1]
	v_max_f32_e32 v108, 0, v220
	v_max_f32_e32 v109, 0, v221
	v_pk_fma_f32 v[0:1], v[30:31], v[108:109], v[0:1]
	v_max_f32_e32 v210, 0, v222
	v_max_f32_e32 v211, 0, v223
	v_pk_fma_f32 v[0:1], v[32:33], v[210:211], v[0:1]
	v_max_f32_e32 v108, 0, v224
	v_max_f32_e32 v109, 0, v225
	v_pk_fma_f32 v[0:1], v[34:35], v[108:109], v[0:1]
	v_max_f32_e32 v210, 0, v226
	v_max_f32_e32 v211, 0, v227
	v_pk_fma_f32 v[0:1], v[36:37], v[210:211], v[0:1]
	v_add_f32_e32 v0, v0, v1
	v_ashrrev_i32_e32 v1, 31, v0
	v_or_b32_e32 v1, 0x80000000, v1
	v_xor_b32_e32 v0, v1, v0
	v_cndmask_b32_e32 v176, v123, v0, vcc
	s_add_i32 m0, s10, 65536
	s_nop 0
	global_load_lds_dwordx4 v102, s[6:7]
	s_add_i32 m0, s10, 66560
	s_nop 0
	global_load_lds_dwordx4 v110, s[6:7]
	s_add_i32 m0, s10, 67584
	s_nop 0
	global_load_lds_dwordx4 v112, s[6:7]
	s_add_i32 m0, s10, 68608
	s_nop 0
	global_load_lds_dwordx4 v193, s[6:7]
	s_add_u32 s6, s6, 0x8000
	s_addc_u32 s7, s7, 0
	s_waitcnt vmcnt(14)
	v_add_u32_e32 v228, 0x10000, v5
	ds_read_b128 v[38:41], v228 offset:43264
	v_add_u32_e32 v228, 0x10000, v52
	ds_read_b128 v[42:45], v228 offset:43264
	v_add_u32_e32 v228, 0x10000, v55
	ds_read_b128 v[46:49], v228 offset:43264
	v_add_u32_e32 v228, 0x10000, v56
	ds_read_b128 v[196:199], v228 offset:43264
	s_waitcnt lgkmcnt(3)
	v_mfma_f32_32x32x16_bf16 v[212:227], v[70:73], v[38:41], 0
	s_waitcnt lgkmcnt(2)
	v_mfma_f32_32x32x16_bf16 v[212:227], v[74:77], v[42:45], v[212:227]
	s_waitcnt lgkmcnt(1)
	v_mfma_f32_32x32x16_bf16 v[212:227], v[78:81], v[46:49], v[212:227]
	s_waitcnt lgkmcnt(0)
	v_mfma_f32_32x32x16_bf16 v[212:227], v[82:85], v[196:199], v[212:227]
	s_cmpk_gt_i32 s11, 336
	s_cselect_b64 vcc, -1, 0
	v_max_f32_e32 v108, 0, v6
	v_max_f32_e32 v109, 0, v7
	v_pk_mul_f32 v[50:51], v[244:245], v[108:109]
	v_max_f32_e32 v210, 0, v8
	v_max_f32_e32 v211, 0, v9
	v_pk_fma_f32 v[50:51], v[246:247], v[210:211], v[50:51]
	v_max_f32_e32 v108, 0, v10
	v_max_f32_e32 v109, 0, v11
	v_pk_fma_f32 v[50:51], v[248:249], v[108:109], v[50:51]
	v_max_f32_e32 v210, 0, v12
	v_max_f32_e32 v211, 0, v13
	v_pk_fma_f32 v[50:51], v[250:251], v[210:211], v[50:51]
	v_max_f32_e32 v108, 0, v14
	v_max_f32_e32 v109, 0, v15
	v_pk_fma_f32 v[50:51], v[252:253], v[108:109], v[50:51]
	v_max_f32_e32 v210, 0, v16
	v_max_f32_e32 v211, 0, v17
	v_pk_fma_f32 v[50:51], v[254:255], v[210:211], v[50:51]
	v_max_f32_e32 v108, 0, v18
	v_max_f32_e32 v109, 0, v19
	v_pk_fma_f32 v[50:51], v[200:201], v[108:109], v[50:51]
	v_max_f32_e32 v210, 0, v20
	v_max_f32_e32 v211, 0, v21
	v_pk_fma_f32 v[50:51], v[202:203], v[210:211], v[50:51]
	v_add_f32_e32 v50, v50, v51
	v_ashrrev_i32_e32 v51, 31, v50
	v_or_b32_e32 v51, 0x80000000, v51
	v_xor_b32_e32 v50, v51, v50
	v_cndmask_b32_e32 v50, v123, v50, vcc
	global_store_dword v243, v50, s[8:9]
	v_mfma_f32_32x32x16_bf16 v[6:21], v[86:89], v[38:41], 0
	v_mfma_f32_32x32x16_bf16 v[6:21], v[90:93], v[42:45], v[6:21]
	v_mfma_f32_32x32x16_bf16 v[6:21], v[94:97], v[46:49], v[6:21]
	v_mfma_f32_32x32x16_bf16 v[6:21], v[98:101], v[196:199], v[6:21]
	s_cmpk_gt_i32 s11, 344
	s_cselect_b64 vcc, -1, 0
	v_max_f32_e32 v108, 0, v212
	v_max_f32_e32 v109, 0, v213
	v_pk_mul_f32 v[0:1], v[22:23], v[108:109]
	v_max_f32_e32 v210, 0, v214
	v_max_f32_e32 v211, 0, v215
	v_pk_fma_f32 v[0:1], v[24:25], v[210:211], v[0:1]
	v_max_f32_e32 v108, 0, v216
	v_max_f32_e32 v109, 0, v217
	v_pk_fma_f32 v[0:1], v[26:27], v[108:109], v[0:1]
	v_max_f32_e32 v210, 0, v218
	v_max_f32_e32 v211, 0, v219
	v_pk_fma_f32 v[0:1], v[28:29], v[210:211], v[0:1]
	v_max_f32_e32 v108, 0, v220
	v_max_f32_e32 v109, 0, v221
	v_pk_fma_f32 v[0:1], v[30:31], v[108:109], v[0:1]
	v_max_f32_e32 v210, 0, v222
	v_max_f32_e32 v211, 0, v223
	v_pk_fma_f32 v[0:1], v[32:33], v[210:211], v[0:1]
	v_max_f32_e32 v108, 0, v224
	v_max_f32_e32 v109, 0, v225
	v_pk_fma_f32 v[0:1], v[34:35], v[108:109], v[0:1]
	v_max_f32_e32 v210, 0, v226
	v_max_f32_e32 v211, 0, v227
	v_pk_fma_f32 v[0:1], v[36:37], v[210:211], v[0:1]
	v_add_f32_e32 v0, v0, v1
	v_ashrrev_i32_e32 v1, 31, v0
	v_or_b32_e32 v1, 0x80000000, v1
	v_xor_b32_e32 v0, v1, v0
	v_cndmask_b32_e32 v175, v123, v0, vcc
	s_add_i32 m0, s10, 98304
	s_nop 0
	global_load_lds_dwordx4 v102, s[6:7]
	s_add_i32 m0, s10, 99328
	s_nop 0
	global_load_lds_dwordx4 v110, s[6:7]
	s_add_i32 m0, s10, 100352
	s_nop 0
	global_load_lds_dwordx4 v112, s[6:7]
	s_add_i32 m0, s10, 101376
	s_nop 0
	global_load_lds_dwordx4 v193, s[6:7]
	s_add_u32 s6, s6, 0x8000
	s_addc_u32 s7, s7, 0
	s_waitcnt vmcnt(15)
	ds_read_b128 v[38:41], v5 offset:10496
	ds_read_b128 v[42:45], v52 offset:10496
	ds_read_b128 v[46:49], v55 offset:10496
	ds_read_b128 v[196:199], v56 offset:10496
	s_waitcnt lgkmcnt(3)
	v_mfma_f32_32x32x16_bf16 v[212:227], v[70:73], v[38:41], 0
	s_waitcnt lgkmcnt(2)
	v_mfma_f32_32x32x16_bf16 v[212:227], v[74:77], v[42:45], v[212:227]
	s_waitcnt lgkmcnt(1)
	v_mfma_f32_32x32x16_bf16 v[212:227], v[78:81], v[46:49], v[212:227]
	s_waitcnt lgkmcnt(0)
	v_mfma_f32_32x32x16_bf16 v[212:227], v[82:85], v[196:199], v[212:227]
	s_cmpk_gt_i32 s11, 344
	s_cselect_b64 vcc, -1, 0
	v_max_f32_e32 v108, 0, v6
	v_max_f32_e32 v109, 0, v7
	v_pk_mul_f32 v[50:51], v[244:245], v[108:109]
	v_max_f32_e32 v210, 0, v8
	v_max_f32_e32 v211, 0, v9
	v_pk_fma_f32 v[50:51], v[246:247], v[210:211], v[50:51]
	v_max_f32_e32 v108, 0, v10
	v_max_f32_e32 v109, 0, v11
	v_pk_fma_f32 v[50:51], v[248:249], v[108:109], v[50:51]
	v_max_f32_e32 v210, 0, v12
	v_max_f32_e32 v211, 0, v13
	v_pk_fma_f32 v[50:51], v[250:251], v[210:211], v[50:51]
	v_max_f32_e32 v108, 0, v14
	v_max_f32_e32 v109, 0, v15
	v_pk_fma_f32 v[50:51], v[252:253], v[108:109], v[50:51]
	v_max_f32_e32 v210, 0, v16
	v_max_f32_e32 v211, 0, v17
	v_pk_fma_f32 v[50:51], v[254:255], v[210:211], v[50:51]
	v_max_f32_e32 v108, 0, v18
	v_max_f32_e32 v109, 0, v19
	v_pk_fma_f32 v[50:51], v[200:201], v[108:109], v[50:51]
	v_max_f32_e32 v210, 0, v20
	v_max_f32_e32 v211, 0, v21
	v_pk_fma_f32 v[50:51], v[202:203], v[210:211], v[50:51]
	v_add_f32_e32 v50, v50, v51
	v_ashrrev_i32_e32 v51, 31, v50
	v_or_b32_e32 v51, 0x80000000, v51
	v_xor_b32_e32 v50, v51, v50
	v_cndmask_b32_e32 v50, v123, v50, vcc
	global_store_dword v243, v50, s[8:9] offset:2048
	s_add_u32 s8, s8, 0x1000
	s_addc_u32 s9, s9, 0
	v_mfma_f32_32x32x16_bf16 v[6:21], v[86:89], v[38:41], 0
	v_mfma_f32_32x32x16_bf16 v[6:21], v[90:93], v[42:45], v[6:21]
	v_mfma_f32_32x32x16_bf16 v[6:21], v[94:97], v[46:49], v[6:21]
	v_mfma_f32_32x32x16_bf16 v[6:21], v[98:101], v[196:199], v[6:21]
	s_cmpk_gt_i32 s11, 352
	s_cselect_b64 vcc, -1, 0
	v_max_f32_e32 v108, 0, v212
	v_max_f32_e32 v109, 0, v213
	v_pk_mul_f32 v[0:1], v[22:23], v[108:109]
	v_max_f32_e32 v210, 0, v214
	v_max_f32_e32 v211, 0, v215
	v_pk_fma_f32 v[0:1], v[24:25], v[210:211], v[0:1]
	v_max_f32_e32 v108, 0, v216
	v_max_f32_e32 v109, 0, v217
	v_pk_fma_f32 v[0:1], v[26:27], v[108:109], v[0:1]
	v_max_f32_e32 v210, 0, v218
	v_max_f32_e32 v211, 0, v219
	v_pk_fma_f32 v[0:1], v[28:29], v[210:211], v[0:1]
	v_max_f32_e32 v108, 0, v220
	v_max_f32_e32 v109, 0, v221
	v_pk_fma_f32 v[0:1], v[30:31], v[108:109], v[0:1]
	v_max_f32_e32 v210, 0, v222
	v_max_f32_e32 v211, 0, v223
	v_pk_fma_f32 v[0:1], v[32:33], v[210:211], v[0:1]
	v_max_f32_e32 v108, 0, v224
	v_max_f32_e32 v109, 0, v225
	v_pk_fma_f32 v[0:1], v[34:35], v[108:109], v[0:1]
	v_max_f32_e32 v210, 0, v226
	v_max_f32_e32 v211, 0, v227
	v_pk_fma_f32 v[0:1], v[36:37], v[210:211], v[0:1]
	v_add_f32_e32 v0, v0, v1
	v_ashrrev_i32_e32 v1, 31, v0
	v_or_b32_e32 v1, 0x80000000, v1
	v_xor_b32_e32 v0, v1, v0
	v_cndmask_b32_e32 v178, v123, v0, vcc
	s_add_i32 m0, s10, 0
	s_nop 0
	global_load_lds_dwordx4 v102, s[6:7]
	s_add_i32 m0, s10, 1024
	s_nop 0
	global_load_lds_dwordx4 v110, s[6:7]
	s_add_i32 m0, s10, 2048
	s_nop 0
	global_load_lds_dwordx4 v112, s[6:7]
	s_add_i32 m0, s10, 3072
	s_nop 0
	global_load_lds_dwordx4 v193, s[6:7]
	s_add_u32 s6, s6, 0x8000
	s_addc_u32 s7, s7, 0
	s_waitcnt vmcnt(15)
	ds_read_b128 v[38:41], v5 offset:43264
	ds_read_b128 v[42:45], v52 offset:43264
	ds_read_b128 v[46:49], v55 offset:43264
	ds_read_b128 v[196:199], v56 offset:43264
	s_waitcnt lgkmcnt(3)
	v_mfma_f32_32x32x16_bf16 v[212:227], v[70:73], v[38:41], 0
	s_waitcnt lgkmcnt(2)
	v_mfma_f32_32x32x16_bf16 v[212:227], v[74:77], v[42:45], v[212:227]
	s_waitcnt lgkmcnt(1)
	v_mfma_f32_32x32x16_bf16 v[212:227], v[78:81], v[46:49], v[212:227]
	s_waitcnt lgkmcnt(0)
	v_mfma_f32_32x32x16_bf16 v[212:227], v[82:85], v[196:199], v[212:227]
	s_cmpk_gt_i32 s11, 352
	s_cselect_b64 vcc, -1, 0
	v_max_f32_e32 v108, 0, v6
	v_max_f32_e32 v109, 0, v7
	v_pk_mul_f32 v[50:51], v[244:245], v[108:109]
	v_max_f32_e32 v210, 0, v8
	v_max_f32_e32 v211, 0, v9
	v_pk_fma_f32 v[50:51], v[246:247], v[210:211], v[50:51]
	v_max_f32_e32 v108, 0, v10
	v_max_f32_e32 v109, 0, v11
	v_pk_fma_f32 v[50:51], v[248:249], v[108:109], v[50:51]
	v_max_f32_e32 v210, 0, v12
	v_max_f32_e32 v211, 0, v13
	v_pk_fma_f32 v[50:51], v[250:251], v[210:211], v[50:51]
	v_max_f32_e32 v108, 0, v14
	v_max_f32_e32 v109, 0, v15
	v_pk_fma_f32 v[50:51], v[252:253], v[108:109], v[50:51]
	v_max_f32_e32 v210, 0, v16
	v_max_f32_e32 v211, 0, v17
	v_pk_fma_f32 v[50:51], v[254:255], v[210:211], v[50:51]
	v_max_f32_e32 v108, 0, v18
	v_max_f32_e32 v109, 0, v19
	v_pk_fma_f32 v[50:51], v[200:201], v[108:109], v[50:51]
	v_max_f32_e32 v210, 0, v20
	v_max_f32_e32 v211, 0, v21
	v_pk_fma_f32 v[50:51], v[202:203], v[210:211], v[50:51]
	v_add_f32_e32 v50, v50, v51
	v_ashrrev_i32_e32 v51, 31, v50
	v_or_b32_e32 v51, 0x80000000, v51
	v_xor_b32_e32 v50, v51, v50
	v_cndmask_b32_e32 v50, v123, v50, vcc
	global_store_dword v243, v50, s[8:9]
	v_mfma_f32_32x32x16_bf16 v[6:21], v[86:89], v[38:41], 0
	v_mfma_f32_32x32x16_bf16 v[6:21], v[90:93], v[42:45], v[6:21]
	v_mfma_f32_32x32x16_bf16 v[6:21], v[94:97], v[46:49], v[6:21]
	v_mfma_f32_32x32x16_bf16 v[6:21], v[98:101], v[196:199], v[6:21]
	s_cmpk_gt_i32 s11, 360
	s_cselect_b64 vcc, -1, 0
	v_max_f32_e32 v108, 0, v212
	v_max_f32_e32 v109, 0, v213
	v_pk_mul_f32 v[0:1], v[22:23], v[108:109]
	v_max_f32_e32 v210, 0, v214
	v_max_f32_e32 v211, 0, v215
	v_pk_fma_f32 v[0:1], v[24:25], v[210:211], v[0:1]
	v_max_f32_e32 v108, 0, v216
	v_max_f32_e32 v109, 0, v217
	v_pk_fma_f32 v[0:1], v[26:27], v[108:109], v[0:1]
	v_max_f32_e32 v210, 0, v218
	v_max_f32_e32 v211, 0, v219
	v_pk_fma_f32 v[0:1], v[28:29], v[210:211], v[0:1]
	v_max_f32_e32 v108, 0, v220
	v_max_f32_e32 v109, 0, v221
	v_pk_fma_f32 v[0:1], v[30:31], v[108:109], v[0:1]
	v_max_f32_e32 v210, 0, v222
	v_max_f32_e32 v211, 0, v223
	v_pk_fma_f32 v[0:1], v[32:33], v[210:211], v[0:1]
	v_max_f32_e32 v108, 0, v224
	v_max_f32_e32 v109, 0, v225
	v_pk_fma_f32 v[0:1], v[34:35], v[108:109], v[0:1]
	v_max_f32_e32 v210, 0, v226
	v_max_f32_e32 v211, 0, v227
	v_pk_fma_f32 v[0:1], v[36:37], v[210:211], v[0:1]
	v_add_f32_e32 v0, v0, v1
	v_ashrrev_i32_e32 v1, 31, v0
	v_or_b32_e32 v1, 0x80000000, v1
	v_xor_b32_e32 v0, v1, v0
	v_cndmask_b32_e32 v177, v123, v0, vcc
	s_add_i32 m0, s10, 32768
	s_nop 0
	global_load_lds_dwordx4 v102, s[6:7]
	s_add_i32 m0, s10, 33792
	s_nop 0
	global_load_lds_dwordx4 v110, s[6:7]
	s_add_i32 m0, s10, 34816
	s_nop 0
	global_load_lds_dwordx4 v112, s[6:7]
	s_add_i32 m0, s10, 35840
	s_nop 0
	global_load_lds_dwordx4 v193, s[6:7]
	s_add_u32 s6, s6, 0x8000
	s_addc_u32 s7, s7, 0
	s_waitcnt vmcnt(15)
	v_add_u32_e32 v228, 0x10000, v5
	ds_read_b128 v[38:41], v228 offset:10496
	v_add_u32_e32 v228, 0x10000, v52
	ds_read_b128 v[42:45], v228 offset:10496
	v_add_u32_e32 v228, 0x10000, v55
	ds_read_b128 v[46:49], v228 offset:10496
	v_add_u32_e32 v228, 0x10000, v56
	ds_read_b128 v[196:199], v228 offset:10496
	s_waitcnt lgkmcnt(3)
	v_mfma_f32_32x32x16_bf16 v[212:227], v[70:73], v[38:41], 0
	s_waitcnt lgkmcnt(2)
	v_mfma_f32_32x32x16_bf16 v[212:227], v[74:77], v[42:45], v[212:227]
	s_waitcnt lgkmcnt(1)
	v_mfma_f32_32x32x16_bf16 v[212:227], v[78:81], v[46:49], v[212:227]
	s_waitcnt lgkmcnt(0)
	v_mfma_f32_32x32x16_bf16 v[212:227], v[82:85], v[196:199], v[212:227]
	s_cmpk_gt_i32 s11, 360
	s_cselect_b64 vcc, -1, 0
	v_max_f32_e32 v108, 0, v6
	v_max_f32_e32 v109, 0, v7
	v_pk_mul_f32 v[50:51], v[244:245], v[108:109]
	v_max_f32_e32 v210, 0, v8
	v_max_f32_e32 v211, 0, v9
	v_pk_fma_f32 v[50:51], v[246:247], v[210:211], v[50:51]
	v_max_f32_e32 v108, 0, v10
	v_max_f32_e32 v109, 0, v11
	v_pk_fma_f32 v[50:51], v[248:249], v[108:109], v[50:51]
	v_max_f32_e32 v210, 0, v12
	v_max_f32_e32 v211, 0, v13
	v_pk_fma_f32 v[50:51], v[250:251], v[210:211], v[50:51]
	v_max_f32_e32 v108, 0, v14
	v_max_f32_e32 v109, 0, v15
	v_pk_fma_f32 v[50:51], v[252:253], v[108:109], v[50:51]
	v_max_f32_e32 v210, 0, v16
	v_max_f32_e32 v211, 0, v17
	v_pk_fma_f32 v[50:51], v[254:255], v[210:211], v[50:51]
	v_max_f32_e32 v108, 0, v18
	v_max_f32_e32 v109, 0, v19
	v_pk_fma_f32 v[50:51], v[200:201], v[108:109], v[50:51]
	v_max_f32_e32 v210, 0, v20
	v_max_f32_e32 v211, 0, v21
	v_pk_fma_f32 v[50:51], v[202:203], v[210:211], v[50:51]
	v_add_f32_e32 v50, v50, v51
	v_ashrrev_i32_e32 v51, 31, v50
	v_or_b32_e32 v51, 0x80000000, v51
	v_xor_b32_e32 v50, v51, v50
	v_cndmask_b32_e32 v50, v123, v50, vcc
	global_store_dword v243, v50, s[8:9] offset:2048
	s_add_u32 s8, s8, 0x1000
	s_addc_u32 s9, s9, 0
	v_mfma_f32_32x32x16_bf16 v[6:21], v[86:89], v[38:41], 0
	v_mfma_f32_32x32x16_bf16 v[6:21], v[90:93], v[42:45], v[6:21]
	v_mfma_f32_32x32x16_bf16 v[6:21], v[94:97], v[46:49], v[6:21]
	v_mfma_f32_32x32x16_bf16 v[6:21], v[98:101], v[196:199], v[6:21]
	s_cmpk_gt_i32 s11, 368
	s_cselect_b64 vcc, -1, 0
	v_max_f32_e32 v108, 0, v212
	v_max_f32_e32 v109, 0, v213
	v_pk_mul_f32 v[0:1], v[22:23], v[108:109]
	v_max_f32_e32 v210, 0, v214
	v_max_f32_e32 v211, 0, v215
	v_pk_fma_f32 v[0:1], v[24:25], v[210:211], v[0:1]
	v_max_f32_e32 v108, 0, v216
	v_max_f32_e32 v109, 0, v217
	v_pk_fma_f32 v[0:1], v[26:27], v[108:109], v[0:1]
	v_max_f32_e32 v210, 0, v218
	v_max_f32_e32 v211, 0, v219
	v_pk_fma_f32 v[0:1], v[28:29], v[210:211], v[0:1]
	v_max_f32_e32 v108, 0, v220
	v_max_f32_e32 v109, 0, v221
	v_pk_fma_f32 v[0:1], v[30:31], v[108:109], v[0:1]
	v_max_f32_e32 v210, 0, v222
	v_max_f32_e32 v211, 0, v223
	v_pk_fma_f32 v[0:1], v[32:33], v[210:211], v[0:1]
	v_max_f32_e32 v108, 0, v224
	v_max_f32_e32 v109, 0, v225
	v_pk_fma_f32 v[0:1], v[34:35], v[108:109], v[0:1]
	v_max_f32_e32 v210, 0, v226
	v_max_f32_e32 v211, 0, v227
	v_pk_fma_f32 v[0:1], v[36:37], v[210:211], v[0:1]
	v_add_f32_e32 v0, v0, v1
	v_ashrrev_i32_e32 v1, 31, v0
	v_or_b32_e32 v1, 0x80000000, v1
	v_xor_b32_e32 v0, v1, v0
	v_cndmask_b32_e32 v179, v123, v0, vcc
	s_add_i32 m0, s10, 65536
	s_nop 0
	global_load_lds_dwordx4 v102, s[6:7]
	s_add_i32 m0, s10, 66560
	s_nop 0
	global_load_lds_dwordx4 v110, s[6:7]
	s_add_i32 m0, s10, 67584
	s_nop 0
	global_load_lds_dwordx4 v112, s[6:7]
	s_add_i32 m0, s10, 68608
	s_nop 0
	global_load_lds_dwordx4 v193, s[6:7]
	s_add_u32 s6, s6, 0x8000
	s_addc_u32 s7, s7, 0
	s_waitcnt vmcnt(15)
	v_add_u32_e32 v228, 0x10000, v5
	ds_read_b128 v[38:41], v228 offset:43264
	v_add_u32_e32 v228, 0x10000, v52
	ds_read_b128 v[42:45], v228 offset:43264
	v_add_u32_e32 v228, 0x10000, v55
	ds_read_b128 v[46:49], v228 offset:43264
	v_add_u32_e32 v228, 0x10000, v56
	ds_read_b128 v[196:199], v228 offset:43264
	s_waitcnt lgkmcnt(3)
	v_mfma_f32_32x32x16_bf16 v[212:227], v[70:73], v[38:41], 0
	s_waitcnt lgkmcnt(2)
	v_mfma_f32_32x32x16_bf16 v[212:227], v[74:77], v[42:45], v[212:227]
	s_waitcnt lgkmcnt(1)
	v_mfma_f32_32x32x16_bf16 v[212:227], v[78:81], v[46:49], v[212:227]
	s_waitcnt lgkmcnt(0)
	v_mfma_f32_32x32x16_bf16 v[212:227], v[82:85], v[196:199], v[212:227]
	s_cmpk_gt_i32 s11, 368
	s_cselect_b64 vcc, -1, 0
	v_max_f32_e32 v108, 0, v6
	v_max_f32_e32 v109, 0, v7
	v_pk_mul_f32 v[50:51], v[244:245], v[108:109]
	v_max_f32_e32 v210, 0, v8
	v_max_f32_e32 v211, 0, v9
	v_pk_fma_f32 v[50:51], v[246:247], v[210:211], v[50:51]
	v_max_f32_e32 v108, 0, v10
	v_max_f32_e32 v109, 0, v11
	v_pk_fma_f32 v[50:51], v[248:249], v[108:109], v[50:51]
	v_max_f32_e32 v210, 0, v12
	v_max_f32_e32 v211, 0, v13
	v_pk_fma_f32 v[50:51], v[250:251], v[210:211], v[50:51]
	v_max_f32_e32 v108, 0, v14
	v_max_f32_e32 v109, 0, v15
	v_pk_fma_f32 v[50:51], v[252:253], v[108:109], v[50:51]
	v_max_f32_e32 v210, 0, v16
	v_max_f32_e32 v211, 0, v17
	v_pk_fma_f32 v[50:51], v[254:255], v[210:211], v[50:51]
	v_max_f32_e32 v108, 0, v18
	v_max_f32_e32 v109, 0, v19
	v_pk_fma_f32 v[50:51], v[200:201], v[108:109], v[50:51]
	v_max_f32_e32 v210, 0, v20
	v_max_f32_e32 v211, 0, v21
	v_pk_fma_f32 v[50:51], v[202:203], v[210:211], v[50:51]
	v_add_f32_e32 v50, v50, v51
	v_ashrrev_i32_e32 v51, 31, v50
	v_or_b32_e32 v51, 0x80000000, v51
	v_xor_b32_e32 v50, v51, v50
	v_cndmask_b32_e32 v50, v123, v50, vcc
	global_store_dword v243, v50, s[8:9]
	v_mfma_f32_32x32x16_bf16 v[6:21], v[86:89], v[38:41], 0
	v_mfma_f32_32x32x16_bf16 v[6:21], v[90:93], v[42:45], v[6:21]
	v_mfma_f32_32x32x16_bf16 v[6:21], v[94:97], v[46:49], v[6:21]
	v_mfma_f32_32x32x16_bf16 v[6:21], v[98:101], v[196:199], v[6:21]
	s_cmpk_gt_i32 s11, 376
	s_cselect_b64 vcc, -1, 0
	v_max_f32_e32 v108, 0, v212
	v_max_f32_e32 v109, 0, v213
	v_pk_mul_f32 v[0:1], v[22:23], v[108:109]
	v_max_f32_e32 v210, 0, v214
	v_max_f32_e32 v211, 0, v215
	v_pk_fma_f32 v[0:1], v[24:25], v[210:211], v[0:1]
	v_max_f32_e32 v108, 0, v216
	v_max_f32_e32 v109, 0, v217
	v_pk_fma_f32 v[0:1], v[26:27], v[108:109], v[0:1]
	v_max_f32_e32 v210, 0, v218
	v_max_f32_e32 v211, 0, v219
	v_pk_fma_f32 v[0:1], v[28:29], v[210:211], v[0:1]
	v_max_f32_e32 v108, 0, v220
	v_max_f32_e32 v109, 0, v221
	v_pk_fma_f32 v[0:1], v[30:31], v[108:109], v[0:1]
	v_max_f32_e32 v210, 0, v222
	v_max_f32_e32 v211, 0, v223
	v_pk_fma_f32 v[0:1], v[32:33], v[210:211], v[0:1]
	v_max_f32_e32 v108, 0, v224
	v_max_f32_e32 v109, 0, v225
	v_pk_fma_f32 v[0:1], v[34:35], v[108:109], v[0:1]
	v_max_f32_e32 v210, 0, v226
	v_max_f32_e32 v211, 0, v227
	v_pk_fma_f32 v[0:1], v[36:37], v[210:211], v[0:1]
	v_add_f32_e32 v0, v0, v1
	v_ashrrev_i32_e32 v1, 31, v0
	v_or_b32_e32 v1, 0x80000000, v1
	v_xor_b32_e32 v0, v1, v0
	v_cndmask_b32_e32 v168, v123, v0, vcc
	v_max_f32_e32 v108, 0, v6
	v_max_f32_e32 v109, 0, v7
	v_pk_mul_f32 v[50:51], v[244:245], v[108:109]
	v_max_f32_e32 v210, 0, v8
	v_max_f32_e32 v211, 0, v9
	v_pk_fma_f32 v[50:51], v[246:247], v[210:211], v[50:51]
	v_max_f32_e32 v108, 0, v10
	v_max_f32_e32 v109, 0, v11
	v_pk_fma_f32 v[50:51], v[248:249], v[108:109], v[50:51]
	v_max_f32_e32 v210, 0, v12
	v_max_f32_e32 v211, 0, v13
	v_pk_fma_f32 v[50:51], v[250:251], v[210:211], v[50:51]
	v_max_f32_e32 v108, 0, v14
	v_max_f32_e32 v109, 0, v15
	v_pk_fma_f32 v[50:51], v[252:253], v[108:109], v[50:51]
	v_max_f32_e32 v210, 0, v16
	v_max_f32_e32 v211, 0, v17
	v_pk_fma_f32 v[50:51], v[254:255], v[210:211], v[50:51]
	v_max_f32_e32 v108, 0, v18
	v_max_f32_e32 v109, 0, v19
	v_pk_fma_f32 v[50:51], v[200:201], v[108:109], v[50:51]
	v_max_f32_e32 v210, 0, v20
	v_max_f32_e32 v211, 0, v21
	v_pk_fma_f32 v[50:51], v[202:203], v[210:211], v[50:51]
	v_add_f32_e32 v50, v50, v51
	v_ashrrev_i32_e32 v51, 31, v50
	v_or_b32_e32 v51, 0x80000000, v51
	v_xor_b32_e32 v50, v51, v50
	v_cndmask_b32_e32 v50, v123, v50, vcc
	global_store_dword v243, v50, s[8:9] offset:2048
	s_add_u32 s8, s8, 0x1000
	s_addc_u32 s9, s9, 0
	s_cmpk_gt_i32 s81, 48
	s_cbranch_scc0 .Lix_fill_6
	s_add_i32 m0, s10, 98304
	s_nop 0
	global_load_lds_dwordx4 v102, s[6:7]
	s_add_i32 m0, s10, 99328
	s_nop 0
	global_load_lds_dwordx4 v110, s[6:7]
	s_add_i32 m0, s10, 100352
	s_nop 0
	global_load_lds_dwordx4 v112, s[6:7]
	s_add_i32 m0, s10, 101376
	s_nop 0
	global_load_lds_dwordx4 v193, s[6:7]
	s_add_u32 s6, s6, 0x8000
	s_addc_u32 s7, s7, 0
	s_waitcnt vmcnt(16)
	ds_read_b128 v[38:41], v5 offset:10496
	ds_read_b128 v[42:45], v52 offset:10496
	ds_read_b128 v[46:49], v55 offset:10496
	ds_read_b128 v[196:199], v56 offset:10496
	s_waitcnt lgkmcnt(3)
	v_mfma_f32_32x32x16_bf16 v[212:227], v[70:73], v[38:41], 0
	s_waitcnt lgkmcnt(2)
	v_mfma_f32_32x32x16_bf16 v[212:227], v[74:77], v[42:45], v[212:227]
	s_waitcnt lgkmcnt(1)
	v_mfma_f32_32x32x16_bf16 v[212:227], v[78:81], v[46:49], v[212:227]
	s_waitcnt lgkmcnt(0)
	v_mfma_f32_32x32x16_bf16 v[212:227], v[82:85], v[196:199], v[212:227]
	v_mfma_f32_32x32x16_bf16 v[6:21], v[86:89], v[38:41], 0
	v_mfma_f32_32x32x16_bf16 v[6:21], v[90:93], v[42:45], v[6:21]
	v_mfma_f32_32x32x16_bf16 v[6:21], v[94:97], v[46:49], v[6:21]
	v_mfma_f32_32x32x16_bf16 v[6:21], v[98:101], v[196:199], v[6:21]
	s_nop 7
	s_cmpk_gt_i32 s11, 384
	s_cselect_b64 vcc, -1, 0
	v_max_f32_e32 v108, 0, v212
	v_max_f32_e32 v109, 0, v213
	v_pk_mul_f32 v[0:1], v[22:23], v[108:109]
	v_max_f32_e32 v210, 0, v214
	v_max_f32_e32 v211, 0, v215
	v_pk_fma_f32 v[0:1], v[24:25], v[210:211], v[0:1]
	v_max_f32_e32 v108, 0, v216
	v_max_f32_e32 v109, 0, v217
	v_pk_fma_f32 v[0:1], v[26:27], v[108:109], v[0:1]
	v_max_f32_e32 v210, 0, v218
	v_max_f32_e32 v211, 0, v219
	v_pk_fma_f32 v[0:1], v[28:29], v[210:211], v[0:1]
	v_max_f32_e32 v108, 0, v220
	v_max_f32_e32 v109, 0, v221
	v_pk_fma_f32 v[0:1], v[30:31], v[108:109], v[0:1]
	v_max_f32_e32 v210, 0, v222
	v_max_f32_e32 v211, 0, v223
	v_pk_fma_f32 v[0:1], v[32:33], v[210:211], v[0:1]
	v_max_f32_e32 v108, 0, v224
	v_max_f32_e32 v109, 0, v225
	v_pk_fma_f32 v[0:1], v[34:35], v[108:109], v[0:1]
	v_max_f32_e32 v210, 0, v226
	v_max_f32_e32 v211, 0, v227
	v_pk_fma_f32 v[0:1], v[36:37], v[210:211], v[0:1]
	v_add_f32_e32 v0, v0, v1
	v_ashrrev_i32_e32 v1, 31, v0
	v_or_b32_e32 v1, 0x80000000, v1
	v_xor_b32_e32 v0, v1, v0
	v_cndmask_b32_e32 v182, v123, v0, vcc
	s_add_i32 m0, s10, 0
	s_nop 0
	global_load_lds_dwordx4 v102, s[6:7]
	s_add_i32 m0, s10, 1024
	s_nop 0
	global_load_lds_dwordx4 v110, s[6:7]
	s_add_i32 m0, s10, 2048
	s_nop 0
	global_load_lds_dwordx4 v112, s[6:7]
	s_add_i32 m0, s10, 3072
	s_nop 0
	global_load_lds_dwordx4 v193, s[6:7]
	s_add_u32 s6, s6, 0x8000
	s_addc_u32 s7, s7, 0
	s_waitcnt vmcnt(15)
	ds_read_b128 v[38:41], v5 offset:43264
	ds_read_b128 v[42:45], v52 offset:43264
	ds_read_b128 v[46:49], v55 offset:43264
	ds_read_b128 v[196:199], v56 offset:43264
	s_waitcnt lgkmcnt(3)
	v_mfma_f32_32x32x16_bf16 v[212:227], v[70:73], v[38:41], 0
	s_waitcnt lgkmcnt(2)
	v_mfma_f32_32x32x16_bf16 v[212:227], v[74:77], v[42:45], v[212:227]
	s_waitcnt lgkmcnt(1)
	v_mfma_f32_32x32x16_bf16 v[212:227], v[78:81], v[46:49], v[212:227]
	s_waitcnt lgkmcnt(0)
	v_mfma_f32_32x32x16_bf16 v[212:227], v[82:85], v[196:199], v[212:227]
	s_cmpk_gt_i32 s11, 384
	s_cselect_b64 vcc, -1, 0
	v_max_f32_e32 v108, 0, v6
	v_max_f32_e32 v109, 0, v7
	v_pk_mul_f32 v[50:51], v[244:245], v[108:109]
	v_max_f32_e32 v210, 0, v8
	v_max_f32_e32 v211, 0, v9
	v_pk_fma_f32 v[50:51], v[246:247], v[210:211], v[50:51]
	v_max_f32_e32 v108, 0, v10
	v_max_f32_e32 v109, 0, v11
	v_pk_fma_f32 v[50:51], v[248:249], v[108:109], v[50:51]
	v_max_f32_e32 v210, 0, v12
	v_max_f32_e32 v211, 0, v13
	v_pk_fma_f32 v[50:51], v[250:251], v[210:211], v[50:51]
	v_max_f32_e32 v108, 0, v14
	v_max_f32_e32 v109, 0, v15
	v_pk_fma_f32 v[50:51], v[252:253], v[108:109], v[50:51]
	v_max_f32_e32 v210, 0, v16
	v_max_f32_e32 v211, 0, v17
	v_pk_fma_f32 v[50:51], v[254:255], v[210:211], v[50:51]
	v_max_f32_e32 v108, 0, v18
	v_max_f32_e32 v109, 0, v19
	v_pk_fma_f32 v[50:51], v[200:201], v[108:109], v[50:51]
	v_max_f32_e32 v210, 0, v20
	v_max_f32_e32 v211, 0, v21
	v_pk_fma_f32 v[50:51], v[202:203], v[210:211], v[50:51]
	v_add_f32_e32 v50, v50, v51
	v_ashrrev_i32_e32 v51, 31, v50
	v_or_b32_e32 v51, 0x80000000, v51
	v_xor_b32_e32 v50, v51, v50
	v_cndmask_b32_e32 v50, v123, v50, vcc
	global_store_dword v243, v50, s[8:9]
	v_mfma_f32_32x32x16_bf16 v[6:21], v[86:89], v[38:41], 0
	v_mfma_f32_32x32x16_bf16 v[6:21], v[90:93], v[42:45], v[6:21]
	v_mfma_f32_32x32x16_bf16 v[6:21], v[94:97], v[46:49], v[6:21]
	v_mfma_f32_32x32x16_bf16 v[6:21], v[98:101], v[196:199], v[6:21]
	s_cmpk_gt_i32 s11, 392
	s_cselect_b64 vcc, -1, 0
	v_max_f32_e32 v108, 0, v212
	v_max_f32_e32 v109, 0, v213
	v_pk_mul_f32 v[0:1], v[22:23], v[108:109]
	v_max_f32_e32 v210, 0, v214
	v_max_f32_e32 v211, 0, v215
	v_pk_fma_f32 v[0:1], v[24:25], v[210:211], v[0:1]
	v_max_f32_e32 v108, 0, v216
	v_max_f32_e32 v109, 0, v217
	v_pk_fma_f32 v[0:1], v[26:27], v[108:109], v[0:1]
	v_max_f32_e32 v210, 0, v218
	v_max_f32_e32 v211, 0, v219
	v_pk_fma_f32 v[0:1], v[28:29], v[210:211], v[0:1]
	v_max_f32_e32 v108, 0, v220
	v_max_f32_e32 v109, 0, v221
	v_pk_fma_f32 v[0:1], v[30:31], v[108:109], v[0:1]
	v_max_f32_e32 v210, 0, v222
	v_max_f32_e32 v211, 0, v223
	v_pk_fma_f32 v[0:1], v[32:33], v[210:211], v[0:1]
	v_max_f32_e32 v108, 0, v224
	v_max_f32_e32 v109, 0, v225
	v_pk_fma_f32 v[0:1], v[34:35], v[108:109], v[0:1]
	v_max_f32_e32 v210, 0, v226
	v_max_f32_e32 v211, 0, v227
	v_pk_fma_f32 v[0:1], v[36:37], v[210:211], v[0:1]
	v_add_f32_e32 v0, v0, v1
	v_ashrrev_i32_e32 v1, 31, v0
	v_or_b32_e32 v1, 0x80000000, v1
	v_xor_b32_e32 v0, v1, v0
	v_cndmask_b32_e32 v181, v123, v0, vcc
	s_add_i32 m0, s10, 32768
	s_nop 0
	global_load_lds_dwordx4 v102, s[6:7]
	s_add_i32 m0, s10, 33792
	s_nop 0
	global_load_lds_dwordx4 v110, s[6:7]
	s_add_i32 m0, s10, 34816
	s_nop 0
	global_load_lds_dwordx4 v112, s[6:7]
	s_add_i32 m0, s10, 35840
	s_nop 0
	global_load_lds_dwordx4 v193, s[6:7]
	s_add_u32 s6, s6, 0x8000
	s_addc_u32 s7, s7, 0
	s_waitcnt vmcnt(15)
	v_add_u32_e32 v228, 0x10000, v5
	ds_read_b128 v[38:41], v228 offset:10496
	v_add_u32_e32 v228, 0x10000, v52
	ds_read_b128 v[42:45], v228 offset:10496
	v_add_u32_e32 v228, 0x10000, v55
	ds_read_b128 v[46:49], v228 offset:10496
	v_add_u32_e32 v228, 0x10000, v56
	ds_read_b128 v[196:199], v228 offset:10496
	s_waitcnt lgkmcnt(3)
	v_mfma_f32_32x32x16_bf16 v[212:227], v[70:73], v[38:41], 0
	s_waitcnt lgkmcnt(2)
	v_mfma_f32_32x32x16_bf16 v[212:227], v[74:77], v[42:45], v[212:227]
	s_waitcnt lgkmcnt(1)
	v_mfma_f32_32x32x16_bf16 v[212:227], v[78:81], v[46:49], v[212:227]
	s_waitcnt lgkmcnt(0)
	v_mfma_f32_32x32x16_bf16 v[212:227], v[82:85], v[196:199], v[212:227]
	s_cmpk_gt_i32 s11, 392
	s_cselect_b64 vcc, -1, 0
	v_max_f32_e32 v108, 0, v6
	v_max_f32_e32 v109, 0, v7
	v_pk_mul_f32 v[50:51], v[244:245], v[108:109]
	v_max_f32_e32 v210, 0, v8
	v_max_f32_e32 v211, 0, v9
	v_pk_fma_f32 v[50:51], v[246:247], v[210:211], v[50:51]
	v_max_f32_e32 v108, 0, v10
	v_max_f32_e32 v109, 0, v11
	v_pk_fma_f32 v[50:51], v[248:249], v[108:109], v[50:51]
	v_max_f32_e32 v210, 0, v12
	v_max_f32_e32 v211, 0, v13
	v_pk_fma_f32 v[50:51], v[250:251], v[210:211], v[50:51]
	v_max_f32_e32 v108, 0, v14
	v_max_f32_e32 v109, 0, v15
	v_pk_fma_f32 v[50:51], v[252:253], v[108:109], v[50:51]
	v_max_f32_e32 v210, 0, v16
	v_max_f32_e32 v211, 0, v17
	v_pk_fma_f32 v[50:51], v[254:255], v[210:211], v[50:51]
	v_max_f32_e32 v108, 0, v18
	v_max_f32_e32 v109, 0, v19
	v_pk_fma_f32 v[50:51], v[200:201], v[108:109], v[50:51]
	v_max_f32_e32 v210, 0, v20
	v_max_f32_e32 v211, 0, v21
	v_pk_fma_f32 v[50:51], v[202:203], v[210:211], v[50:51]
	v_add_f32_e32 v50, v50, v51
	v_ashrrev_i32_e32 v51, 31, v50
	v_or_b32_e32 v51, 0x80000000, v51
	v_xor_b32_e32 v50, v51, v50
	v_cndmask_b32_e32 v50, v123, v50, vcc
	global_store_dword v243, v50, s[8:9] offset:2048
	s_add_u32 s8, s8, 0x1000
	s_addc_u32 s9, s9, 0
	v_mfma_f32_32x32x16_bf16 v[6:21], v[86:89], v[38:41], 0
	v_mfma_f32_32x32x16_bf16 v[6:21], v[90:93], v[42:45], v[6:21]
	v_mfma_f32_32x32x16_bf16 v[6:21], v[94:97], v[46:49], v[6:21]
	v_mfma_f32_32x32x16_bf16 v[6:21], v[98:101], v[196:199], v[6:21]
	s_cmpk_gt_i32 s11, 400
	s_cselect_b64 vcc, -1, 0
	v_max_f32_e32 v108, 0, v212
	v_max_f32_e32 v109, 0, v213
	v_pk_mul_f32 v[0:1], v[22:23], v[108:109]
	v_max_f32_e32 v210, 0, v214
	v_max_f32_e32 v211, 0, v215
	v_pk_fma_f32 v[0:1], v[24:25], v[210:211], v[0:1]
	v_max_f32_e32 v108, 0, v216
	v_max_f32_e32 v109, 0, v217
	v_pk_fma_f32 v[0:1], v[26:27], v[108:109], v[0:1]
	v_max_f32_e32 v210, 0, v218
	v_max_f32_e32 v211, 0, v219
	v_pk_fma_f32 v[0:1], v[28:29], v[210:211], v[0:1]
	v_max_f32_e32 v108, 0, v220
	v_max_f32_e32 v109, 0, v221
	v_pk_fma_f32 v[0:1], v[30:31], v[108:109], v[0:1]
	v_max_f32_e32 v210, 0, v222
	v_max_f32_e32 v211, 0, v223
	v_pk_fma_f32 v[0:1], v[32:33], v[210:211], v[0:1]
	v_max_f32_e32 v108, 0, v224
	v_max_f32_e32 v109, 0, v225
	v_pk_fma_f32 v[0:1], v[34:35], v[108:109], v[0:1]
	v_max_f32_e32 v210, 0, v226
	v_max_f32_e32 v211, 0, v227
	v_pk_fma_f32 v[0:1], v[36:37], v[210:211], v[0:1]
	v_add_f32_e32 v0, v0, v1
	v_ashrrev_i32_e32 v1, 31, v0
	v_or_b32_e32 v1, 0x80000000, v1
	v_xor_b32_e32 v0, v1, v0
	v_cndmask_b32_e32 v184, v123, v0, vcc
	s_add_i32 m0, s10, 65536
	s_nop 0
	global_load_lds_dwordx4 v102, s[6:7]
	s_add_i32 m0, s10, 66560
	s_nop 0
	global_load_lds_dwordx4 v110, s[6:7]
	s_add_i32 m0, s10, 67584
	s_nop 0
	global_load_lds_dwordx4 v112, s[6:7]
	s_add_i32 m0, s10, 68608
	s_nop 0
	global_load_lds_dwordx4 v193, s[6:7]
	s_add_u32 s6, s6, 0x8000
	s_addc_u32 s7, s7, 0
	s_waitcnt vmcnt(14)
	v_add_u32_e32 v228, 0x10000, v5
	ds_read_b128 v[38:41], v228 offset:43264
	v_add_u32_e32 v228, 0x10000, v52
	ds_read_b128 v[42:45], v228 offset:43264
	v_add_u32_e32 v228, 0x10000, v55
	ds_read_b128 v[46:49], v228 offset:43264
	v_add_u32_e32 v228, 0x10000, v56
	ds_read_b128 v[196:199], v228 offset:43264
	s_waitcnt lgkmcnt(3)
	v_mfma_f32_32x32x16_bf16 v[212:227], v[70:73], v[38:41], 0
	s_waitcnt lgkmcnt(2)
	v_mfma_f32_32x32x16_bf16 v[212:227], v[74:77], v[42:45], v[212:227]
	s_waitcnt lgkmcnt(1)
	v_mfma_f32_32x32x16_bf16 v[212:227], v[78:81], v[46:49], v[212:227]
	s_waitcnt lgkmcnt(0)
	v_mfma_f32_32x32x16_bf16 v[212:227], v[82:85], v[196:199], v[212:227]
	s_cmpk_gt_i32 s11, 400
	s_cselect_b64 vcc, -1, 0
	v_max_f32_e32 v108, 0, v6
	v_max_f32_e32 v109, 0, v7
	v_pk_mul_f32 v[50:51], v[244:245], v[108:109]
	v_max_f32_e32 v210, 0, v8
	v_max_f32_e32 v211, 0, v9
	v_pk_fma_f32 v[50:51], v[246:247], v[210:211], v[50:51]
	v_max_f32_e32 v108, 0, v10
	v_max_f32_e32 v109, 0, v11
	v_pk_fma_f32 v[50:51], v[248:249], v[108:109], v[50:51]
	v_max_f32_e32 v210, 0, v12
	v_max_f32_e32 v211, 0, v13
	v_pk_fma_f32 v[50:51], v[250:251], v[210:211], v[50:51]
	v_max_f32_e32 v108, 0, v14
	v_max_f32_e32 v109, 0, v15
	v_pk_fma_f32 v[50:51], v[252:253], v[108:109], v[50:51]
	v_max_f32_e32 v210, 0, v16
	v_max_f32_e32 v211, 0, v17
	v_pk_fma_f32 v[50:51], v[254:255], v[210:211], v[50:51]
	v_max_f32_e32 v108, 0, v18
	v_max_f32_e32 v109, 0, v19
	v_pk_fma_f32 v[50:51], v[200:201], v[108:109], v[50:51]
	v_max_f32_e32 v210, 0, v20
	v_max_f32_e32 v211, 0, v21
	v_pk_fma_f32 v[50:51], v[202:203], v[210:211], v[50:51]
	v_add_f32_e32 v50, v50, v51
	v_ashrrev_i32_e32 v51, 31, v50
	v_or_b32_e32 v51, 0x80000000, v51
	v_xor_b32_e32 v50, v51, v50
	v_cndmask_b32_e32 v50, v123, v50, vcc
	global_store_dword v243, v50, s[8:9]
	v_mfma_f32_32x32x16_bf16 v[6:21], v[86:89], v[38:41], 0
	v_mfma_f32_32x32x16_bf16 v[6:21], v[90:93], v[42:45], v[6:21]
	v_mfma_f32_32x32x16_bf16 v[6:21], v[94:97], v[46:49], v[6:21]
	v_mfma_f32_32x32x16_bf16 v[6:21], v[98:101], v[196:199], v[6:21]
	s_cmpk_gt_i32 s11, 408
	s_cselect_b64 vcc, -1, 0
	v_max_f32_e32 v108, 0, v212
	v_max_f32_e32 v109, 0, v213
	v_pk_mul_f32 v[0:1], v[22:23], v[108:109]
	v_max_f32_e32 v210, 0, v214
	v_max_f32_e32 v211, 0, v215
	v_pk_fma_f32 v[0:1], v[24:25], v[210:211], v[0:1]
	v_max_f32_e32 v108, 0, v216
	v_max_f32_e32 v109, 0, v217
	v_pk_fma_f32 v[0:1], v[26:27], v[108:109], v[0:1]
	v_max_f32_e32 v210, 0, v218
	v_max_f32_e32 v211, 0, v219
	v_pk_fma_f32 v[0:1], v[28:29], v[210:211], v[0:1]
	v_max_f32_e32 v108, 0, v220
	v_max_f32_e32 v109, 0, v221
	v_pk_fma_f32 v[0:1], v[30:31], v[108:109], v[0:1]
	v_max_f32_e32 v210, 0, v222
	v_max_f32_e32 v211, 0, v223
	v_pk_fma_f32 v[0:1], v[32:33], v[210:211], v[0:1]
	v_max_f32_e32 v108, 0, v224
	v_max_f32_e32 v109, 0, v225
	v_pk_fma_f32 v[0:1], v[34:35], v[108:109], v[0:1]
	v_max_f32_e32 v210, 0, v226
	v_max_f32_e32 v211, 0, v227
	v_pk_fma_f32 v[0:1], v[36:37], v[210:211], v[0:1]
	v_add_f32_e32 v0, v0, v1
	v_ashrrev_i32_e32 v1, 31, v0
	v_or_b32_e32 v1, 0x80000000, v1
	v_xor_b32_e32 v0, v1, v0
	v_cndmask_b32_e32 v183, v123, v0, vcc
	s_add_i32 m0, s10, 98304
	s_nop 0
	global_load_lds_dwordx4 v102, s[6:7]
	s_add_i32 m0, s10, 99328
	s_nop 0
	global_load_lds_dwordx4 v110, s[6:7]
	s_add_i32 m0, s10, 100352
	s_nop 0
	global_load_lds_dwordx4 v112, s[6:7]
	s_add_i32 m0, s10, 101376
	s_nop 0
	global_load_lds_dwordx4 v193, s[6:7]
	s_add_u32 s6, s6, 0x8000
	s_addc_u32 s7, s7, 0
	s_waitcnt vmcnt(15)
	ds_read_b128 v[38:41], v5 offset:10496
	ds_read_b128 v[42:45], v52 offset:10496
	ds_read_b128 v[46:49], v55 offset:10496
	ds_read_b128 v[196:199], v56 offset:10496
	s_waitcnt lgkmcnt(3)
	v_mfma_f32_32x32x16_bf16 v[212:227], v[70:73], v[38:41], 0
	s_waitcnt lgkmcnt(2)
	v_mfma_f32_32x32x16_bf16 v[212:227], v[74:77], v[42:45], v[212:227]
	s_waitcnt lgkmcnt(1)
	v_mfma_f32_32x32x16_bf16 v[212:227], v[78:81], v[46:49], v[212:227]
	s_waitcnt lgkmcnt(0)
	v_mfma_f32_32x32x16_bf16 v[212:227], v[82:85], v[196:199], v[212:227]
	s_cmpk_gt_i32 s11, 408
	s_cselect_b64 vcc, -1, 0
	v_max_f32_e32 v108, 0, v6
	v_max_f32_e32 v109, 0, v7
	v_pk_mul_f32 v[50:51], v[244:245], v[108:109]
	v_max_f32_e32 v210, 0, v8
	v_max_f32_e32 v211, 0, v9
	v_pk_fma_f32 v[50:51], v[246:247], v[210:211], v[50:51]
	v_max_f32_e32 v108, 0, v10
	v_max_f32_e32 v109, 0, v11
	v_pk_fma_f32 v[50:51], v[248:249], v[108:109], v[50:51]
	v_max_f32_e32 v210, 0, v12
	v_max_f32_e32 v211, 0, v13
	v_pk_fma_f32 v[50:51], v[250:251], v[210:211], v[50:51]
	v_max_f32_e32 v108, 0, v14
	v_max_f32_e32 v109, 0, v15
	v_pk_fma_f32 v[50:51], v[252:253], v[108:109], v[50:51]
	v_max_f32_e32 v210, 0, v16
	v_max_f32_e32 v211, 0, v17
	v_pk_fma_f32 v[50:51], v[254:255], v[210:211], v[50:51]
	v_max_f32_e32 v108, 0, v18
	v_max_f32_e32 v109, 0, v19
	v_pk_fma_f32 v[50:51], v[200:201], v[108:109], v[50:51]
	v_max_f32_e32 v210, 0, v20
	v_max_f32_e32 v211, 0, v21
	v_pk_fma_f32 v[50:51], v[202:203], v[210:211], v[50:51]
	v_add_f32_e32 v50, v50, v51
	v_ashrrev_i32_e32 v51, 31, v50
	v_or_b32_e32 v51, 0x80000000, v51
	v_xor_b32_e32 v50, v51, v50
	v_cndmask_b32_e32 v50, v123, v50, vcc
	global_store_dword v243, v50, s[8:9] offset:2048
	s_add_u32 s8, s8, 0x1000
	s_addc_u32 s9, s9, 0
	v_mfma_f32_32x32x16_bf16 v[6:21], v[86:89], v[38:41], 0
	v_mfma_f32_32x32x16_bf16 v[6:21], v[90:93], v[42:45], v[6:21]
	v_mfma_f32_32x32x16_bf16 v[6:21], v[94:97], v[46:49], v[6:21]
	v_mfma_f32_32x32x16_bf16 v[6:21], v[98:101], v[196:199], v[6:21]
	s_cmpk_gt_i32 s11, 416
	s_cselect_b64 vcc, -1, 0
	v_max_f32_e32 v108, 0, v212
	v_max_f32_e32 v109, 0, v213
	v_pk_mul_f32 v[0:1], v[22:23], v[108:109]
	v_max_f32_e32 v210, 0, v214
	v_max_f32_e32 v211, 0, v215
	v_pk_fma_f32 v[0:1], v[24:25], v[210:211], v[0:1]
	v_max_f32_e32 v108, 0, v216
	v_max_f32_e32 v109, 0, v217
	v_pk_fma_f32 v[0:1], v[26:27], v[108:109], v[0:1]
	v_max_f32_e32 v210, 0, v218
	v_max_f32_e32 v211, 0, v219
	v_pk_fma_f32 v[0:1], v[28:29], v[210:211], v[0:1]
	v_max_f32_e32 v108, 0, v220
	v_max_f32_e32 v109, 0, v221
	v_pk_fma_f32 v[0:1], v[30:31], v[108:109], v[0:1]
	v_max_f32_e32 v210, 0, v222
	v_max_f32_e32 v211, 0, v223
	v_pk_fma_f32 v[0:1], v[32:33], v[210:211], v[0:1]
	v_max_f32_e32 v108, 0, v224
	v_max_f32_e32 v109, 0, v225
	v_pk_fma_f32 v[0:1], v[34:35], v[108:109], v[0:1]
	v_max_f32_e32 v210, 0, v226
	v_max_f32_e32 v211, 0, v227
	v_pk_fma_f32 v[0:1], v[36:37], v[210:211], v[0:1]
	v_add_f32_e32 v0, v0, v1
	v_ashrrev_i32_e32 v1, 31, v0
	v_or_b32_e32 v1, 0x80000000, v1
	v_xor_b32_e32 v0, v1, v0
	v_cndmask_b32_e32 v187, v123, v0, vcc
	s_add_i32 m0, s10, 0
	s_nop 0
	global_load_lds_dwordx4 v102, s[6:7]
	s_add_i32 m0, s10, 1024
	s_nop 0
	global_load_lds_dwordx4 v110, s[6:7]
	s_add_i32 m0, s10, 2048
	s_nop 0
	global_load_lds_dwordx4 v112, s[6:7]
	s_add_i32 m0, s10, 3072
	s_nop 0
	global_load_lds_dwordx4 v193, s[6:7]
	s_add_u32 s6, s6, 0x8000
	s_addc_u32 s7, s7, 0
	s_waitcnt vmcnt(15)
	ds_read_b128 v[38:41], v5 offset:43264
	ds_read_b128 v[42:45], v52 offset:43264
	ds_read_b128 v[46:49], v55 offset:43264
	ds_read_b128 v[196:199], v56 offset:43264
	s_waitcnt lgkmcnt(3)
	v_mfma_f32_32x32x16_bf16 v[212:227], v[70:73], v[38:41], 0
	s_waitcnt lgkmcnt(2)
	v_mfma_f32_32x32x16_bf16 v[212:227], v[74:77], v[42:45], v[212:227]
	s_waitcnt lgkmcnt(1)
	v_mfma_f32_32x32x16_bf16 v[212:227], v[78:81], v[46:49], v[212:227]
	s_waitcnt lgkmcnt(0)
	v_mfma_f32_32x32x16_bf16 v[212:227], v[82:85], v[196:199], v[212:227]
	s_cmpk_gt_i32 s11, 416
	s_cselect_b64 vcc, -1, 0
	v_max_f32_e32 v108, 0, v6
	v_max_f32_e32 v109, 0, v7
	v_pk_mul_f32 v[50:51], v[244:245], v[108:109]
	v_max_f32_e32 v210, 0, v8
	v_max_f32_e32 v211, 0, v9
	v_pk_fma_f32 v[50:51], v[246:247], v[210:211], v[50:51]
	v_max_f32_e32 v108, 0, v10
	v_max_f32_e32 v109, 0, v11
	v_pk_fma_f32 v[50:51], v[248:249], v[108:109], v[50:51]
	v_max_f32_e32 v210, 0, v12
	v_max_f32_e32 v211, 0, v13
	v_pk_fma_f32 v[50:51], v[250:251], v[210:211], v[50:51]
	v_max_f32_e32 v108, 0, v14
	v_max_f32_e32 v109, 0, v15
	v_pk_fma_f32 v[50:51], v[252:253], v[108:109], v[50:51]
	v_max_f32_e32 v210, 0, v16
	v_max_f32_e32 v211, 0, v17
	v_pk_fma_f32 v[50:51], v[254:255], v[210:211], v[50:51]
	v_max_f32_e32 v108, 0, v18
	v_max_f32_e32 v109, 0, v19
	v_pk_fma_f32 v[50:51], v[200:201], v[108:109], v[50:51]
	v_max_f32_e32 v210, 0, v20
	v_max_f32_e32 v211, 0, v21
	v_pk_fma_f32 v[50:51], v[202:203], v[210:211], v[50:51]
	v_add_f32_e32 v50, v50, v51
	v_ashrrev_i32_e32 v51, 31, v50
	v_or_b32_e32 v51, 0x80000000, v51
	v_xor_b32_e32 v50, v51, v50
	v_cndmask_b32_e32 v50, v123, v50, vcc
	global_store_dword v243, v50, s[8:9]
	v_mfma_f32_32x32x16_bf16 v[6:21], v[86:89], v[38:41], 0
	v_mfma_f32_32x32x16_bf16 v[6:21], v[90:93], v[42:45], v[6:21]
	v_mfma_f32_32x32x16_bf16 v[6:21], v[94:97], v[46:49], v[6:21]
	v_mfma_f32_32x32x16_bf16 v[6:21], v[98:101], v[196:199], v[6:21]
	s_cmpk_gt_i32 s11, 424
	s_cselect_b64 vcc, -1, 0
	v_max_f32_e32 v108, 0, v212
	v_max_f32_e32 v109, 0, v213
	v_pk_mul_f32 v[0:1], v[22:23], v[108:109]
	v_max_f32_e32 v210, 0, v214
	v_max_f32_e32 v211, 0, v215
	v_pk_fma_f32 v[0:1], v[24:25], v[210:211], v[0:1]
	v_max_f32_e32 v108, 0, v216
	v_max_f32_e32 v109, 0, v217
	v_pk_fma_f32 v[0:1], v[26:27], v[108:109], v[0:1]
	v_max_f32_e32 v210, 0, v218
	v_max_f32_e32 v211, 0, v219
	v_pk_fma_f32 v[0:1], v[28:29], v[210:211], v[0:1]
	v_max_f32_e32 v108, 0, v220
	v_max_f32_e32 v109, 0, v221
	v_pk_fma_f32 v[0:1], v[30:31], v[108:109], v[0:1]
	v_max_f32_e32 v210, 0, v222
	v_max_f32_e32 v211, 0, v223
	v_pk_fma_f32 v[0:1], v[32:33], v[210:211], v[0:1]
	v_max_f32_e32 v108, 0, v224
	v_max_f32_e32 v109, 0, v225
	v_pk_fma_f32 v[0:1], v[34:35], v[108:109], v[0:1]
	v_max_f32_e32 v210, 0, v226
	v_max_f32_e32 v211, 0, v227
	v_pk_fma_f32 v[0:1], v[36:37], v[210:211], v[0:1]
	v_add_f32_e32 v0, v0, v1
	v_ashrrev_i32_e32 v1, 31, v0
	v_or_b32_e32 v1, 0x80000000, v1
	v_xor_b32_e32 v0, v1, v0
	v_cndmask_b32_e32 v186, v123, v0, vcc
	s_add_i32 m0, s10, 32768
	s_nop 0
	global_load_lds_dwordx4 v102, s[6:7]
	s_add_i32 m0, s10, 33792
	s_nop 0
	global_load_lds_dwordx4 v110, s[6:7]
	s_add_i32 m0, s10, 34816
	s_nop 0
	global_load_lds_dwordx4 v112, s[6:7]
	s_add_i32 m0, s10, 35840
	s_nop 0
	global_load_lds_dwordx4 v193, s[6:7]
	s_add_u32 s6, s6, 0x8000
	s_addc_u32 s7, s7, 0
	s_waitcnt vmcnt(15)
	v_add_u32_e32 v228, 0x10000, v5
	ds_read_b128 v[38:41], v228 offset:10496
	v_add_u32_e32 v228, 0x10000, v52
	ds_read_b128 v[42:45], v228 offset:10496
	v_add_u32_e32 v228, 0x10000, v55
	ds_read_b128 v[46:49], v228 offset:10496
	v_add_u32_e32 v228, 0x10000, v56
	ds_read_b128 v[196:199], v228 offset:10496
	s_waitcnt lgkmcnt(3)
	v_mfma_f32_32x32x16_bf16 v[212:227], v[70:73], v[38:41], 0
	s_waitcnt lgkmcnt(2)
	v_mfma_f32_32x32x16_bf16 v[212:227], v[74:77], v[42:45], v[212:227]
	s_waitcnt lgkmcnt(1)
	v_mfma_f32_32x32x16_bf16 v[212:227], v[78:81], v[46:49], v[212:227]
	s_waitcnt lgkmcnt(0)
	v_mfma_f32_32x32x16_bf16 v[212:227], v[82:85], v[196:199], v[212:227]
	s_cmpk_gt_i32 s11, 424
	s_cselect_b64 vcc, -1, 0
	v_max_f32_e32 v108, 0, v6
	v_max_f32_e32 v109, 0, v7
	v_pk_mul_f32 v[50:51], v[244:245], v[108:109]
	v_max_f32_e32 v210, 0, v8
	v_max_f32_e32 v211, 0, v9
	v_pk_fma_f32 v[50:51], v[246:247], v[210:211], v[50:51]
	v_max_f32_e32 v108, 0, v10
	v_max_f32_e32 v109, 0, v11
	v_pk_fma_f32 v[50:51], v[248:249], v[108:109], v[50:51]
	v_max_f32_e32 v210, 0, v12
	v_max_f32_e32 v211, 0, v13
	v_pk_fma_f32 v[50:51], v[250:251], v[210:211], v[50:51]
	v_max_f32_e32 v108, 0, v14
	v_max_f32_e32 v109, 0, v15
	v_pk_fma_f32 v[50:51], v[252:253], v[108:109], v[50:51]
	v_max_f32_e32 v210, 0, v16
	v_max_f32_e32 v211, 0, v17
	v_pk_fma_f32 v[50:51], v[254:255], v[210:211], v[50:51]
	v_max_f32_e32 v108, 0, v18
	v_max_f32_e32 v109, 0, v19
	v_pk_fma_f32 v[50:51], v[200:201], v[108:109], v[50:51]
	v_max_f32_e32 v210, 0, v20
	v_max_f32_e32 v211, 0, v21
	v_pk_fma_f32 v[50:51], v[202:203], v[210:211], v[50:51]
	v_add_f32_e32 v50, v50, v51
	v_ashrrev_i32_e32 v51, 31, v50
	v_or_b32_e32 v51, 0x80000000, v51
	v_xor_b32_e32 v50, v51, v50
	v_cndmask_b32_e32 v50, v123, v50, vcc
	global_store_dword v243, v50, s[8:9] offset:2048
	s_add_u32 s8, s8, 0x1000
	s_addc_u32 s9, s9, 0
	v_mfma_f32_32x32x16_bf16 v[6:21], v[86:89], v[38:41], 0
	v_mfma_f32_32x32x16_bf16 v[6:21], v[90:93], v[42:45], v[6:21]
	v_mfma_f32_32x32x16_bf16 v[6:21], v[94:97], v[46:49], v[6:21]
	v_mfma_f32_32x32x16_bf16 v[6:21], v[98:101], v[196:199], v[6:21]
	s_cmpk_gt_i32 s11, 432
	s_cselect_b64 vcc, -1, 0
	v_max_f32_e32 v108, 0, v212
	v_max_f32_e32 v109, 0, v213
	v_pk_mul_f32 v[0:1], v[22:23], v[108:109]
	v_max_f32_e32 v210, 0, v214
	v_max_f32_e32 v211, 0, v215
	v_pk_fma_f32 v[0:1], v[24:25], v[210:211], v[0:1]
	v_max_f32_e32 v108, 0, v216
	v_max_f32_e32 v109, 0, v217
	v_pk_fma_f32 v[0:1], v[26:27], v[108:109], v[0:1]
	v_max_f32_e32 v210, 0, v218
	v_max_f32_e32 v211, 0, v219
	v_pk_fma_f32 v[0:1], v[28:29], v[210:211], v[0:1]
	v_max_f32_e32 v108, 0, v220
	v_max_f32_e32 v109, 0, v221
	v_pk_fma_f32 v[0:1], v[30:31], v[108:109], v[0:1]
	v_max_f32_e32 v210, 0, v222
	v_max_f32_e32 v211, 0, v223
	v_pk_fma_f32 v[0:1], v[32:33], v[210:211], v[0:1]
	v_max_f32_e32 v108, 0, v224
	v_max_f32_e32 v109, 0, v225
	v_pk_fma_f32 v[0:1], v[34:35], v[108:109], v[0:1]
	v_max_f32_e32 v210, 0, v226
	v_max_f32_e32 v211, 0, v227
	v_pk_fma_f32 v[0:1], v[36:37], v[210:211], v[0:1]
	v_add_f32_e32 v0, v0, v1
	v_ashrrev_i32_e32 v1, 31, v0
	v_or_b32_e32 v1, 0x80000000, v1
	v_xor_b32_e32 v0, v1, v0
	v_cndmask_b32_e32 v189, v123, v0, vcc
	s_add_i32 m0, s10, 65536
	s_nop 0
	global_load_lds_dwordx4 v102, s[6:7]
	s_add_i32 m0, s10, 66560
	s_nop 0
	global_load_lds_dwordx4 v110, s[6:7]
	s_add_i32 m0, s10, 67584
	s_nop 0
	global_load_lds_dwordx4 v112, s[6:7]
	s_add_i32 m0, s10, 68608
	s_nop 0
	global_load_lds_dwordx4 v193, s[6:7]
	s_add_u32 s6, s6, 0x8000
	s_addc_u32 s7, s7, 0
	s_waitcnt vmcnt(15)
	v_add_u32_e32 v228, 0x10000, v5
	ds_read_b128 v[38:41], v228 offset:43264
	v_add_u32_e32 v228, 0x10000, v52
	ds_read_b128 v[42:45], v228 offset:43264
	v_add_u32_e32 v228, 0x10000, v55
	ds_read_b128 v[46:49], v228 offset:43264
	v_add_u32_e32 v228, 0x10000, v56
	ds_read_b128 v[196:199], v228 offset:43264
	s_waitcnt lgkmcnt(3)
	v_mfma_f32_32x32x16_bf16 v[212:227], v[70:73], v[38:41], 0
	s_waitcnt lgkmcnt(2)
	v_mfma_f32_32x32x16_bf16 v[212:227], v[74:77], v[42:45], v[212:227]
	s_waitcnt lgkmcnt(1)
	v_mfma_f32_32x32x16_bf16 v[212:227], v[78:81], v[46:49], v[212:227]
	s_waitcnt lgkmcnt(0)
	v_mfma_f32_32x32x16_bf16 v[212:227], v[82:85], v[196:199], v[212:227]
	s_cmpk_gt_i32 s11, 432
	s_cselect_b64 vcc, -1, 0
	v_max_f32_e32 v108, 0, v6
	v_max_f32_e32 v109, 0, v7
	v_pk_mul_f32 v[50:51], v[244:245], v[108:109]
	v_max_f32_e32 v210, 0, v8
	v_max_f32_e32 v211, 0, v9
	v_pk_fma_f32 v[50:51], v[246:247], v[210:211], v[50:51]
	v_max_f32_e32 v108, 0, v10
	v_max_f32_e32 v109, 0, v11
	v_pk_fma_f32 v[50:51], v[248:249], v[108:109], v[50:51]
	v_max_f32_e32 v210, 0, v12
	v_max_f32_e32 v211, 0, v13
	v_pk_fma_f32 v[50:51], v[250:251], v[210:211], v[50:51]
	v_max_f32_e32 v108, 0, v14
	v_max_f32_e32 v109, 0, v15
	v_pk_fma_f32 v[50:51], v[252:253], v[108:109], v[50:51]
	v_max_f32_e32 v210, 0, v16
	v_max_f32_e32 v211, 0, v17
	v_pk_fma_f32 v[50:51], v[254:255], v[210:211], v[50:51]
	v_max_f32_e32 v108, 0, v18
	v_max_f32_e32 v109, 0, v19
	v_pk_fma_f32 v[50:51], v[200:201], v[108:109], v[50:51]
	v_max_f32_e32 v210, 0, v20
	v_max_f32_e32 v211, 0, v21
	v_pk_fma_f32 v[50:51], v[202:203], v[210:211], v[50:51]
	v_add_f32_e32 v50, v50, v51
	v_ashrrev_i32_e32 v51, 31, v50
	v_or_b32_e32 v51, 0x80000000, v51
	v_xor_b32_e32 v50, v51, v50
	v_cndmask_b32_e32 v50, v123, v50, vcc
	global_store_dword v243, v50, s[8:9]
	v_mfma_f32_32x32x16_bf16 v[6:21], v[86:89], v[38:41], 0
	v_mfma_f32_32x32x16_bf16 v[6:21], v[90:93], v[42:45], v[6:21]
	v_mfma_f32_32x32x16_bf16 v[6:21], v[94:97], v[46:49], v[6:21]
	v_mfma_f32_32x32x16_bf16 v[6:21], v[98:101], v[196:199], v[6:21]
	s_cmpk_gt_i32 s11, 440
	s_cselect_b64 vcc, -1, 0
	v_max_f32_e32 v108, 0, v212
	v_max_f32_e32 v109, 0, v213
	v_pk_mul_f32 v[0:1], v[22:23], v[108:109]
	v_max_f32_e32 v210, 0, v214
	v_max_f32_e32 v211, 0, v215
	v_pk_fma_f32 v[0:1], v[24:25], v[210:211], v[0:1]
	v_max_f32_e32 v108, 0, v216
	v_max_f32_e32 v109, 0, v217
	v_pk_fma_f32 v[0:1], v[26:27], v[108:109], v[0:1]
	v_max_f32_e32 v210, 0, v218
	v_max_f32_e32 v211, 0, v219
	v_pk_fma_f32 v[0:1], v[28:29], v[210:211], v[0:1]
	v_max_f32_e32 v108, 0, v220
	v_max_f32_e32 v109, 0, v221
	v_pk_fma_f32 v[0:1], v[30:31], v[108:109], v[0:1]
	v_max_f32_e32 v210, 0, v222
	v_max_f32_e32 v211, 0, v223
	v_pk_fma_f32 v[0:1], v[32:33], v[210:211], v[0:1]
	v_max_f32_e32 v108, 0, v224
	v_max_f32_e32 v109, 0, v225
	v_pk_fma_f32 v[0:1], v[34:35], v[108:109], v[0:1]
	v_max_f32_e32 v210, 0, v226
	v_max_f32_e32 v211, 0, v227
	v_pk_fma_f32 v[0:1], v[36:37], v[210:211], v[0:1]
	v_add_f32_e32 v0, v0, v1
	v_ashrrev_i32_e32 v1, 31, v0
	v_or_b32_e32 v1, 0x80000000, v1
	v_xor_b32_e32 v0, v1, v0
	v_cndmask_b32_e32 v188, v123, v0, vcc
	v_max_f32_e32 v108, 0, v6
	v_max_f32_e32 v109, 0, v7
	v_pk_mul_f32 v[50:51], v[244:245], v[108:109]
	v_max_f32_e32 v210, 0, v8
	v_max_f32_e32 v211, 0, v9
	v_pk_fma_f32 v[50:51], v[246:247], v[210:211], v[50:51]
	v_max_f32_e32 v108, 0, v10
	v_max_f32_e32 v109, 0, v11
	v_pk_fma_f32 v[50:51], v[248:249], v[108:109], v[50:51]
	v_max_f32_e32 v210, 0, v12
	v_max_f32_e32 v211, 0, v13
	v_pk_fma_f32 v[50:51], v[250:251], v[210:211], v[50:51]
	v_max_f32_e32 v108, 0, v14
	v_max_f32_e32 v109, 0, v15
	v_pk_fma_f32 v[50:51], v[252:253], v[108:109], v[50:51]
	v_max_f32_e32 v210, 0, v16
	v_max_f32_e32 v211, 0, v17
	v_pk_fma_f32 v[50:51], v[254:255], v[210:211], v[50:51]
	v_max_f32_e32 v108, 0, v18
	v_max_f32_e32 v109, 0, v19
	v_pk_fma_f32 v[50:51], v[200:201], v[108:109], v[50:51]
	v_max_f32_e32 v210, 0, v20
	v_max_f32_e32 v211, 0, v21
	v_pk_fma_f32 v[50:51], v[202:203], v[210:211], v[50:51]
	v_add_f32_e32 v50, v50, v51
	v_ashrrev_i32_e32 v51, 31, v50
	v_or_b32_e32 v51, 0x80000000, v51
	v_xor_b32_e32 v50, v51, v50
	v_cndmask_b32_e32 v50, v123, v50, vcc
	global_store_dword v243, v50, s[8:9] offset:2048
	s_add_u32 s8, s8, 0x1000
	s_addc_u32 s9, s9, 0
	s_cmpk_gt_i32 s81, 56
	s_cbranch_scc0 .Lix_fill_7
	s_add_i32 m0, s10, 98304
	s_nop 0
	global_load_lds_dwordx4 v102, s[6:7]
	s_add_i32 m0, s10, 99328
	s_nop 0
	global_load_lds_dwordx4 v110, s[6:7]
	s_add_i32 m0, s10, 100352
	s_nop 0
	global_load_lds_dwordx4 v112, s[6:7]
	s_add_i32 m0, s10, 101376
	s_nop 0
	global_load_lds_dwordx4 v193, s[6:7]
	s_add_u32 s6, s6, 0x8000
	s_addc_u32 s7, s7, 0
	s_waitcnt vmcnt(16)
	ds_read_b128 v[38:41], v5 offset:10496
	ds_read_b128 v[42:45], v52 offset:10496
	ds_read_b128 v[46:49], v55 offset:10496
	ds_read_b128 v[196:199], v56 offset:10496
	s_waitcnt lgkmcnt(3)
	v_mfma_f32_32x32x16_bf16 v[212:227], v[70:73], v[38:41], 0
	s_waitcnt lgkmcnt(2)
	v_mfma_f32_32x32x16_bf16 v[212:227], v[74:77], v[42:45], v[212:227]
	s_waitcnt lgkmcnt(1)
	v_mfma_f32_32x32x16_bf16 v[212:227], v[78:81], v[46:49], v[212:227]
	s_waitcnt lgkmcnt(0)
	v_mfma_f32_32x32x16_bf16 v[212:227], v[82:85], v[196:199], v[212:227]
	v_mfma_f32_32x32x16_bf16 v[6:21], v[86:89], v[38:41], 0
	v_mfma_f32_32x32x16_bf16 v[6:21], v[90:93], v[42:45], v[6:21]
	v_mfma_f32_32x32x16_bf16 v[6:21], v[94:97], v[46:49], v[6:21]
	v_mfma_f32_32x32x16_bf16 v[6:21], v[98:101], v[196:199], v[6:21]
	s_nop 7
	s_cmpk_gt_i32 s11, 448
	s_cselect_b64 vcc, -1, 0
	v_max_f32_e32 v108, 0, v212
	v_max_f32_e32 v109, 0, v213
	v_pk_mul_f32 v[0:1], v[22:23], v[108:109]
	v_max_f32_e32 v210, 0, v214
	v_max_f32_e32 v211, 0, v215
	v_pk_fma_f32 v[0:1], v[24:25], v[210:211], v[0:1]
	v_max_f32_e32 v108, 0, v216
	v_max_f32_e32 v109, 0, v217
	v_pk_fma_f32 v[0:1], v[26:27], v[108:109], v[0:1]
	v_max_f32_e32 v210, 0, v218
	v_max_f32_e32 v211, 0, v219
	v_pk_fma_f32 v[0:1], v[28:29], v[210:211], v[0:1]
	v_max_f32_e32 v108, 0, v220
	v_max_f32_e32 v109, 0, v221
	v_pk_fma_f32 v[0:1], v[30:31], v[108:109], v[0:1]
	v_max_f32_e32 v210, 0, v222
	v_max_f32_e32 v211, 0, v223
	v_pk_fma_f32 v[0:1], v[32:33], v[210:211], v[0:1]
	v_max_f32_e32 v108, 0, v224
	v_max_f32_e32 v109, 0, v225
	v_pk_fma_f32 v[0:1], v[34:35], v[108:109], v[0:1]
	v_max_f32_e32 v210, 0, v226
	v_max_f32_e32 v211, 0, v227
	v_pk_fma_f32 v[0:1], v[36:37], v[210:211], v[0:1]
	v_add_f32_e32 v0, v0, v1
	v_ashrrev_i32_e32 v1, 31, v0
	v_or_b32_e32 v1, 0x80000000, v1
	v_xor_b32_e32 v0, v1, v0
	v_cndmask_b32_e32 v190, v123, v0, vcc
	s_add_i32 m0, s10, 0
	s_nop 0
	global_load_lds_dwordx4 v102, s[6:7]
	s_add_i32 m0, s10, 1024
	s_nop 0
	global_load_lds_dwordx4 v110, s[6:7]
	s_add_i32 m0, s10, 2048
	s_nop 0
	global_load_lds_dwordx4 v112, s[6:7]
	s_add_i32 m0, s10, 3072
	s_nop 0
	global_load_lds_dwordx4 v193, s[6:7]
	s_add_u32 s6, s6, 0x8000
	s_addc_u32 s7, s7, 0
	s_waitcnt vmcnt(15)
	ds_read_b128 v[38:41], v5 offset:43264
	ds_read_b128 v[42:45], v52 offset:43264
	ds_read_b128 v[46:49], v55 offset:43264
	ds_read_b128 v[196:199], v56 offset:43264
	s_waitcnt lgkmcnt(3)
	v_mfma_f32_32x32x16_bf16 v[212:227], v[70:73], v[38:41], 0
	s_waitcnt lgkmcnt(2)
	v_mfma_f32_32x32x16_bf16 v[212:227], v[74:77], v[42:45], v[212:227]
	s_waitcnt lgkmcnt(1)
	v_mfma_f32_32x32x16_bf16 v[212:227], v[78:81], v[46:49], v[212:227]
	s_waitcnt lgkmcnt(0)
	v_mfma_f32_32x32x16_bf16 v[212:227], v[82:85], v[196:199], v[212:227]
	s_cmpk_gt_i32 s11, 448
	s_cselect_b64 vcc, -1, 0
	v_max_f32_e32 v108, 0, v6
	v_max_f32_e32 v109, 0, v7
	v_pk_mul_f32 v[50:51], v[244:245], v[108:109]
	v_max_f32_e32 v210, 0, v8
	v_max_f32_e32 v211, 0, v9
	v_pk_fma_f32 v[50:51], v[246:247], v[210:211], v[50:51]
	v_max_f32_e32 v108, 0, v10
	v_max_f32_e32 v109, 0, v11
	v_pk_fma_f32 v[50:51], v[248:249], v[108:109], v[50:51]
	v_max_f32_e32 v210, 0, v12
	v_max_f32_e32 v211, 0, v13
	v_pk_fma_f32 v[50:51], v[250:251], v[210:211], v[50:51]
	v_max_f32_e32 v108, 0, v14
	v_max_f32_e32 v109, 0, v15
	v_pk_fma_f32 v[50:51], v[252:253], v[108:109], v[50:51]
	v_max_f32_e32 v210, 0, v16
	v_max_f32_e32 v211, 0, v17
	v_pk_fma_f32 v[50:51], v[254:255], v[210:211], v[50:51]
	v_max_f32_e32 v108, 0, v18
	v_max_f32_e32 v109, 0, v19
	v_pk_fma_f32 v[50:51], v[200:201], v[108:109], v[50:51]
	v_max_f32_e32 v210, 0, v20
	v_max_f32_e32 v211, 0, v21
	v_pk_fma_f32 v[50:51], v[202:203], v[210:211], v[50:51]
	v_add_f32_e32 v50, v50, v51
	v_ashrrev_i32_e32 v51, 31, v50
	v_or_b32_e32 v51, 0x80000000, v51
	v_xor_b32_e32 v50, v51, v50
	v_cndmask_b32_e32 v50, v123, v50, vcc
	global_store_dword v243, v50, s[8:9]
	v_mfma_f32_32x32x16_bf16 v[6:21], v[86:89], v[38:41], 0
	v_mfma_f32_32x32x16_bf16 v[6:21], v[90:93], v[42:45], v[6:21]
	v_mfma_f32_32x32x16_bf16 v[6:21], v[94:97], v[46:49], v[6:21]
	v_mfma_f32_32x32x16_bf16 v[6:21], v[98:101], v[196:199], v[6:21]
	s_cmpk_gt_i32 s11, 456
	s_cselect_b64 vcc, -1, 0
	v_max_f32_e32 v108, 0, v212
	v_max_f32_e32 v109, 0, v213
	v_pk_mul_f32 v[0:1], v[22:23], v[108:109]
	v_max_f32_e32 v210, 0, v214
	v_max_f32_e32 v211, 0, v215
	v_pk_fma_f32 v[0:1], v[24:25], v[210:211], v[0:1]
	v_max_f32_e32 v108, 0, v216
	v_max_f32_e32 v109, 0, v217
	v_pk_fma_f32 v[0:1], v[26:27], v[108:109], v[0:1]
	v_max_f32_e32 v210, 0, v218
	v_max_f32_e32 v211, 0, v219
	v_pk_fma_f32 v[0:1], v[28:29], v[210:211], v[0:1]
	v_max_f32_e32 v108, 0, v220
	v_max_f32_e32 v109, 0, v221
	v_pk_fma_f32 v[0:1], v[30:31], v[108:109], v[0:1]
	v_max_f32_e32 v210, 0, v222
	v_max_f32_e32 v211, 0, v223
	v_pk_fma_f32 v[0:1], v[32:33], v[210:211], v[0:1]
	v_max_f32_e32 v108, 0, v224
	v_max_f32_e32 v109, 0, v225
	v_pk_fma_f32 v[0:1], v[34:35], v[108:109], v[0:1]
	v_max_f32_e32 v210, 0, v226
	v_max_f32_e32 v211, 0, v227
	v_pk_fma_f32 v[0:1], v[36:37], v[210:211], v[0:1]
	v_add_f32_e32 v0, v0, v1
	v_ashrrev_i32_e32 v1, 31, v0
	v_or_b32_e32 v1, 0x80000000, v1
	v_xor_b32_e32 v0, v1, v0
	v_cndmask_b32_e32 v53, v123, v0, vcc
	s_add_i32 m0, s10, 32768
	s_nop 0
	global_load_lds_dwordx4 v102, s[6:7]
	s_add_i32 m0, s10, 33792
	s_nop 0
	global_load_lds_dwordx4 v110, s[6:7]
	s_add_i32 m0, s10, 34816
	s_nop 0
	global_load_lds_dwordx4 v112, s[6:7]
	s_add_i32 m0, s10, 35840
	s_nop 0
	global_load_lds_dwordx4 v193, s[6:7]
	s_add_u32 s6, s6, 0x8000
	s_addc_u32 s7, s7, 0
	s_waitcnt vmcnt(15)
	v_add_u32_e32 v228, 0x10000, v5
	ds_read_b128 v[38:41], v228 offset:10496
	v_add_u32_e32 v228, 0x10000, v52
	ds_read_b128 v[42:45], v228 offset:10496
	v_add_u32_e32 v228, 0x10000, v55
	ds_read_b128 v[46:49], v228 offset:10496
	v_add_u32_e32 v228, 0x10000, v56
	ds_read_b128 v[196:199], v228 offset:10496
	s_waitcnt lgkmcnt(3)
	v_mfma_f32_32x32x16_bf16 v[212:227], v[70:73], v[38:41], 0
	s_waitcnt lgkmcnt(2)
	v_mfma_f32_32x32x16_bf16 v[212:227], v[74:77], v[42:45], v[212:227]
	s_waitcnt lgkmcnt(1)
	v_mfma_f32_32x32x16_bf16 v[212:227], v[78:81], v[46:49], v[212:227]
	s_waitcnt lgkmcnt(0)
	v_mfma_f32_32x32x16_bf16 v[212:227], v[82:85], v[196:199], v[212:227]
	s_cmpk_gt_i32 s11, 456
	s_cselect_b64 vcc, -1, 0
	v_max_f32_e32 v108, 0, v6
	v_max_f32_e32 v109, 0, v7
	v_pk_mul_f32 v[50:51], v[244:245], v[108:109]
	v_max_f32_e32 v210, 0, v8
	v_max_f32_e32 v211, 0, v9
	v_pk_fma_f32 v[50:51], v[246:247], v[210:211], v[50:51]
	v_max_f32_e32 v108, 0, v10
	v_max_f32_e32 v109, 0, v11
	v_pk_fma_f32 v[50:51], v[248:249], v[108:109], v[50:51]
	v_max_f32_e32 v210, 0, v12
	v_max_f32_e32 v211, 0, v13
	v_pk_fma_f32 v[50:51], v[250:251], v[210:211], v[50:51]
	v_max_f32_e32 v108, 0, v14
	v_max_f32_e32 v109, 0, v15
	v_pk_fma_f32 v[50:51], v[252:253], v[108:109], v[50:51]
	v_max_f32_e32 v210, 0, v16
	v_max_f32_e32 v211, 0, v17
	v_pk_fma_f32 v[50:51], v[254:255], v[210:211], v[50:51]
	v_max_f32_e32 v108, 0, v18
	v_max_f32_e32 v109, 0, v19
	v_pk_fma_f32 v[50:51], v[200:201], v[108:109], v[50:51]
	v_max_f32_e32 v210, 0, v20
	v_max_f32_e32 v211, 0, v21
	v_pk_fma_f32 v[50:51], v[202:203], v[210:211], v[50:51]
	v_add_f32_e32 v50, v50, v51
	v_ashrrev_i32_e32 v51, 31, v50
	v_or_b32_e32 v51, 0x80000000, v51
	v_xor_b32_e32 v50, v51, v50
	v_cndmask_b32_e32 v50, v123, v50, vcc
	global_store_dword v243, v50, s[8:9] offset:2048
	s_add_u32 s8, s8, 0x1000
	s_addc_u32 s9, s9, 0
	v_mfma_f32_32x32x16_bf16 v[6:21], v[86:89], v[38:41], 0
	v_mfma_f32_32x32x16_bf16 v[6:21], v[90:93], v[42:45], v[6:21]
	v_mfma_f32_32x32x16_bf16 v[6:21], v[94:97], v[46:49], v[6:21]
	v_mfma_f32_32x32x16_bf16 v[6:21], v[98:101], v[196:199], v[6:21]
	s_cmpk_gt_i32 s11, 464
	s_cselect_b64 vcc, -1, 0
	v_max_f32_e32 v108, 0, v212
	v_max_f32_e32 v109, 0, v213
	v_pk_mul_f32 v[0:1], v[22:23], v[108:109]
	v_max_f32_e32 v210, 0, v214
	v_max_f32_e32 v211, 0, v215
	v_pk_fma_f32 v[0:1], v[24:25], v[210:211], v[0:1]
	v_max_f32_e32 v108, 0, v216
	v_max_f32_e32 v109, 0, v217
	v_pk_fma_f32 v[0:1], v[26:27], v[108:109], v[0:1]
	v_max_f32_e32 v210, 0, v218
	v_max_f32_e32 v211, 0, v219
	v_pk_fma_f32 v[0:1], v[28:29], v[210:211], v[0:1]
	v_max_f32_e32 v108, 0, v220
	v_max_f32_e32 v109, 0, v221
	v_pk_fma_f32 v[0:1], v[30:31], v[108:109], v[0:1]
	v_max_f32_e32 v210, 0, v222
	v_max_f32_e32 v211, 0, v223
	v_pk_fma_f32 v[0:1], v[32:33], v[210:211], v[0:1]
	v_max_f32_e32 v108, 0, v224
	v_max_f32_e32 v109, 0, v225
	v_pk_fma_f32 v[0:1], v[34:35], v[108:109], v[0:1]
	v_max_f32_e32 v210, 0, v226
	v_max_f32_e32 v211, 0, v227
	v_pk_fma_f32 v[0:1], v[36:37], v[210:211], v[0:1]
	v_add_f32_e32 v0, v0, v1
	v_ashrrev_i32_e32 v1, 31, v0
	v_or_b32_e32 v1, 0x80000000, v1
	v_xor_b32_e32 v0, v1, v0
	v_cndmask_b32_e32 v192, v123, v0, vcc
	s_add_i32 m0, s10, 65536
	s_nop 0
	global_load_lds_dwordx4 v102, s[6:7]
	s_add_i32 m0, s10, 66560
	s_nop 0
	global_load_lds_dwordx4 v110, s[6:7]
	s_add_i32 m0, s10, 67584
	s_nop 0
	global_load_lds_dwordx4 v112, s[6:7]
	s_add_i32 m0, s10, 68608
	s_nop 0
	global_load_lds_dwordx4 v193, s[6:7]
	s_add_u32 s6, s6, 0x8000
	s_addc_u32 s7, s7, 0
	s_waitcnt vmcnt(14)
	v_add_u32_e32 v228, 0x10000, v5
	ds_read_b128 v[38:41], v228 offset:43264
	v_add_u32_e32 v228, 0x10000, v52
	ds_read_b128 v[42:45], v228 offset:43264
	v_add_u32_e32 v228, 0x10000, v55
	ds_read_b128 v[46:49], v228 offset:43264
	v_add_u32_e32 v228, 0x10000, v56
	ds_read_b128 v[196:199], v228 offset:43264
	s_waitcnt lgkmcnt(3)
	v_mfma_f32_32x32x16_bf16 v[212:227], v[70:73], v[38:41], 0
	s_waitcnt lgkmcnt(2)
	v_mfma_f32_32x32x16_bf16 v[212:227], v[74:77], v[42:45], v[212:227]
	s_waitcnt lgkmcnt(1)
	v_mfma_f32_32x32x16_bf16 v[212:227], v[78:81], v[46:49], v[212:227]
	s_waitcnt lgkmcnt(0)
	v_mfma_f32_32x32x16_bf16 v[212:227], v[82:85], v[196:199], v[212:227]
	s_cmpk_gt_i32 s11, 464
	s_cselect_b64 vcc, -1, 0
	v_max_f32_e32 v108, 0, v6
	v_max_f32_e32 v109, 0, v7
	v_pk_mul_f32 v[50:51], v[244:245], v[108:109]
	v_max_f32_e32 v210, 0, v8
	v_max_f32_e32 v211, 0, v9
	v_pk_fma_f32 v[50:51], v[246:247], v[210:211], v[50:51]
	v_max_f32_e32 v108, 0, v10
	v_max_f32_e32 v109, 0, v11
	v_pk_fma_f32 v[50:51], v[248:249], v[108:109], v[50:51]
	v_max_f32_e32 v210, 0, v12
	v_max_f32_e32 v211, 0, v13
	v_pk_fma_f32 v[50:51], v[250:251], v[210:211], v[50:51]
	v_max_f32_e32 v108, 0, v14
	v_max_f32_e32 v109, 0, v15
	v_pk_fma_f32 v[50:51], v[252:253], v[108:109], v[50:51]
	v_max_f32_e32 v210, 0, v16
	v_max_f32_e32 v211, 0, v17
	v_pk_fma_f32 v[50:51], v[254:255], v[210:211], v[50:51]
	v_max_f32_e32 v108, 0, v18
	v_max_f32_e32 v109, 0, v19
	v_pk_fma_f32 v[50:51], v[200:201], v[108:109], v[50:51]
	v_max_f32_e32 v210, 0, v20
	v_max_f32_e32 v211, 0, v21
	v_pk_fma_f32 v[50:51], v[202:203], v[210:211], v[50:51]
	v_add_f32_e32 v50, v50, v51
	v_ashrrev_i32_e32 v51, 31, v50
	v_or_b32_e32 v51, 0x80000000, v51
	v_xor_b32_e32 v50, v51, v50
	v_cndmask_b32_e32 v50, v123, v50, vcc
	global_store_dword v243, v50, s[8:9]
	v_mfma_f32_32x32x16_bf16 v[6:21], v[86:89], v[38:41], 0
	v_mfma_f32_32x32x16_bf16 v[6:21], v[90:93], v[42:45], v[6:21]
	v_mfma_f32_32x32x16_bf16 v[6:21], v[94:97], v[46:49], v[6:21]
	v_mfma_f32_32x32x16_bf16 v[6:21], v[98:101], v[196:199], v[6:21]
	s_cmpk_gt_i32 s11, 472
	s_cselect_b64 vcc, -1, 0
	v_max_f32_e32 v108, 0, v212
	v_max_f32_e32 v109, 0, v213
	v_pk_mul_f32 v[0:1], v[22:23], v[108:109]
	v_max_f32_e32 v210, 0, v214
	v_max_f32_e32 v211, 0, v215
	v_pk_fma_f32 v[0:1], v[24:25], v[210:211], v[0:1]
	v_max_f32_e32 v108, 0, v216
	v_max_f32_e32 v109, 0, v217
	v_pk_fma_f32 v[0:1], v[26:27], v[108:109], v[0:1]
	v_max_f32_e32 v210, 0, v218
	v_max_f32_e32 v211, 0, v219
	v_pk_fma_f32 v[0:1], v[28:29], v[210:211], v[0:1]
	v_max_f32_e32 v108, 0, v220
	v_max_f32_e32 v109, 0, v221
	v_pk_fma_f32 v[0:1], v[30:31], v[108:109], v[0:1]
	v_max_f32_e32 v210, 0, v222
	v_max_f32_e32 v211, 0, v223
	v_pk_fma_f32 v[0:1], v[32:33], v[210:211], v[0:1]
	v_max_f32_e32 v108, 0, v224
	v_max_f32_e32 v109, 0, v225
	v_pk_fma_f32 v[0:1], v[34:35], v[108:109], v[0:1]
	v_max_f32_e32 v210, 0, v226
	v_max_f32_e32 v211, 0, v227
	v_pk_fma_f32 v[0:1], v[36:37], v[210:211], v[0:1]
	v_add_f32_e32 v0, v0, v1
	v_ashrrev_i32_e32 v1, 31, v0
	v_or_b32_e32 v1, 0x80000000, v1
	v_xor_b32_e32 v0, v1, v0
	v_cndmask_b32_e32 v191, v123, v0, vcc
	s_add_i32 m0, s10, 98304
	s_nop 0
	global_load_lds_dwordx4 v102, s[6:7]
	s_add_i32 m0, s10, 99328
	s_nop 0
	global_load_lds_dwordx4 v110, s[6:7]
	s_add_i32 m0, s10, 100352
	s_nop 0
	global_load_lds_dwordx4 v112, s[6:7]
	s_add_i32 m0, s10, 101376
	s_nop 0
	global_load_lds_dwordx4 v193, s[6:7]
	s_add_u32 s6, s6, 0x8000
	s_addc_u32 s7, s7, 0
	s_waitcnt vmcnt(15)
	ds_read_b128 v[38:41], v5 offset:10496
	ds_read_b128 v[42:45], v52 offset:10496
	ds_read_b128 v[46:49], v55 offset:10496
	ds_read_b128 v[196:199], v56 offset:10496
	s_waitcnt lgkmcnt(3)
	v_mfma_f32_32x32x16_bf16 v[212:227], v[70:73], v[38:41], 0
	s_waitcnt lgkmcnt(2)
	v_mfma_f32_32x32x16_bf16 v[212:227], v[74:77], v[42:45], v[212:227]
	s_waitcnt lgkmcnt(1)
	v_mfma_f32_32x32x16_bf16 v[212:227], v[78:81], v[46:49], v[212:227]
	s_waitcnt lgkmcnt(0)
	v_mfma_f32_32x32x16_bf16 v[212:227], v[82:85], v[196:199], v[212:227]
	s_cmpk_gt_i32 s11, 472
	s_cselect_b64 vcc, -1, 0
	v_max_f32_e32 v108, 0, v6
	v_max_f32_e32 v109, 0, v7
	v_pk_mul_f32 v[50:51], v[244:245], v[108:109]
	v_max_f32_e32 v210, 0, v8
	v_max_f32_e32 v211, 0, v9
	v_pk_fma_f32 v[50:51], v[246:247], v[210:211], v[50:51]
	v_max_f32_e32 v108, 0, v10
	v_max_f32_e32 v109, 0, v11
	v_pk_fma_f32 v[50:51], v[248:249], v[108:109], v[50:51]
	v_max_f32_e32 v210, 0, v12
	v_max_f32_e32 v211, 0, v13
	v_pk_fma_f32 v[50:51], v[250:251], v[210:211], v[50:51]
	v_max_f32_e32 v108, 0, v14
	v_max_f32_e32 v109, 0, v15
	v_pk_fma_f32 v[50:51], v[252:253], v[108:109], v[50:51]
	v_max_f32_e32 v210, 0, v16
	v_max_f32_e32 v211, 0, v17
	v_pk_fma_f32 v[50:51], v[254:255], v[210:211], v[50:51]
	v_max_f32_e32 v108, 0, v18
	v_max_f32_e32 v109, 0, v19
	v_pk_fma_f32 v[50:51], v[200:201], v[108:109], v[50:51]
	v_max_f32_e32 v210, 0, v20
	v_max_f32_e32 v211, 0, v21
	v_pk_fma_f32 v[50:51], v[202:203], v[210:211], v[50:51]
	v_add_f32_e32 v50, v50, v51
	v_ashrrev_i32_e32 v51, 31, v50
	v_or_b32_e32 v51, 0x80000000, v51
	v_xor_b32_e32 v50, v51, v50
	v_cndmask_b32_e32 v50, v123, v50, vcc
	global_store_dword v243, v50, s[8:9] offset:2048
	s_add_u32 s8, s8, 0x1000
	s_addc_u32 s9, s9, 0
	v_mfma_f32_32x32x16_bf16 v[6:21], v[86:89], v[38:41], 0
	v_mfma_f32_32x32x16_bf16 v[6:21], v[90:93], v[42:45], v[6:21]
	v_mfma_f32_32x32x16_bf16 v[6:21], v[94:97], v[46:49], v[6:21]
	v_mfma_f32_32x32x16_bf16 v[6:21], v[98:101], v[196:199], v[6:21]
	s_cmpk_gt_i32 s11, 480
	s_cselect_b64 vcc, -1, 0
	v_max_f32_e32 v108, 0, v212
	v_max_f32_e32 v109, 0, v213
	v_pk_mul_f32 v[0:1], v[22:23], v[108:109]
	v_max_f32_e32 v210, 0, v214
	v_max_f32_e32 v211, 0, v215
	v_pk_fma_f32 v[0:1], v[24:25], v[210:211], v[0:1]
	v_max_f32_e32 v108, 0, v216
	v_max_f32_e32 v109, 0, v217
	v_pk_fma_f32 v[0:1], v[26:27], v[108:109], v[0:1]
	v_max_f32_e32 v210, 0, v218
	v_max_f32_e32 v211, 0, v219
	v_pk_fma_f32 v[0:1], v[28:29], v[210:211], v[0:1]
	v_max_f32_e32 v108, 0, v220
	v_max_f32_e32 v109, 0, v221
	v_pk_fma_f32 v[0:1], v[30:31], v[108:109], v[0:1]
	v_max_f32_e32 v210, 0, v222
	v_max_f32_e32 v211, 0, v223
	v_pk_fma_f32 v[0:1], v[32:33], v[210:211], v[0:1]
	v_max_f32_e32 v108, 0, v224
	v_max_f32_e32 v109, 0, v225
	v_pk_fma_f32 v[0:1], v[34:35], v[108:109], v[0:1]
	v_max_f32_e32 v210, 0, v226
	v_max_f32_e32 v211, 0, v227
	v_pk_fma_f32 v[0:1], v[36:37], v[210:211], v[0:1]
	v_add_f32_e32 v0, v0, v1
	v_ashrrev_i32_e32 v1, 31, v0
	v_or_b32_e32 v1, 0x80000000, v1
	v_xor_b32_e32 v0, v1, v0
	v_cndmask_b32_e32 v3, v123, v0, vcc
	s_add_i32 m0, s10, 0
	s_nop 0
	global_load_lds_dwordx4 v102, s[6:7]
	s_add_i32 m0, s10, 1024
	s_nop 0
	global_load_lds_dwordx4 v110, s[6:7]
	s_add_i32 m0, s10, 2048
	s_nop 0
	global_load_lds_dwordx4 v112, s[6:7]
	s_add_i32 m0, s10, 3072
	s_nop 0
	global_load_lds_dwordx4 v193, s[6:7]
	s_add_u32 s6, s6, 0x8000
	s_addc_u32 s7, s7, 0
	s_waitcnt vmcnt(15)
	ds_read_b128 v[38:41], v5 offset:43264
	ds_read_b128 v[42:45], v52 offset:43264
	ds_read_b128 v[46:49], v55 offset:43264
	ds_read_b128 v[196:199], v56 offset:43264
	s_waitcnt lgkmcnt(3)
	v_mfma_f32_32x32x16_bf16 v[212:227], v[70:73], v[38:41], 0
	s_waitcnt lgkmcnt(2)
	v_mfma_f32_32x32x16_bf16 v[212:227], v[74:77], v[42:45], v[212:227]
	s_waitcnt lgkmcnt(1)
	v_mfma_f32_32x32x16_bf16 v[212:227], v[78:81], v[46:49], v[212:227]
	s_waitcnt lgkmcnt(0)
	v_mfma_f32_32x32x16_bf16 v[212:227], v[82:85], v[196:199], v[212:227]
	s_cmpk_gt_i32 s11, 480
	s_cselect_b64 vcc, -1, 0
	v_max_f32_e32 v108, 0, v6
	v_max_f32_e32 v109, 0, v7
	v_pk_mul_f32 v[50:51], v[244:245], v[108:109]
	v_max_f32_e32 v210, 0, v8
	v_max_f32_e32 v211, 0, v9
	v_pk_fma_f32 v[50:51], v[246:247], v[210:211], v[50:51]
	v_max_f32_e32 v108, 0, v10
	v_max_f32_e32 v109, 0, v11
	v_pk_fma_f32 v[50:51], v[248:249], v[108:109], v[50:51]
	v_max_f32_e32 v210, 0, v12
	v_max_f32_e32 v211, 0, v13
	v_pk_fma_f32 v[50:51], v[250:251], v[210:211], v[50:51]
	v_max_f32_e32 v108, 0, v14
	v_max_f32_e32 v109, 0, v15
	v_pk_fma_f32 v[50:51], v[252:253], v[108:109], v[50:51]
	v_max_f32_e32 v210, 0, v16
	v_max_f32_e32 v211, 0, v17
	v_pk_fma_f32 v[50:51], v[254:255], v[210:211], v[50:51]
	v_max_f32_e32 v108, 0, v18
	v_max_f32_e32 v109, 0, v19
	v_pk_fma_f32 v[50:51], v[200:201], v[108:109], v[50:51]
	v_max_f32_e32 v210, 0, v20
	v_max_f32_e32 v211, 0, v21
	v_pk_fma_f32 v[50:51], v[202:203], v[210:211], v[50:51]
	v_add_f32_e32 v50, v50, v51
	v_ashrrev_i32_e32 v51, 31, v50
	v_or_b32_e32 v51, 0x80000000, v51
	v_xor_b32_e32 v50, v51, v50
	v_cndmask_b32_e32 v50, v123, v50, vcc
	global_store_dword v243, v50, s[8:9]
	v_mfma_f32_32x32x16_bf16 v[6:21], v[86:89], v[38:41], 0
	v_mfma_f32_32x32x16_bf16 v[6:21], v[90:93], v[42:45], v[6:21]
	v_mfma_f32_32x32x16_bf16 v[6:21], v[94:97], v[46:49], v[6:21]
	v_mfma_f32_32x32x16_bf16 v[6:21], v[98:101], v[196:199], v[6:21]
	s_cmpk_gt_i32 s11, 488
	s_cselect_b64 vcc, -1, 0
	v_max_f32_e32 v108, 0, v212
	v_max_f32_e32 v109, 0, v213
	v_pk_mul_f32 v[0:1], v[22:23], v[108:109]
	v_max_f32_e32 v210, 0, v214
	v_max_f32_e32 v211, 0, v215
	v_pk_fma_f32 v[0:1], v[24:25], v[210:211], v[0:1]
	v_max_f32_e32 v108, 0, v216
	v_max_f32_e32 v109, 0, v217
	v_pk_fma_f32 v[0:1], v[26:27], v[108:109], v[0:1]
	v_max_f32_e32 v210, 0, v218
	v_max_f32_e32 v211, 0, v219
	v_pk_fma_f32 v[0:1], v[28:29], v[210:211], v[0:1]
	v_max_f32_e32 v108, 0, v220
	v_max_f32_e32 v109, 0, v221
	v_pk_fma_f32 v[0:1], v[30:31], v[108:109], v[0:1]
	v_max_f32_e32 v210, 0, v222
	v_max_f32_e32 v211, 0, v223
	v_pk_fma_f32 v[0:1], v[32:33], v[210:211], v[0:1]
	v_max_f32_e32 v108, 0, v224
	v_max_f32_e32 v109, 0, v225
	v_pk_fma_f32 v[0:1], v[34:35], v[108:109], v[0:1]
	v_max_f32_e32 v210, 0, v226
	v_max_f32_e32 v211, 0, v227
	v_pk_fma_f32 v[0:1], v[36:37], v[210:211], v[0:1]
	v_add_f32_e32 v0, v0, v1
	v_ashrrev_i32_e32 v1, 31, v0
	v_or_b32_e32 v1, 0x80000000, v1
	v_xor_b32_e32 v0, v1, v0
	v_cndmask_b32_e32 v2, v123, v0, vcc
	s_add_i32 m0, s10, 32768
	s_nop 0
	global_load_lds_dwordx4 v102, s[6:7]
	s_add_i32 m0, s10, 33792
	s_nop 0
	global_load_lds_dwordx4 v110, s[6:7]
	s_add_i32 m0, s10, 34816
	s_nop 0
	global_load_lds_dwordx4 v112, s[6:7]
	s_add_i32 m0, s10, 35840
	s_nop 0
	global_load_lds_dwordx4 v193, s[6:7]
	s_add_u32 s6, s6, 0x8000
	s_addc_u32 s7, s7, 0
	s_waitcnt vmcnt(15)
	v_add_u32_e32 v228, 0x10000, v5
	ds_read_b128 v[38:41], v228 offset:10496
	v_add_u32_e32 v228, 0x10000, v52
	ds_read_b128 v[42:45], v228 offset:10496
	v_add_u32_e32 v228, 0x10000, v55
	ds_read_b128 v[46:49], v228 offset:10496
	v_add_u32_e32 v228, 0x10000, v56
	ds_read_b128 v[196:199], v228 offset:10496
	s_waitcnt lgkmcnt(3)
	v_mfma_f32_32x32x16_bf16 v[212:227], v[70:73], v[38:41], 0
	s_waitcnt lgkmcnt(2)
	v_mfma_f32_32x32x16_bf16 v[212:227], v[74:77], v[42:45], v[212:227]
	s_waitcnt lgkmcnt(1)
	v_mfma_f32_32x32x16_bf16 v[212:227], v[78:81], v[46:49], v[212:227]
	s_waitcnt lgkmcnt(0)
	v_mfma_f32_32x32x16_bf16 v[212:227], v[82:85], v[196:199], v[212:227]
	s_cmpk_gt_i32 s11, 488
	s_cselect_b64 vcc, -1, 0
	v_max_f32_e32 v108, 0, v6
	v_max_f32_e32 v109, 0, v7
	v_pk_mul_f32 v[50:51], v[244:245], v[108:109]
	v_max_f32_e32 v210, 0, v8
	v_max_f32_e32 v211, 0, v9
	v_pk_fma_f32 v[50:51], v[246:247], v[210:211], v[50:51]
	v_max_f32_e32 v108, 0, v10
	v_max_f32_e32 v109, 0, v11
	v_pk_fma_f32 v[50:51], v[248:249], v[108:109], v[50:51]
	v_max_f32_e32 v210, 0, v12
	v_max_f32_e32 v211, 0, v13
	v_pk_fma_f32 v[50:51], v[250:251], v[210:211], v[50:51]
	v_max_f32_e32 v108, 0, v14
	v_max_f32_e32 v109, 0, v15
	v_pk_fma_f32 v[50:51], v[252:253], v[108:109], v[50:51]
	v_max_f32_e32 v210, 0, v16
	v_max_f32_e32 v211, 0, v17
	v_pk_fma_f32 v[50:51], v[254:255], v[210:211], v[50:51]
	v_max_f32_e32 v108, 0, v18
	v_max_f32_e32 v109, 0, v19
	v_pk_fma_f32 v[50:51], v[200:201], v[108:109], v[50:51]
	v_max_f32_e32 v210, 0, v20
	v_max_f32_e32 v211, 0, v21
	v_pk_fma_f32 v[50:51], v[202:203], v[210:211], v[50:51]
	v_add_f32_e32 v50, v50, v51
	v_ashrrev_i32_e32 v51, 31, v50
	v_or_b32_e32 v51, 0x80000000, v51
	v_xor_b32_e32 v50, v51, v50
	v_cndmask_b32_e32 v50, v123, v50, vcc
	global_store_dword v243, v50, s[8:9] offset:2048
	s_add_u32 s8, s8, 0x1000
	s_addc_u32 s9, s9, 0
	v_mfma_f32_32x32x16_bf16 v[6:21], v[86:89], v[38:41], 0
	v_mfma_f32_32x32x16_bf16 v[6:21], v[90:93], v[42:45], v[6:21]
	v_mfma_f32_32x32x16_bf16 v[6:21], v[94:97], v[46:49], v[6:21]
	v_mfma_f32_32x32x16_bf16 v[6:21], v[98:101], v[196:199], v[6:21]
	s_cmpk_gt_i32 s11, 496
	s_cselect_b64 vcc, -1, 0
	v_max_f32_e32 v108, 0, v212
	v_max_f32_e32 v109, 0, v213
	v_pk_mul_f32 v[0:1], v[22:23], v[108:109]
	v_max_f32_e32 v210, 0, v214
	v_max_f32_e32 v211, 0, v215
	v_pk_fma_f32 v[0:1], v[24:25], v[210:211], v[0:1]
	v_max_f32_e32 v108, 0, v216
	v_max_f32_e32 v109, 0, v217
	v_pk_fma_f32 v[0:1], v[26:27], v[108:109], v[0:1]
	v_max_f32_e32 v210, 0, v218
	v_max_f32_e32 v211, 0, v219
	v_pk_fma_f32 v[0:1], v[28:29], v[210:211], v[0:1]
	v_max_f32_e32 v108, 0, v220
	v_max_f32_e32 v109, 0, v221
	v_pk_fma_f32 v[0:1], v[30:31], v[108:109], v[0:1]
	v_max_f32_e32 v210, 0, v222
	v_max_f32_e32 v211, 0, v223
	v_pk_fma_f32 v[0:1], v[32:33], v[210:211], v[0:1]
	v_max_f32_e32 v108, 0, v224
	v_max_f32_e32 v109, 0, v225
	v_pk_fma_f32 v[0:1], v[34:35], v[108:109], v[0:1]
	v_max_f32_e32 v210, 0, v226
	v_max_f32_e32 v211, 0, v227
	v_pk_fma_f32 v[0:1], v[36:37], v[210:211], v[0:1]
	v_add_f32_e32 v0, v0, v1
	v_ashrrev_i32_e32 v1, 31, v0
	v_or_b32_e32 v1, 0x80000000, v1
	v_xor_b32_e32 v0, v1, v0
	v_cndmask_b32_e32 v4, v123, v0, vcc
	s_add_i32 m0, s10, 65536
	s_nop 0
	global_load_lds_dwordx4 v102, s[6:7]
	s_add_i32 m0, s10, 66560
	s_nop 0
	global_load_lds_dwordx4 v110, s[6:7]
	s_add_i32 m0, s10, 67584
	s_nop 0
	global_load_lds_dwordx4 v112, s[6:7]
	s_add_i32 m0, s10, 68608
	s_nop 0
	global_load_lds_dwordx4 v193, s[6:7]
	s_add_u32 s6, s6, 0x8000
	s_addc_u32 s7, s7, 0
	s_waitcnt vmcnt(15)
	v_add_u32_e32 v228, 0x10000, v5
	ds_read_b128 v[38:41], v228 offset:43264
	v_add_u32_e32 v228, 0x10000, v52
	ds_read_b128 v[42:45], v228 offset:43264
	v_add_u32_e32 v228, 0x10000, v55
	ds_read_b128 v[46:49], v228 offset:43264
	v_add_u32_e32 v228, 0x10000, v56
	ds_read_b128 v[196:199], v228 offset:43264
	s_waitcnt lgkmcnt(3)
	v_mfma_f32_32x32x16_bf16 v[212:227], v[70:73], v[38:41], 0
	s_waitcnt lgkmcnt(2)
	v_mfma_f32_32x32x16_bf16 v[212:227], v[74:77], v[42:45], v[212:227]
	s_waitcnt lgkmcnt(1)
	v_mfma_f32_32x32x16_bf16 v[212:227], v[78:81], v[46:49], v[212:227]
	s_waitcnt lgkmcnt(0)
	v_mfma_f32_32x32x16_bf16 v[212:227], v[82:85], v[196:199], v[212:227]
	s_cmpk_gt_i32 s11, 496
	s_cselect_b64 vcc, -1, 0
	v_max_f32_e32 v108, 0, v6
	v_max_f32_e32 v109, 0, v7
	v_pk_mul_f32 v[50:51], v[244:245], v[108:109]
	v_max_f32_e32 v210, 0, v8
	v_max_f32_e32 v211, 0, v9
	v_pk_fma_f32 v[50:51], v[246:247], v[210:211], v[50:51]
	v_max_f32_e32 v108, 0, v10
	v_max_f32_e32 v109, 0, v11
	v_pk_fma_f32 v[50:51], v[248:249], v[108:109], v[50:51]
	v_max_f32_e32 v210, 0, v12
	v_max_f32_e32 v211, 0, v13
	v_pk_fma_f32 v[50:51], v[250:251], v[210:211], v[50:51]
	v_max_f32_e32 v108, 0, v14
	v_max_f32_e32 v109, 0, v15
	v_pk_fma_f32 v[50:51], v[252:253], v[108:109], v[50:51]
	v_max_f32_e32 v210, 0, v16
	v_max_f32_e32 v211, 0, v17
	v_pk_fma_f32 v[50:51], v[254:255], v[210:211], v[50:51]
	v_max_f32_e32 v108, 0, v18
	v_max_f32_e32 v109, 0, v19
	v_pk_fma_f32 v[50:51], v[200:201], v[108:109], v[50:51]
	v_max_f32_e32 v210, 0, v20
	v_max_f32_e32 v211, 0, v21
	v_pk_fma_f32 v[50:51], v[202:203], v[210:211], v[50:51]
	v_add_f32_e32 v50, v50, v51
	v_ashrrev_i32_e32 v51, 31, v50
	v_or_b32_e32 v51, 0x80000000, v51
	v_xor_b32_e32 v50, v51, v50
	v_cndmask_b32_e32 v50, v123, v50, vcc
	global_store_dword v243, v50, s[8:9]
	v_mfma_f32_32x32x16_bf16 v[6:21], v[86:89], v[38:41], 0
	v_mfma_f32_32x32x16_bf16 v[6:21], v[90:93], v[42:45], v[6:21]
	v_mfma_f32_32x32x16_bf16 v[6:21], v[94:97], v[46:49], v[6:21]
	v_mfma_f32_32x32x16_bf16 v[6:21], v[98:101], v[196:199], v[6:21]
	s_cmpk_gt_i32 s11, 504
	s_cselect_b64 vcc, -1, 0
	v_max_f32_e32 v108, 0, v212
	v_max_f32_e32 v109, 0, v213
	v_pk_mul_f32 v[0:1], v[22:23], v[108:109]
	v_max_f32_e32 v210, 0, v214
	v_max_f32_e32 v211, 0, v215
	v_pk_fma_f32 v[0:1], v[24:25], v[210:211], v[0:1]
	v_max_f32_e32 v108, 0, v216
	v_max_f32_e32 v109, 0, v217
	v_pk_fma_f32 v[0:1], v[26:27], v[108:109], v[0:1]
	v_max_f32_e32 v210, 0, v218
	v_max_f32_e32 v211, 0, v219
	v_pk_fma_f32 v[0:1], v[28:29], v[210:211], v[0:1]
	v_max_f32_e32 v108, 0, v220
	v_max_f32_e32 v109, 0, v221
	v_pk_fma_f32 v[0:1], v[30:31], v[108:109], v[0:1]
	v_max_f32_e32 v210, 0, v222
	v_max_f32_e32 v211, 0, v223
	v_pk_fma_f32 v[0:1], v[32:33], v[210:211], v[0:1]
	v_max_f32_e32 v108, 0, v224
	v_max_f32_e32 v109, 0, v225
	v_pk_fma_f32 v[0:1], v[34:35], v[108:109], v[0:1]
	v_max_f32_e32 v210, 0, v226
	v_max_f32_e32 v211, 0, v227
	v_pk_fma_f32 v[0:1], v[36:37], v[210:211], v[0:1]
	v_add_f32_e32 v0, v0, v1
	v_ashrrev_i32_e32 v1, 31, v0
	v_or_b32_e32 v1, 0x80000000, v1
	v_xor_b32_e32 v0, v1, v0
	v_cndmask_b32_e32 v185, v123, v0, vcc
	v_max_f32_e32 v108, 0, v6
	v_max_f32_e32 v109, 0, v7
	v_pk_mul_f32 v[50:51], v[244:245], v[108:109]
	v_max_f32_e32 v210, 0, v8
	v_max_f32_e32 v211, 0, v9
	v_pk_fma_f32 v[50:51], v[246:247], v[210:211], v[50:51]
	v_max_f32_e32 v108, 0, v10
	v_max_f32_e32 v109, 0, v11
	v_pk_fma_f32 v[50:51], v[248:249], v[108:109], v[50:51]
	v_max_f32_e32 v210, 0, v12
	v_max_f32_e32 v211, 0, v13
	v_pk_fma_f32 v[50:51], v[250:251], v[210:211], v[50:51]
	v_max_f32_e32 v108, 0, v14
	v_max_f32_e32 v109, 0, v15
	v_pk_fma_f32 v[50:51], v[252:253], v[108:109], v[50:51]
	v_max_f32_e32 v210, 0, v16
	v_max_f32_e32 v211, 0, v17
	v_pk_fma_f32 v[50:51], v[254:255], v[210:211], v[50:51]
	v_max_f32_e32 v108, 0, v18
	v_max_f32_e32 v109, 0, v19
	v_pk_fma_f32 v[50:51], v[200:201], v[108:109], v[50:51]
	v_max_f32_e32 v210, 0, v20
	v_max_f32_e32 v211, 0, v21
	v_pk_fma_f32 v[50:51], v[202:203], v[210:211], v[50:51]
	v_add_f32_e32 v50, v50, v51
	v_ashrrev_i32_e32 v51, 31, v50
	v_or_b32_e32 v51, 0x80000000, v51
	v_xor_b32_e32 v50, v51, v50
	v_cndmask_b32_e32 v50, v123, v50, vcc
	global_store_dword v243, v50, s[8:9] offset:2048
	s_add_u32 s8, s8, 0x1000
	s_addc_u32 s9, s9, 0
	s_branch .Lix_done

.Lix_rdone:
.Lix_done:
	s_waitcnt vmcnt(0)
